# on top of v27: in every GEMM load interval the two LDS-DMA loads are issued before the ds_reads
# baseline (speedup 1.0000x reference)
; #define PG8_STAGE(bufoff, gbase) do { _Pragma("unroll") for (int _i = 0; _i < 2; ++_i) \
;         __builtin_amdgcn_global_load_lds((const unsigned*)((const char*)(gbase) + voff[_i]), (LAS unsigned*)(lds + (bufoff) + ldsw + _i * 8192), 16, 0, 0); } while (0)
; #define PG8_LDA(dst, b, h) do { _Pragma("unroll") for (int m = 0; m < 4; ++m) _Pragma("unroll") for (int k = 0; k < 2; ++k) dst[m][k] = *(const LAS bf16x8*)(lds + PG8_SA(b, h) + aoff + m * 2048 + k * 1024); } while (0)
; #define PG8_LDB(dst, b, h) do { _Pragma("unroll") for (int n = 0; n < 2; ++n) _Pragma("unroll") for (int k = 0; k < 2; ++k) dst[n][k] = *(const LAS bf16x8*)(lds + PG8_SB(b, h) + boff + n * 2048 + k * 1024); } while (0)
; #define PG8_MMA(ai, bj, At, Bt) do { __builtin_amdgcn_s_setprio(1); _Pragma("unroll") for (int m = 0; m < 4; ++m) _Pragma("unroll") for (int n = 0; n < 2; ++n) _Pragma("unroll") for (int k = 0; k < 2; ++k) \
;         acc[ai][bj][m][n] = __builtin_amdgcn_mfma_f32_16x16x32_bf16(Bt[n][k], At[m][k], acc[ai][bj][m][n], 0, 0, 0); __builtin_amdgcn_s_setprio(0); } while (0)
; #define PG8_WAIT_V(n) asm volatile("s_waitcnt vmcnt(" #n ")" ::: "memory")
; #define PG8_WAIT_L(n) asm volatile("s_waitcnt lgkmcnt(" #n ")" ::: "memory")
; #define PG8_BAR __builtin_amdgcn_s_barrier()
; #define PG8_SCHED __builtin_amdgcn_sched_barrier(0)
; template <class Epi>
; DI void gemm_phase(LAS unsigned char* lds, const Gemm g, const StaticOrder& S, const Epi& E) {
;     ...
;         for (int t = 0; t < nt; t += 2) {
;             const bool last = (t == nt - 2);
;             const char* a1 = cA + (size_t)(t + 1) * kstep;
;             const char* a2 = last ? nA : cA + (size_t)(t + 2) * kstep; const char* b2 = last ? nB : cB + (size_t)(t + 2) * kstep;
;             const char* a3 = a2 + kstep; const char* b3 = b2 + kstep;
;             PG8_LDB(B0, 0, 0); PG8_SCHED; PG8_LDA(At, 0, 0); PG8_STAGE(PG8_SA(1, 1), a1 + hstep);
;             PG8_WAIT_L(8); PG8_BAR; PG8_WAIT_L(0); PG8_MMA(0, 0, At, B0); PG8_BAR; PG8_SCHED;
;             PG8_LDB(B1, 0, 1); PG8_STAGE(PG8_SB(0, 0), b2);
;             PG8_BAR; PG8_WAIT_L(0); PG8_MMA(0, 1, At, B1); PG8_BAR;
;             PG8_LDA(At, 0, 1); PG8_STAGE(PG8_SA(0, 0), a2);
;             PG8_BAR; PG8_WAIT_L(0); PG8_MMA(1, 0, At, B0); PG8_BAR; PG8_SCHED;
;             PG8_STAGE(PG8_SB(0, 1), b2 + hstep);
;             PG8_WAIT_V(6); PG8_BAR; PG8_MMA(1, 1, At, B1); PG8_BAR;
.LBB0_37:
	s_add_u32 s20, s18, 0xfff80080
	s_addc_u32 s21, s19, -1
	s_add_i32 s39, 0, 0x10000
	s_cmp_eq_u32 s38, 28
	s_cselect_b32 s23, s4, s21
	s_cselect_b32 s22, s5, s20
	s_cselect_b32 s21, s9, s37
	s_cselect_b32 s20, s11, s33
	s_add_i32 m0, s28, 0xc000
	s_nop 0
	global_load_lds_dwordx4 v130, s[18:19]
	s_add_i32 m0, s28, 0xe000
	s_nop 0
	global_load_lds_dwordx4 v132, s[18:19]
	ds_read_b128 v[138:141], v135
	ds_read_b128 v[142:145], v135 offset:1024
	ds_read_b128 v[146:149], v135 offset:2048
	ds_read_b128 v[150:153], v135 offset:3072
	ds_read_b128 v[186:189], v137
	ds_read_b128 v[190:193], v137 offset:1024
	ds_read_b128 v[194:197], v137 offset:2048
	ds_read_b128 v[198:201], v137 offset:3072
	ds_read_b128 v[202:205], v137 offset:4096
	ds_read_b128 v[206:209], v137 offset:5120
	ds_read_b128 v[210:213], v137 offset:6144
	ds_read_b128 v[214:217], v137 offset:7168
	s_waitcnt lgkmcnt(8)
	s_setprio 1
	s_barrier
	s_waitcnt lgkmcnt(0)
	v_mfma_f32_16x16x32_bf16 v[124:127], v[138:141], v[186:189], v[124:127]
	v_mfma_f32_16x16x32_bf16 v[120:123], v[146:149], v[186:189], v[120:123]
	v_mfma_f32_16x16x32_bf16 v[108:111], v[138:141], v[194:197], v[108:111]
	v_mfma_f32_16x16x32_bf16 v[104:107], v[146:149], v[194:197], v[104:107]
	v_mfma_f32_16x16x32_bf16 v[92:95], v[138:141], v[202:205], v[92:95]
	v_mfma_f32_16x16x32_bf16 v[88:91], v[146:149], v[202:205], v[88:91]
	v_mfma_f32_16x16x32_bf16 v[76:79], v[138:141], v[210:213], v[76:79]
	v_mfma_f32_16x16x32_bf16 v[72:75], v[146:149], v[210:213], v[72:75]
	v_mfma_f32_16x16x32_bf16 v[124:127], v[142:145], v[190:193], v[124:127]
	v_mfma_f32_16x16x32_bf16 v[120:123], v[150:153], v[190:193], v[120:123]
	v_mfma_f32_16x16x32_bf16 v[108:111], v[142:145], v[198:201], v[108:111]
	v_mfma_f32_16x16x32_bf16 v[104:107], v[150:153], v[198:201], v[104:107]
	v_mfma_f32_16x16x32_bf16 v[92:95], v[142:145], v[206:209], v[92:95]
	v_mfma_f32_16x16x32_bf16 v[88:91], v[150:153], v[206:209], v[88:91]
	v_mfma_f32_16x16x32_bf16 v[76:79], v[142:145], v[214:217], v[76:79]
	s_setprio 0
	v_mfma_f32_16x16x32_bf16 v[72:75], v[150:153], v[214:217], v[72:75]
	s_barrier
	s_add_i32 s42, 0, 0x14000
	s_add_i32 s39, s39, s27
	s_mov_b32 m0, s39
	s_nop 0
	global_load_lds_dwordx4 v158, s[20:21]
	s_add_i32 m0, s39, 0x2000
	s_nop 0
	global_load_lds_dwordx4 v128, s[20:21]
	ds_read_b128 v[226:229], v135 offset:16384
	ds_read_b128 v[230:233], v135 offset:17408
	ds_read_b128 v[234:237], v135 offset:18432
	ds_read_b128 v[238:241], v135 offset:19456
	s_waitcnt lgkmcnt(0)
	s_setprio 1
	s_barrier
	v_mfma_f32_16x16x32_bf16 v[116:119], v[226:229], v[186:189], v[116:119]
	v_mfma_f32_16x16x32_bf16 v[112:115], v[234:237], v[186:189], v[112:115]
	v_mfma_f32_16x16x32_bf16 v[100:103], v[226:229], v[194:197], v[100:103]
	v_mfma_f32_16x16x32_bf16 v[96:99], v[234:237], v[194:197], v[96:99]
	v_mfma_f32_16x16x32_bf16 v[84:87], v[226:229], v[202:205], v[84:87]
	v_mfma_f32_16x16x32_bf16 v[80:83], v[234:237], v[202:205], v[80:83]
	v_mfma_f32_16x16x32_bf16 v[68:71], v[226:229], v[210:213], v[68:71]
	v_mfma_f32_16x16x32_bf16 v[64:67], v[234:237], v[210:213], v[64:67]
	v_mfma_f32_16x16x32_bf16 v[116:119], v[230:233], v[190:193], v[116:119]
	s_mov_b32 m0, s28
	v_mfma_f32_16x16x32_bf16 v[112:115], v[238:241], v[190:193], v[112:115]
	s_mov_b64 s[100:101], s[22:23]
	v_mfma_f32_16x16x32_bf16 v[100:103], v[230:233], v[198:201], v[100:103]
	v_mfma_f32_16x16x32_bf16 v[96:99], v[238:241], v[198:201], v[96:99]
	v_mfma_f32_16x16x32_bf16 v[84:87], v[230:233], v[206:209], v[84:87]
	v_mfma_f32_16x16x32_bf16 v[80:83], v[238:241], v[206:209], v[80:83]
	v_mfma_f32_16x16x32_bf16 v[68:71], v[230:233], v[214:217], v[68:71]
	s_setprio 0
	v_mfma_f32_16x16x32_bf16 v[64:67], v[238:241], v[214:217], v[64:67]
	s_barrier
	global_load_lds_dwordx4 v158, s[22:23]
	s_mov_b64 s[100:101], s[22:23]
	s_mov_b32 m0, s29
	s_nop 0
	global_load_lds_dwordx4 v128, s[22:23]
	ds_read_b128 v[186:189], v137 offset:16384
	ds_read_b128 v[190:193], v137 offset:17408
	ds_read_b128 v[194:197], v137 offset:18432
	ds_read_b128 v[198:201], v137 offset:19456
	ds_read_b128 v[202:205], v137 offset:20480
	ds_read_b128 v[206:209], v137 offset:21504
	ds_read_b128 v[210:213], v137 offset:22528
	ds_read_b128 v[214:217], v137 offset:23552
	s_waitcnt lgkmcnt(0)
	s_setprio 1
	s_barrier
	v_mfma_f32_16x16x32_bf16 v[60:63], v[138:141], v[186:189], v[60:63]
	v_mfma_f32_16x16x32_bf16 v[56:59], v[146:149], v[186:189], v[56:59]
	v_mfma_f32_16x16x32_bf16 v[44:47], v[138:141], v[194:197], v[44:47]
	v_mfma_f32_16x16x32_bf16 v[40:43], v[146:149], v[194:197], v[40:43]
	v_mfma_f32_16x16x32_bf16 v[28:31], v[138:141], v[202:205], v[28:31]
	v_mfma_f32_16x16x32_bf16 v[24:27], v[146:149], v[202:205], v[24:27]
	v_mfma_f32_16x16x32_bf16 v[12:15], v[138:141], v[210:213], v[12:15]
	v_mfma_f32_16x16x32_bf16 v[8:11], v[146:149], v[210:213], v[8:11]
	v_mfma_f32_16x16x32_bf16 v[60:63], v[142:145], v[190:193], v[60:63]
	v_mfma_f32_16x16x32_bf16 v[56:59], v[150:153], v[190:193], v[56:59]
	v_mfma_f32_16x16x32_bf16 v[44:47], v[142:145], v[198:201], v[44:47]
	v_mfma_f32_16x16x32_bf16 v[40:43], v[150:153], v[198:201], v[40:43]
	v_mfma_f32_16x16x32_bf16 v[28:31], v[142:145], v[206:209], v[28:31]
	v_mfma_f32_16x16x32_bf16 v[24:27], v[150:153], v[206:209], v[24:27]
	v_mfma_f32_16x16x32_bf16 v[12:15], v[142:145], v[214:217], v[12:15]
	s_setprio 0
	v_mfma_f32_16x16x32_bf16 v[8:11], v[150:153], v[214:217], v[8:11]
	s_barrier
	s_add_u32 s40, s20, 0x80000
	s_addc_u32 s41, s21, 0
	s_add_i32 s39, s42, s27
	s_mov_b32 m0, s39
	s_nop 0
	global_load_lds_dwordx4 v158, s[40:41]
	s_add_i32 m0, s39, 0x2000
	s_nop 0
	global_load_lds_dwordx4 v128, s[40:41]
	s_waitcnt vmcnt(6)
	s_setprio 1
	s_barrier
; #define PG8_STAGE(bufoff, gbase) do { _Pragma("unroll") for (int _i = 0; _i < 2; ++_i) \
;         __builtin_amdgcn_global_load_lds((const unsigned*)((const char*)(gbase) + voff[_i]), (LAS unsigned*)(lds + (bufoff) + ldsw + _i * 8192), 16, 0, 0); } while (0)
; #define PG8_LDA(dst, b, h) do { _Pragma("unroll") for (int m = 0; m < 4; ++m) _Pragma("unroll") for (int k = 0; k < 2; ++k) dst[m][k] = *(const LAS bf16x8*)(lds + PG8_SA(b, h) + aoff + m * 2048 + k * 1024); } while (0)
; #define PG8_LDB(dst, b, h) do { _Pragma("unroll") for (int n = 0; n < 2; ++n) _Pragma("unroll") for (int k = 0; k < 2; ++k) dst[n][k] = *(const LAS bf16x8*)(lds + PG8_SB(b, h) + boff + n * 2048 + k * 1024); } while (0)
; #define PG8_MMA(ai, bj, At, Bt) do { __builtin_amdgcn_s_setprio(1); _Pragma("unroll") for (int m = 0; m < 4; ++m) _Pragma("unroll") for (int n = 0; n < 2; ++n) _Pragma("unroll") for (int k = 0; k < 2; ++k) \
;         acc[ai][bj][m][n] = __builtin_amdgcn_mfma_f32_16x16x32_bf16(Bt[n][k], At[m][k], acc[ai][bj][m][n], 0, 0, 0); __builtin_amdgcn_s_setprio(0); } while (0)
; #define PG8_WAIT_V(n) asm volatile("s_waitcnt vmcnt(" #n ")" ::: "memory")
; #define PG8_WAIT_L(n) asm volatile("s_waitcnt lgkmcnt(" #n ")" ::: "memory")
; #define PG8_BAR __builtin_amdgcn_s_barrier()
; #define PG8_SCHED __builtin_amdgcn_sched_barrier(0)
; template <class Epi>
; DI void gemm_phase(LAS unsigned char* lds, const Gemm g, const StaticOrder& S, const Epi& E) {
;     ...
;             PG8_WAIT_V(6); PG8_BAR; PG8_MMA(1, 1, At, B1); PG8_BAR;
;             PG8_LDB(B0, 1, 0); PG8_SCHED; PG8_LDA(At, 1, 0); PG8_STAGE(PG8_SA(0, 1), a2 + hstep);
;             PG8_WAIT_L(8); PG8_BAR; PG8_WAIT_L(0); PG8_MMA(0, 0, At, B0); PG8_BAR; PG8_SCHED;
;             PG8_LDB(B1, 1, 1); PG8_STAGE(PG8_SB(1, 0), b3);
;             PG8_BAR; PG8_WAIT_L(0); PG8_MMA(0, 1, At, B1); PG8_BAR;
;             PG8_LDA(At, 1, 1); PG8_STAGE(PG8_SA(1, 0), a3);
;             PG8_BAR; PG8_WAIT_L(0); PG8_MMA(1, 0, At, B0); PG8_BAR; PG8_SCHED;
;             PG8_STAGE(PG8_SB(1, 1), b3 + hstep);
	v_mfma_f32_16x16x32_bf16 v[52:55], v[226:229], v[186:189], v[52:55]
	v_mfma_f32_16x16x32_bf16 v[48:51], v[234:237], v[186:189], v[48:51]
	v_mfma_f32_16x16x32_bf16 v[36:39], v[226:229], v[194:197], v[36:39]
	v_mfma_f32_16x16x32_bf16 v[32:35], v[234:237], v[194:197], v[32:35]
	v_mfma_f32_16x16x32_bf16 v[20:23], v[226:229], v[202:205], v[20:23]
	v_mfma_f32_16x16x32_bf16 v[16:19], v[234:237], v[202:205], v[16:19]
	v_mfma_f32_16x16x32_bf16 v[4:7], v[226:229], v[210:213], v[4:7]
	v_mfma_f32_16x16x32_bf16 v[0:3], v[234:237], v[210:213], v[0:3]
	v_mfma_f32_16x16x32_bf16 v[52:55], v[230:233], v[190:193], v[52:55]
	s_add_i32 s39, 0, 0x18000
	v_mfma_f32_16x16x32_bf16 v[48:51], v[238:241], v[190:193], v[48:51]
	v_mfma_f32_16x16x32_bf16 v[36:39], v[230:233], v[198:201], v[36:39]
	v_mfma_f32_16x16x32_bf16 v[32:35], v[238:241], v[198:201], v[32:35]
	v_mfma_f32_16x16x32_bf16 v[20:23], v[230:233], v[206:209], v[20:23]
	v_mfma_f32_16x16x32_bf16 v[16:19], v[238:241], v[206:209], v[16:19]
	v_mfma_f32_16x16x32_bf16 v[4:7], v[230:233], v[214:217], v[4:7]
	s_setprio 0
	v_mfma_f32_16x16x32_bf16 v[0:3], v[238:241], v[214:217], v[0:3]
	s_barrier
	s_add_u32 s22, s22, 0x80000
	s_addc_u32 s23, s23, 0
	s_mov_b32 m0, s30
	s_nop 0
	global_load_lds_dwordx4 v158, s[22:23]
	s_mov_b32 m0, s31
	s_nop 0
	global_load_lds_dwordx4 v128, s[22:23]
	ds_read_b128 v[138:141], v135 offset:32768
	ds_read_b128 v[142:145], v135 offset:33792
	ds_read_b128 v[146:149], v135 offset:34816
	ds_read_b128 v[150:153], v135 offset:35840
	ds_read_b128 v[186:189], v137 offset:32768
	ds_read_b128 v[190:193], v137 offset:33792
	ds_read_b128 v[194:197], v137 offset:34816
	ds_read_b128 v[198:201], v137 offset:35840
	ds_read_b128 v[202:205], v137 offset:36864
	ds_read_b128 v[206:209], v137 offset:37888
	ds_read_b128 v[210:213], v137 offset:38912
	ds_read_b128 v[214:217], v137 offset:39936
	s_waitcnt lgkmcnt(8)
	s_setprio 1
	s_barrier
	s_waitcnt lgkmcnt(0)
	v_mfma_f32_16x16x32_bf16 v[124:127], v[138:141], v[186:189], v[124:127]
	v_mfma_f32_16x16x32_bf16 v[120:123], v[146:149], v[186:189], v[120:123]
	v_mfma_f32_16x16x32_bf16 v[108:111], v[138:141], v[194:197], v[108:111]
	v_mfma_f32_16x16x32_bf16 v[104:107], v[146:149], v[194:197], v[104:107]
	v_mfma_f32_16x16x32_bf16 v[92:95], v[138:141], v[202:205], v[92:95]
	v_mfma_f32_16x16x32_bf16 v[88:91], v[146:149], v[202:205], v[88:91]
	v_mfma_f32_16x16x32_bf16 v[76:79], v[138:141], v[210:213], v[76:79]
	v_mfma_f32_16x16x32_bf16 v[72:75], v[146:149], v[210:213], v[72:75]
	v_mfma_f32_16x16x32_bf16 v[124:127], v[142:145], v[190:193], v[124:127]
	v_mfma_f32_16x16x32_bf16 v[120:123], v[150:153], v[190:193], v[120:123]
	v_mfma_f32_16x16x32_bf16 v[108:111], v[142:145], v[198:201], v[108:111]
	v_mfma_f32_16x16x32_bf16 v[104:107], v[150:153], v[198:201], v[104:107]
	v_mfma_f32_16x16x32_bf16 v[92:95], v[142:145], v[206:209], v[92:95]
	v_mfma_f32_16x16x32_bf16 v[88:91], v[150:153], v[206:209], v[88:91]
	v_mfma_f32_16x16x32_bf16 v[76:79], v[142:145], v[214:217], v[76:79]
	s_setprio 0
	v_mfma_f32_16x16x32_bf16 v[72:75], v[150:153], v[214:217], v[72:75]
	s_barrier
	s_add_i32 s22, 0, 0x1c000
	s_add_i32 s23, s39, s27
	s_add_i32 m0, s23, 0xffffff80
	s_nop 0
	global_load_lds_dwordx4 v158, s[20:21] offset:128
	s_add_i32 m0, s23, 0x1f80
	s_nop 0
	global_load_lds_dwordx4 v128, s[20:21] offset:128
	ds_read_b128 v[226:229], v135 offset:49152
	ds_read_b128 v[230:233], v135 offset:50176
	ds_read_b128 v[234:237], v135 offset:51200
	ds_read_b128 v[238:241], v135 offset:52224
	s_waitcnt lgkmcnt(0)
	s_setprio 1
	s_barrier
	v_mfma_f32_16x16x32_bf16 v[116:119], v[226:229], v[186:189], v[116:119]
	v_mfma_f32_16x16x32_bf16 v[112:115], v[234:237], v[186:189], v[112:115]
	v_mfma_f32_16x16x32_bf16 v[100:103], v[226:229], v[194:197], v[100:103]
	v_mfma_f32_16x16x32_bf16 v[96:99], v[234:237], v[194:197], v[96:99]
	v_mfma_f32_16x16x32_bf16 v[84:87], v[226:229], v[202:205], v[84:87]
	v_mfma_f32_16x16x32_bf16 v[80:83], v[234:237], v[202:205], v[80:83]
	v_mfma_f32_16x16x32_bf16 v[68:71], v[226:229], v[210:213], v[68:71]
	v_mfma_f32_16x16x32_bf16 v[64:67], v[234:237], v[210:213], v[64:67]
	v_mfma_f32_16x16x32_bf16 v[116:119], v[230:233], v[190:193], v[116:119]
	s_add_i32 m0, s34, 0xffffff80
	v_mfma_f32_16x16x32_bf16 v[112:115], v[238:241], v[190:193], v[112:115]
	v_mfma_f32_16x16x32_bf16 v[100:103], v[230:233], v[198:201], v[100:103]
	v_mfma_f32_16x16x32_bf16 v[96:99], v[238:241], v[198:201], v[96:99]
	v_mfma_f32_16x16x32_bf16 v[84:87], v[230:233], v[206:209], v[84:87]
	v_mfma_f32_16x16x32_bf16 v[80:83], v[238:241], v[206:209], v[80:83]
	v_mfma_f32_16x16x32_bf16 v[68:71], v[230:233], v[214:217], v[68:71]
	s_setprio 0
	v_mfma_f32_16x16x32_bf16 v[64:67], v[238:241], v[214:217], v[64:67]
	s_barrier
	global_load_lds_dwordx4 v158, s[100:101] offset:128
	s_add_i32 m0, s35, 0xffffff80
	s_nop 0
	global_load_lds_dwordx4 v128, s[100:101] offset:128
	ds_read_b128 v[186:189], v137 offset:49152
	ds_read_b128 v[190:193], v137 offset:50176
	ds_read_b128 v[194:197], v137 offset:51200
	ds_read_b128 v[198:201], v137 offset:52224
	ds_read_b128 v[202:205], v137 offset:53248
	ds_read_b128 v[206:209], v137 offset:54272
	ds_read_b128 v[210:213], v137 offset:55296
	ds_read_b128 v[214:217], v137 offset:56320
	s_waitcnt lgkmcnt(0)
	s_setprio 1
	s_barrier
; #define PG8_STAGE(bufoff, gbase) do { _Pragma("unroll") for (int _i = 0; _i < 2; ++_i) \
;         __builtin_amdgcn_global_load_lds((const unsigned*)((const char*)(gbase) + voff[_i]), (LAS unsigned*)(lds + (bufoff) + ldsw + _i * 8192), 16, 0, 0); } while (0)
; #define PG8_MMA(ai, bj, At, Bt) do { __builtin_amdgcn_s_setprio(1); _Pragma("unroll") for (int m = 0; m < 4; ++m) _Pragma("unroll") for (int n = 0; n < 2; ++n) _Pragma("unroll") for (int k = 0; k < 2; ++k) \
;         acc[ai][bj][m][n] = __builtin_amdgcn_mfma_f32_16x16x32_bf16(Bt[n][k], At[m][k], acc[ai][bj][m][n], 0, 0, 0); __builtin_amdgcn_s_setprio(0); } while (0)
; #define PG8_WAIT_V(n) asm volatile("s_waitcnt vmcnt(" #n ")" ::: "memory")
; #define PG8_BAR __builtin_amdgcn_s_barrier()
; template <class Epi>
; DI void gemm_phase(LAS unsigned char* lds, const Gemm g, const StaticOrder& S, const Epi& E) {
;     ...
;             PG8_STAGE(PG8_SB(1, 1), b3 + hstep);
;             PG8_WAIT_V(6); PG8_BAR; PG8_MMA(1, 1, At, B1); PG8_BAR;
;         }
;     DI void operator()(const f32x4 (&acc)[2][2][4][2], const Unit& u, int wr, int wc, int fr, int fq) const {
;         const int row0 = u.pm * BM + wr * 64 + fr, col0 = u.pn * HALF + wc * 32 + 8 * fq;
; #pragma unroll
;         for (int ai = 0; ai < 2; ++ai)
; #pragma unroll
;             for (int m = 0; m < 4; ++m) { float hv[8];
; #pragma unroll
;                 for (int n = 0; n < 2; ++n)
; #pragma unroll
;                     for (int e = 0; e < 4; ++e) { const float gt = acc[ai][0][m][n][e], up = acc[ai][1][m][n][e];
;                         hv[n * 4 + e] = gt * __builtin_amdgcn_rcpf(1.f + __builtin_amdgcn_exp2f(-1.4426950408889634f * gt)) * up; }
;                 *(u32x4*)(H + (size_t)(row0 + ai * HALF + m * 16) * DFF + col0) = (u32x4){pk(hv[0], hv[1]), pk(hv[2], hv[3]), pk(hv[4], hv[5]), pk(hv[6], hv[7])}; }
	v_mfma_f32_16x16x32_bf16 v[60:63], v[138:141], v[186:189], v[60:63]
	v_mfma_f32_16x16x32_bf16 v[56:59], v[146:149], v[186:189], v[56:59]
	v_mfma_f32_16x16x32_bf16 v[44:47], v[138:141], v[194:197], v[44:47]
	v_mfma_f32_16x16x32_bf16 v[40:43], v[146:149], v[194:197], v[40:43]
	v_mfma_f32_16x16x32_bf16 v[28:31], v[138:141], v[202:205], v[28:31]
	v_mfma_f32_16x16x32_bf16 v[24:27], v[146:149], v[202:205], v[24:27]
	v_mfma_f32_16x16x32_bf16 v[12:15], v[138:141], v[210:213], v[12:15]
	v_mfma_f32_16x16x32_bf16 v[8:11], v[146:149], v[210:213], v[8:11]
	v_mfma_f32_16x16x32_bf16 v[60:63], v[142:145], v[190:193], v[60:63]
	v_mfma_f32_16x16x32_bf16 v[56:59], v[150:153], v[190:193], v[56:59]
	v_mfma_f32_16x16x32_bf16 v[44:47], v[142:145], v[198:201], v[44:47]
	v_mfma_f32_16x16x32_bf16 v[40:43], v[150:153], v[198:201], v[40:43]
	v_mfma_f32_16x16x32_bf16 v[28:31], v[142:145], v[206:209], v[28:31]
	v_mfma_f32_16x16x32_bf16 v[24:27], v[150:153], v[206:209], v[24:27]
	v_mfma_f32_16x16x32_bf16 v[12:15], v[142:145], v[214:217], v[12:15]
	s_setprio 0
	v_mfma_f32_16x16x32_bf16 v[8:11], v[150:153], v[214:217], v[8:11]
	s_barrier
	s_add_u32 s20, s20, 0x80080
	s_addc_u32 s21, s21, 0
	s_add_i32 s22, s22, s27
	s_mov_b32 m0, s22
	s_nop 0
	global_load_lds_dwordx4 v158, s[20:21]
	s_add_i32 m0, s22, 0x2000
	s_nop 0
	global_load_lds_dwordx4 v128, s[20:21]
	s_waitcnt vmcnt(6)
	s_setprio 1
	s_barrier
	v_mfma_f32_16x16x32_bf16 v[52:55], v[226:229], v[186:189], v[52:55]
	v_mfma_f32_16x16x32_bf16 v[48:51], v[234:237], v[186:189], v[48:51]
	v_mfma_f32_16x16x32_bf16 v[36:39], v[226:229], v[194:197], v[36:39]
	v_mfma_f32_16x16x32_bf16 v[32:35], v[234:237], v[194:197], v[32:35]
	v_mfma_f32_16x16x32_bf16 v[20:23], v[226:229], v[202:205], v[20:23]
	v_mfma_f32_16x16x32_bf16 v[16:19], v[234:237], v[202:205], v[16:19]
	v_mfma_f32_16x16x32_bf16 v[4:7], v[226:229], v[210:213], v[4:7]
	v_mfma_f32_16x16x32_bf16 v[0:3], v[234:237], v[210:213], v[0:3]
	v_mfma_f32_16x16x32_bf16 v[52:55], v[230:233], v[190:193], v[52:55]
	s_add_i32 s38, s38, 2
	v_mfma_f32_16x16x32_bf16 v[48:51], v[238:241], v[190:193], v[48:51]
	s_add_u32 s18, s18, 0x100
	v_mfma_f32_16x16x32_bf16 v[36:39], v[230:233], v[198:201], v[36:39]
	s_addc_u32 s19, s19, 0
	v_mfma_f32_16x16x32_bf16 v[32:35], v[238:241], v[198:201], v[32:35]
	s_add_u32 s33, s33, 0x100
	v_mfma_f32_16x16x32_bf16 v[20:23], v[230:233], v[206:209], v[20:23]
	s_addc_u32 s37, s37, 0
	v_mfma_f32_16x16x32_bf16 v[16:19], v[238:241], v[206:209], v[16:19]
	s_cmp_gt_u32 s38, 29
	v_mfma_f32_16x16x32_bf16 v[4:7], v[230:233], v[214:217], v[4:7]
	s_setprio 0
	v_mfma_f32_16x16x32_bf16 v[0:3], v[238:241], v[214:217], v[0:3]
	s_barrier
	s_cbranch_scc0 .LBB0_37
	v_mul_f32_e32 v139, 0xbfb8aa3b, v124
	v_exp_f32_e32 v139, v139
	v_lshl_or_b32 v140, s2, 7, v136
	v_lshl_add_u32 v138, s3, 8, v134
	v_ashrrev_i32_e32 v141, 31, v140
	v_add_f32_e32 v139, 1.0, v139
	v_rcp_f32_e32 v142, v139
	v_mul_f32_e32 v139, 0xbfb8aa3b, v125
	v_exp_f32_e32 v139, v139
	s_movk_i32 s4, 0x2c00
	s_and_b64 vcc, exec, s[6:7]
	s_mov_b64 s[20:21], s[16:17]
	v_add_f32_e32 v139, 1.0, v139
	v_rcp_f32_e32 v143, v139
	v_mul_f32_e32 v139, 0xbfb8aa3b, v126
	v_exp_f32_e32 v139, v139
	s_mov_b64 s[18:19], s[14:15]
	v_pk_mul_f32 v[124:125], v[124:125], v[142:143]
	v_add_f32_e32 v139, 1.0, v139
	v_rcp_f32_e32 v144, v139
	v_mul_f32_e32 v139, 0xbfb8aa3b, v127
	v_exp_f32_e32 v139, v139
	v_pk_mul_f32 v[116:117], v[124:125], v[116:117]
	v_add_f32_e32 v139, 1.0, v139
	v_rcp_f32_e32 v145, v139
	v_mul_f32_e32 v139, 0xbfb8aa3b, v120
	v_exp_f32_e32 v139, v139
	v_cvt_pk_bf16_f32 v116, v116, v117
	v_pk_mul_f32 v[124:125], v[126:127], v[144:145]
	v_add_f32_e32 v139, 1.0, v139
	v_rcp_f32_e32 v146, v139
	v_mul_f32_e32 v139, 0xbfb8aa3b, v121
	v_exp_f32_e32 v139, v139
	v_pk_mul_f32 v[118:119], v[124:125], v[118:119]
	v_add_f32_e32 v139, 1.0, v139
	v_rcp_f32_e32 v147, v139
	v_mul_f32_e32 v139, 0xbfb8aa3b, v122
	v_exp_f32_e32 v139, v139
	v_cvt_pk_bf16_f32 v117, v118, v119
	v_pk_mul_f32 v[118:119], v[120:121], v[146:147]
	v_add_f32_e32 v139, 1.0, v139
	v_rcp_f32_e32 v148, v139
	v_mul_f32_e32 v139, 0xbfb8aa3b, v123
	v_exp_f32_e32 v139, v139
	v_pk_mul_f32 v[112:113], v[118:119], v[112:113]
	v_add_f32_e32 v139, 1.0, v139
	v_rcp_f32_e32 v149, v139
	v_cvt_pk_bf16_f32 v118, v112, v113
	v_pk_mul_f32 v[112:113], v[122:123], v[148:149]
	s_nop 0
	v_pk_mul_f32 v[112:113], v[112:113], v[114:115]
	v_lshlrev_b64 v[114:115], 1, v[140:141]
	v_cvt_pk_bf16_f32 v119, v112, v113
	v_mov_b64_e32 v[112:113], s[54:55]
	v_mad_i64_i32 v[120:121], s[2:3], v138, s4, v[112:113]
	v_lshl_add_u64 v[120:121], v[120:121], 0, v[114:115]
	global_store_dwordx4 v[120:121], v[116:119], off
	v_mul_f32_e32 v120, 0xbfb8aa3b, v104
	v_mul_f32_e32 v121, 0xbfb8aa3b, v105
	v_mul_f32_e32 v116, 0xbfb8aa3b, v108
	v_mul_f32_e32 v117, 0xbfb8aa3b, v109
	v_exp_f32_e32 v116, v116
	v_exp_f32_e32 v117, v117
	v_mul_f32_e32 v118, 0xbfb8aa3b, v110
	v_mul_f32_e32 v119, 0xbfb8aa3b, v111
	v_exp_f32_e32 v118, v118
	v_exp_f32_e32 v119, v119
	v_exp_f32_e32 v120, v120
	v_exp_f32_e32 v121, v121
	v_add_f32_e32 v116, 1.0, v116
	v_add_f32_e32 v117, 1.0, v117
	v_mul_f32_e32 v122, 0xbfb8aa3b, v106
	v_mul_f32_e32 v123, 0xbfb8aa3b, v107
	v_rcp_f32_e32 v116, v116
	v_rcp_f32_e32 v117, v117
	v_add_f32_e32 v118, 1.0, v118
	v_add_f32_e32 v119, 1.0, v119
	v_exp_f32_e32 v122, v122
	v_exp_f32_e32 v123, v123
	v_rcp_f32_e32 v118, v118
	v_rcp_f32_e32 v119, v119
	v_add_f32_e32 v120, 1.0, v120
	v_add_f32_e32 v121, 1.0, v121
	v_rcp_f32_e32 v120, v120
	v_rcp_f32_e32 v121, v121
	v_add_f32_e32 v122, 1.0, v122
	v_add_f32_e32 v123, 1.0, v123
	v_pk_mul_f32 v[108:109], v[108:109], v[116:117]
	v_rcp_f32_e32 v122, v122
;     DI void operator()(const f32x4 (&acc)[2][2][4][2], const Unit& u, int wr, int wc, int fr, int fq) const {
;         const int row0 = u.pm * BM + wr * 64 + fr, col0 = u.pn * HALF + wc * 32 + 8 * fq;
; #pragma unroll
;         for (int ai = 0; ai < 2; ++ai)
; #pragma unroll
;             for (int m = 0; m < 4; ++m) { float hv[8];
; #pragma unroll
;                 for (int n = 0; n < 2; ++n)
; #pragma unroll
;                     for (int e = 0; e < 4; ++e) { const float gt = acc[ai][0][m][n][e], up = acc[ai][1][m][n][e];
;                         hv[n * 4 + e] = gt * __builtin_amdgcn_rcpf(1.f + __builtin_amdgcn_exp2f(-1.4426950408889634f * gt)) * up; }
;                 *(u32x4*)(H + (size_t)(row0 + ai * HALF + m * 16) * DFF + col0) = (u32x4){pk(hv[0], hv[1]), pk(hv[2], hv[3]), pk(hv[4], hv[5]), pk(hv[6], hv[7])}; }
	v_rcp_f32_e32 v123, v123
	v_pk_mul_f32 v[100:101], v[108:109], v[100:101]
	v_pk_mul_f32 v[108:109], v[110:111], v[118:119]
	v_cvt_pk_bf16_f32 v100, v100, v101
	v_pk_mul_f32 v[102:103], v[108:109], v[102:103]
	s_nop 0
	v_cvt_pk_bf16_f32 v101, v102, v103
	v_pk_mul_f32 v[102:103], v[104:105], v[120:121]
	s_nop 0
	v_pk_mul_f32 v[96:97], v[102:103], v[96:97]
	s_nop 0
	v_cvt_pk_bf16_f32 v102, v96, v97
	v_pk_mul_f32 v[96:97], v[106:107], v[122:123]
	s_nop 0
	v_pk_mul_f32 v[96:97], v[96:97], v[98:99]
	v_mul_f32_e32 v98, 0xbfb8aa3b, v94
	v_cvt_pk_bf16_f32 v103, v96, v97
	v_or_b32_e32 v96, 16, v138
	v_mad_i64_i32 v[96:97], s[2:3], v96, s4, v[112:113]
	v_lshl_add_u64 v[96:97], v[96:97], 0, v[114:115]
	global_store_dwordx4 v[96:97], v[100:103], off
	v_mul_f32_e32 v96, 0xbfb8aa3b, v92
	v_mul_f32_e32 v97, 0xbfb8aa3b, v93
	v_exp_f32_e32 v96, v96
	v_exp_f32_e32 v97, v97
	v_mul_f32_e32 v99, 0xbfb8aa3b, v95
	v_exp_f32_e32 v98, v98
	v_exp_f32_e32 v99, v99
	v_mul_f32_e32 v100, 0xbfb8aa3b, v88
	v_mul_f32_e32 v101, 0xbfb8aa3b, v89
	v_exp_f32_e32 v100, v100
	v_exp_f32_e32 v101, v101
	v_add_f32_e32 v96, 1.0, v96
	v_add_f32_e32 v97, 1.0, v97
	v_mul_f32_e32 v102, 0xbfb8aa3b, v90
	v_mul_f32_e32 v103, 0xbfb8aa3b, v91
	v_rcp_f32_e32 v96, v96
	v_rcp_f32_e32 v97, v97
	v_add_f32_e32 v98, 1.0, v98
	v_add_f32_e32 v99, 1.0, v99
	v_exp_f32_e32 v102, v102
	v_exp_f32_e32 v103, v103
	v_rcp_f32_e32 v98, v98
	v_rcp_f32_e32 v99, v99
	v_add_f32_e32 v100, 1.0, v100
	v_add_f32_e32 v101, 1.0, v101
	v_rcp_f32_e32 v100, v100
	v_rcp_f32_e32 v101, v101
	v_add_f32_e32 v102, 1.0, v102
	v_add_f32_e32 v103, 1.0, v103
	v_pk_mul_f32 v[92:93], v[92:93], v[96:97]
	v_rcp_f32_e32 v102, v102
	v_rcp_f32_e32 v103, v103
	v_pk_mul_f32 v[84:85], v[92:93], v[84:85]
	v_pk_mul_f32 v[92:93], v[94:95], v[98:99]
	v_cvt_pk_bf16_f32 v84, v84, v85
	v_pk_mul_f32 v[86:87], v[92:93], v[86:87]
	s_nop 0
	v_cvt_pk_bf16_f32 v85, v86, v87
	v_pk_mul_f32 v[86:87], v[88:89], v[100:101]
	s_nop 0
	v_pk_mul_f32 v[80:81], v[86:87], v[80:81]
	s_nop 0
	v_cvt_pk_bf16_f32 v86, v80, v81
	v_pk_mul_f32 v[80:81], v[90:91], v[102:103]
	s_nop 0
	v_pk_mul_f32 v[80:81], v[80:81], v[82:83]
	v_mul_f32_e32 v82, 0xbfb8aa3b, v78
	v_cvt_pk_bf16_f32 v87, v80, v81
	v_or_b32_e32 v80, 32, v138
	v_mad_i64_i32 v[80:81], s[2:3], v80, s4, v[112:113]
	v_lshl_add_u64 v[80:81], v[80:81], 0, v[114:115]
	global_store_dwordx4 v[80:81], v[84:87], off
	v_mul_f32_e32 v80, 0xbfb8aa3b, v76
	v_mul_f32_e32 v81, 0xbfb8aa3b, v77
	v_exp_f32_e32 v80, v80
	v_exp_f32_e32 v81, v81
	v_mul_f32_e32 v83, 0xbfb8aa3b, v79
	v_exp_f32_e32 v82, v82
	v_exp_f32_e32 v83, v83
	v_mul_f32_e32 v84, 0xbfb8aa3b, v72
	v_mul_f32_e32 v85, 0xbfb8aa3b, v73
	v_exp_f32_e32 v84, v84
	v_exp_f32_e32 v85, v85
	v_add_f32_e32 v80, 1.0, v80
	v_add_f32_e32 v81, 1.0, v81
	v_mul_f32_e32 v86, 0xbfb8aa3b, v74
	v_mul_f32_e32 v87, 0xbfb8aa3b, v75
	v_rcp_f32_e32 v80, v80
	v_rcp_f32_e32 v81, v81
	v_add_f32_e32 v82, 1.0, v82
	v_add_f32_e32 v83, 1.0, v83
	v_exp_f32_e32 v86, v86
	v_exp_f32_e32 v87, v87
	v_rcp_f32_e32 v82, v82
	v_rcp_f32_e32 v83, v83
	v_add_f32_e32 v84, 1.0, v84
	v_add_f32_e32 v85, 1.0, v85
	v_rcp_f32_e32 v84, v84
	v_rcp_f32_e32 v85, v85
	v_add_f32_e32 v86, 1.0, v86
	v_add_f32_e32 v87, 1.0, v87
	v_pk_mul_f32 v[76:77], v[76:77], v[80:81]
	v_rcp_f32_e32 v86, v86
	v_rcp_f32_e32 v87, v87
	v_pk_mul_f32 v[68:69], v[76:77], v[68:69]
	v_pk_mul_f32 v[76:77], v[78:79], v[82:83]
	v_cvt_pk_bf16_f32 v68, v68, v69
	v_pk_mul_f32 v[70:71], v[76:77], v[70:71]
	s_nop 0
	v_cvt_pk_bf16_f32 v69, v70, v71
	v_pk_mul_f32 v[70:71], v[72:73], v[84:85]
	v_add_u32_e32 v72, 0x80, v138
	v_pk_mul_f32 v[64:65], v[70:71], v[64:65]
	s_nop 0
	v_cvt_pk_bf16_f32 v70, v64, v65
	v_pk_mul_f32 v[64:65], v[74:75], v[86:87]
	s_nop 0
	v_pk_mul_f32 v[64:65], v[64:65], v[66:67]
	v_mul_f32_e32 v66, 0xbfb8aa3b, v62
	v_cvt_pk_bf16_f32 v71, v64, v65
	v_or_b32_e32 v64, 48, v138
	v_mad_i64_i32 v[64:65], s[2:3], v64, s4, v[112:113]
	v_lshl_add_u64 v[64:65], v[64:65], 0, v[114:115]
	global_store_dwordx4 v[64:65], v[68:71], off
	v_mul_f32_e32 v64, 0xbfb8aa3b, v60
	v_mul_f32_e32 v65, 0xbfb8aa3b, v61
	v_exp_f32_e32 v64, v64
	v_exp_f32_e32 v65, v65
	v_mul_f32_e32 v67, 0xbfb8aa3b, v63
	v_exp_f32_e32 v66, v66
	v_exp_f32_e32 v67, v67
	v_mul_f32_e32 v68, 0xbfb8aa3b, v56
	v_mul_f32_e32 v69, 0xbfb8aa3b, v57
	v_exp_f32_e32 v68, v68
	v_exp_f32_e32 v69, v69
	v_add_f32_e32 v64, 1.0, v64
	v_add_f32_e32 v65, 1.0, v65
	v_mul_f32_e32 v70, 0xbfb8aa3b, v58
	v_mul_f32_e32 v71, 0xbfb8aa3b, v59
	v_rcp_f32_e32 v64, v64
	v_rcp_f32_e32 v65, v65
	v_add_f32_e32 v66, 1.0, v66
	v_add_f32_e32 v67, 1.0, v67
	v_exp_f32_e32 v70, v70
	v_exp_f32_e32 v71, v71
	v_rcp_f32_e32 v66, v66
	v_rcp_f32_e32 v67, v67
	v_add_f32_e32 v68, 1.0, v68
	v_add_f32_e32 v69, 1.0, v69
	v_rcp_f32_e32 v68, v68
	v_rcp_f32_e32 v69, v69
	v_add_f32_e32 v70, 1.0, v70
	v_add_f32_e32 v71, 1.0, v71
	v_pk_mul_f32 v[60:61], v[60:61], v[64:65]
	v_rcp_f32_e32 v70, v70
	v_rcp_f32_e32 v71, v71
	v_pk_mul_f32 v[52:53], v[60:61], v[52:53]
	v_pk_mul_f32 v[60:61], v[62:63], v[66:67]
	v_cvt_pk_bf16_f32 v52, v52, v53
	v_pk_mul_f32 v[54:55], v[60:61], v[54:55]
	s_nop 0
	v_cvt_pk_bf16_f32 v53, v54, v55
	v_pk_mul_f32 v[54:55], v[56:57], v[68:69]
	s_nop 0
	v_pk_mul_f32 v[48:49], v[54:55], v[48:49]
; #define PG8_WAIT_V(n) asm volatile("s_waitcnt vmcnt(" #n ")" ::: "memory")
; #define PG8_BAR __builtin_amdgcn_s_barrier()
; template <class Epi>
; DI void gemm_phase(LAS unsigned char* lds, const Gemm g, const StaticOrder& S, const Epi& E) {
;     ...
;     PG8_WAIT_V(0);
;     if (wr == 0) PG8_BAR;
;     PG8_BAR;
;     DI void operator()(const f32x4 (&acc)[2][2][4][2], const Unit& u, int wr, int wc, int fr, int fq) const {
;         const int row0 = u.pm * BM + wr * 64 + fr, col0 = u.pn * HALF + wc * 32 + 8 * fq;
; #pragma unroll
;         for (int ai = 0; ai < 2; ++ai)
; #pragma unroll
;             for (int m = 0; m < 4; ++m) { float hv[8];
; #pragma unroll
;                 for (int n = 0; n < 2; ++n)
; #pragma unroll
;                     for (int e = 0; e < 4; ++e) { const float gt = acc[ai][0][m][n][e], up = acc[ai][1][m][n][e];
;                         hv[n * 4 + e] = gt * __builtin_amdgcn_rcpf(1.f + __builtin_amdgcn_exp2f(-1.4426950408889634f * gt)) * up; }
;                 *(u32x4*)(H + (size_t)(row0 + ai * HALF + m * 16) * DFF + col0) = (u32x4){pk(hv[0], hv[1]), pk(hv[2], hv[3]), pk(hv[4], hv[5]), pk(hv[6], hv[7])}; }
	s_nop 0
	v_cvt_pk_bf16_f32 v54, v48, v49
	v_pk_mul_f32 v[48:49], v[58:59], v[70:71]
	s_nop 0
	v_pk_mul_f32 v[48:49], v[48:49], v[50:51]
	v_mul_f32_e32 v50, 0xbfb8aa3b, v46
	v_cvt_pk_bf16_f32 v55, v48, v49
	v_mad_i64_i32 v[48:49], s[2:3], v72, s4, v[112:113]
	v_lshl_add_u64 v[48:49], v[48:49], 0, v[114:115]
	global_store_dwordx4 v[48:49], v[52:55], off
	v_mul_f32_e32 v48, 0xbfb8aa3b, v44
	v_mul_f32_e32 v49, 0xbfb8aa3b, v45
	v_exp_f32_e32 v48, v48
	v_exp_f32_e32 v49, v49
	v_mul_f32_e32 v51, 0xbfb8aa3b, v47
	v_exp_f32_e32 v50, v50
	v_exp_f32_e32 v51, v51
	v_mul_f32_e32 v52, 0xbfb8aa3b, v40
	v_mul_f32_e32 v53, 0xbfb8aa3b, v41
	v_exp_f32_e32 v52, v52
	v_exp_f32_e32 v53, v53
	v_add_f32_e32 v48, 1.0, v48
	v_add_f32_e32 v49, 1.0, v49
	v_mul_f32_e32 v54, 0xbfb8aa3b, v42
	v_mul_f32_e32 v55, 0xbfb8aa3b, v43
	v_rcp_f32_e32 v48, v48
	v_rcp_f32_e32 v49, v49
	v_add_f32_e32 v50, 1.0, v50
	v_add_f32_e32 v51, 1.0, v51
	v_exp_f32_e32 v54, v54
	v_exp_f32_e32 v55, v55
	v_rcp_f32_e32 v50, v50
	v_rcp_f32_e32 v51, v51
	v_add_f32_e32 v52, 1.0, v52
	v_add_f32_e32 v53, 1.0, v53
	v_rcp_f32_e32 v52, v52
	v_rcp_f32_e32 v53, v53
	v_add_f32_e32 v54, 1.0, v54
	v_add_f32_e32 v55, 1.0, v55
	v_pk_mul_f32 v[44:45], v[44:45], v[48:49]
	v_rcp_f32_e32 v54, v54
	v_rcp_f32_e32 v55, v55
	v_pk_mul_f32 v[36:37], v[44:45], v[36:37]
	v_pk_mul_f32 v[44:45], v[46:47], v[50:51]
	v_cvt_pk_bf16_f32 v36, v36, v37
	v_pk_mul_f32 v[38:39], v[44:45], v[38:39]
	s_nop 0
	v_cvt_pk_bf16_f32 v37, v38, v39
	v_pk_mul_f32 v[38:39], v[40:41], v[52:53]
	s_nop 0
	v_pk_mul_f32 v[32:33], v[38:39], v[32:33]
	s_nop 0
	v_cvt_pk_bf16_f32 v38, v32, v33
	v_pk_mul_f32 v[32:33], v[42:43], v[54:55]
	s_nop 0
	v_pk_mul_f32 v[32:33], v[32:33], v[34:35]
	v_mul_f32_e32 v34, 0xbfb8aa3b, v30
	v_cvt_pk_bf16_f32 v39, v32, v33
	v_add_u32_e32 v32, 0x90, v138
	v_mad_i64_i32 v[32:33], s[2:3], v32, s4, v[112:113]
	v_lshl_add_u64 v[32:33], v[32:33], 0, v[114:115]
	global_store_dwordx4 v[32:33], v[36:39], off
	v_mul_f32_e32 v32, 0xbfb8aa3b, v28
	v_mul_f32_e32 v33, 0xbfb8aa3b, v29
	v_exp_f32_e32 v32, v32
	v_exp_f32_e32 v33, v33
	v_mul_f32_e32 v35, 0xbfb8aa3b, v31
	v_exp_f32_e32 v34, v34
	v_exp_f32_e32 v35, v35
	v_mul_f32_e32 v36, 0xbfb8aa3b, v24
	v_mul_f32_e32 v37, 0xbfb8aa3b, v25
	v_exp_f32_e32 v36, v36
	v_exp_f32_e32 v37, v37
	v_add_f32_e32 v32, 1.0, v32
	v_add_f32_e32 v33, 1.0, v33
	v_mul_f32_e32 v38, 0xbfb8aa3b, v26
	v_mul_f32_e32 v39, 0xbfb8aa3b, v27
	v_rcp_f32_e32 v32, v32
	v_rcp_f32_e32 v33, v33
	v_add_f32_e32 v34, 1.0, v34
	v_add_f32_e32 v35, 1.0, v35
	v_exp_f32_e32 v38, v38
	v_exp_f32_e32 v39, v39
	v_rcp_f32_e32 v34, v34
	v_rcp_f32_e32 v35, v35
	v_add_f32_e32 v36, 1.0, v36
	v_add_f32_e32 v37, 1.0, v37
	v_rcp_f32_e32 v36, v36
	v_rcp_f32_e32 v37, v37
	v_add_f32_e32 v38, 1.0, v38
	v_add_f32_e32 v39, 1.0, v39
	v_pk_mul_f32 v[28:29], v[28:29], v[32:33]
	v_rcp_f32_e32 v38, v38
	v_rcp_f32_e32 v39, v39
	v_pk_mul_f32 v[20:21], v[28:29], v[20:21]
	v_pk_mul_f32 v[28:29], v[30:31], v[34:35]
	v_cvt_pk_bf16_f32 v20, v20, v21
	v_pk_mul_f32 v[22:23], v[28:29], v[22:23]
	s_nop 0
	v_cvt_pk_bf16_f32 v21, v22, v23
	v_pk_mul_f32 v[22:23], v[24:25], v[36:37]
	s_nop 0
	v_pk_mul_f32 v[16:17], v[22:23], v[16:17]
	s_nop 0
	v_cvt_pk_bf16_f32 v22, v16, v17
	v_pk_mul_f32 v[16:17], v[26:27], v[38:39]
	s_nop 0
	v_pk_mul_f32 v[16:17], v[16:17], v[18:19]
	v_mul_f32_e32 v18, 0xbfb8aa3b, v14
	v_cvt_pk_bf16_f32 v23, v16, v17
	v_add_u32_e32 v16, 0xa0, v138
	v_mad_i64_i32 v[16:17], s[2:3], v16, s4, v[112:113]
	v_lshl_add_u64 v[16:17], v[16:17], 0, v[114:115]
	global_store_dwordx4 v[16:17], v[20:23], off
	v_mul_f32_e32 v16, 0xbfb8aa3b, v12
	v_mul_f32_e32 v17, 0xbfb8aa3b, v13
	v_exp_f32_e32 v16, v16
	v_exp_f32_e32 v17, v17
	v_mul_f32_e32 v19, 0xbfb8aa3b, v15
	v_exp_f32_e32 v18, v18
	v_exp_f32_e32 v19, v19
	v_mul_f32_e32 v20, 0xbfb8aa3b, v8
	v_mul_f32_e32 v21, 0xbfb8aa3b, v9
	v_exp_f32_e32 v20, v20
	v_exp_f32_e32 v21, v21
	v_add_f32_e32 v16, 1.0, v16
	v_add_f32_e32 v17, 1.0, v17
	v_mul_f32_e32 v22, 0xbfb8aa3b, v10
	v_mul_f32_e32 v23, 0xbfb8aa3b, v11
	v_rcp_f32_e32 v16, v16
	v_rcp_f32_e32 v17, v17
	v_add_f32_e32 v18, 1.0, v18
	v_add_f32_e32 v19, 1.0, v19
	v_exp_f32_e32 v22, v22
	v_exp_f32_e32 v23, v23
	v_rcp_f32_e32 v18, v18
	v_rcp_f32_e32 v19, v19
	v_add_f32_e32 v20, 1.0, v20
	v_add_f32_e32 v21, 1.0, v21
	v_rcp_f32_e32 v20, v20
	v_rcp_f32_e32 v21, v21
	v_add_f32_e32 v22, 1.0, v22
	v_add_f32_e32 v23, 1.0, v23
	v_pk_mul_f32 v[12:13], v[12:13], v[16:17]
	v_rcp_f32_e32 v22, v22
	v_rcp_f32_e32 v23, v23
	v_pk_mul_f32 v[4:5], v[12:13], v[4:5]
	v_pk_mul_f32 v[12:13], v[14:15], v[18:19]
	v_cvt_pk_bf16_f32 v4, v4, v5
	v_pk_mul_f32 v[6:7], v[12:13], v[6:7]
	s_nop 0
	v_cvt_pk_bf16_f32 v5, v6, v7
	v_pk_mul_f32 v[6:7], v[8:9], v[20:21]
	s_nop 0
	v_pk_mul_f32 v[0:1], v[6:7], v[0:1]
	s_nop 0
	v_cvt_pk_bf16_f32 v6, v0, v1
	v_pk_mul_f32 v[0:1], v[10:11], v[22:23]
	s_nop 0
	v_pk_mul_f32 v[0:1], v[0:1], v[2:3]
	s_nop 0
	v_cvt_pk_bf16_f32 v7, v0, v1
	v_add_u32_e32 v0, 0xb0, v138
	v_mad_i64_i32 v[0:1], s[2:3], v0, s4, v[112:113]
	v_lshl_add_u64 v[0:1], v[0:1], 0, v[114:115]
	s_mov_b32 s2, s8
	s_mov_b32 s3, s10
	global_store_dwordx4 v[0:1], v[4:7], off
	s_cbranch_vccz .LBB0_34
	s_waitcnt vmcnt(0)
	s_cmpk_gt_u32 s24, 0xff
	s_cbranch_scc1 .LBB0_41
	s_barrier

; #define PG8_STAGE(bufoff, gbase) do { _Pragma("unroll") for (int _i = 0; _i < 2; ++_i) \
;         __builtin_amdgcn_global_load_lds((const unsigned*)((const char*)(gbase) + voff[_i]), (LAS unsigned*)(lds + (bufoff) + ldsw + _i * 8192), 16, 0, 0); } while (0)
; #define PG8_LDA(dst, b, h) do { _Pragma("unroll") for (int m = 0; m < 4; ++m) _Pragma("unroll") for (int k = 0; k < 2; ++k) dst[m][k] = *(const LAS bf16x8*)(lds + PG8_SA(b, h) + aoff + m * 2048 + k * 1024); } while (0)
; #define PG8_LDB(dst, b, h) do { _Pragma("unroll") for (int n = 0; n < 2; ++n) _Pragma("unroll") for (int k = 0; k < 2; ++k) dst[n][k] = *(const LAS bf16x8*)(lds + PG8_SB(b, h) + boff + n * 2048 + k * 1024); } while (0)
; #define PG8_MMA(ai, bj, At, Bt) do { __builtin_amdgcn_s_setprio(1); _Pragma("unroll") for (int m = 0; m < 4; ++m) _Pragma("unroll") for (int n = 0; n < 2; ++n) _Pragma("unroll") for (int k = 0; k < 2; ++k) \
;         acc[ai][bj][m][n] = __builtin_amdgcn_mfma_f32_16x16x32_bf16(Bt[n][k], At[m][k], acc[ai][bj][m][n], 0, 0, 0); __builtin_amdgcn_s_setprio(0); } while (0)
; #define PG8_WAIT_V(n) asm volatile("s_waitcnt vmcnt(" #n ")" ::: "memory")
; #define PG8_WAIT_L(n) asm volatile("s_waitcnt lgkmcnt(" #n ")" ::: "memory")
; #define PG8_BAR __builtin_amdgcn_s_barrier()
; #define PG8_SCHED __builtin_amdgcn_sched_barrier(0)
; template <class Epi>
; DI void gemm_phase(LAS unsigned char* lds, const Gemm g, const StaticOrder& S, const Epi& E) {
;     ...
;         for (int t = 0; t < nt; t += 2) {
;             const bool last = (t == nt - 2);
;             const char* a1 = cA + (size_t)(t + 1) * kstep;
;             const char* a2 = last ? nA : cA + (size_t)(t + 2) * kstep; const char* b2 = last ? nB : cB + (size_t)(t + 2) * kstep;
;             const char* a3 = a2 + kstep; const char* b3 = b2 + kstep;
;             PG8_LDB(B0, 0, 0); PG8_SCHED; PG8_LDA(At, 0, 0); PG8_STAGE(PG8_SA(1, 1), a1 + hstep);
;             PG8_WAIT_L(8); PG8_BAR; PG8_WAIT_L(0); PG8_MMA(0, 0, At, B0); PG8_BAR; PG8_SCHED;
;             PG8_LDB(B1, 0, 1); PG8_STAGE(PG8_SB(0, 0), b2);
;             PG8_BAR; PG8_WAIT_L(0); PG8_MMA(0, 1, At, B1); PG8_BAR;
;             PG8_LDA(At, 0, 1); PG8_STAGE(PG8_SA(0, 0), a2);
;             PG8_BAR; PG8_WAIT_L(0); PG8_MMA(1, 0, At, B0); PG8_BAR; PG8_SCHED;
;             PG8_STAGE(PG8_SB(0, 1), b2 + hstep);
;             PG8_WAIT_V(6); PG8_BAR; PG8_MMA(1, 1, At, B1); PG8_BAR;
.LBB0_77:
	s_add_u32 s22, s20, 0x100
	s_addc_u32 s23, s21, 0
	s_add_i32 s43, 0, 0x10000
	s_cmp_eq_u32 s33, 32
	s_cselect_b32 s27, s9, s23
	s_cselect_b32 s26, s8, s22
	s_cselect_b32 s25, s11, s5
	s_cselect_b32 s24, s10, s4
	s_add_i32 m0, s34, 0xc000
	s_nop 0
	global_load_lds_dwordx4 v190, s[20:21]
	s_add_i32 m0, s34, 0xe000
	s_nop 0
	global_load_lds_dwordx4 v192, s[20:21]
	ds_read_b128 v[128:131], v226
	ds_read_b128 v[132:135], v226 offset:1024
	ds_read_b128 v[136:139], v226 offset:2048
	ds_read_b128 v[140:143], v226 offset:3072
	ds_read_b128 v[144:147], v228
	ds_read_b128 v[148:151], v228 offset:1024
	ds_read_b128 v[152:155], v228 offset:2048
	ds_read_b128 v[194:197], v228 offset:3072
	ds_read_b128 v[198:201], v228 offset:4096
	ds_read_b128 v[202:205], v228 offset:5120
	ds_read_b128 v[206:209], v228 offset:6144
	ds_read_b128 v[210:213], v228 offset:7168
	s_waitcnt lgkmcnt(8)
	s_setprio 1
	s_barrier
	s_waitcnt lgkmcnt(0)
	v_mfma_f32_16x16x32_bf16 v[124:127], v[128:131], v[144:147], v[124:127]
	v_mfma_f32_16x16x32_bf16 v[120:123], v[136:139], v[144:147], v[120:123]
	v_mfma_f32_16x16x32_bf16 v[116:119], v[128:131], v[152:155], v[116:119]
	v_mfma_f32_16x16x32_bf16 v[112:115], v[136:139], v[152:155], v[112:115]
	v_mfma_f32_16x16x32_bf16 v[108:111], v[128:131], v[198:201], v[108:111]
	v_mfma_f32_16x16x32_bf16 v[104:107], v[136:139], v[198:201], v[104:107]
	v_mfma_f32_16x16x32_bf16 v[100:103], v[128:131], v[206:209], v[100:103]
	v_mfma_f32_16x16x32_bf16 v[96:99], v[136:139], v[206:209], v[96:99]
	v_mfma_f32_16x16x32_bf16 v[124:127], v[132:135], v[148:151], v[124:127]
	v_mfma_f32_16x16x32_bf16 v[120:123], v[140:143], v[148:151], v[120:123]
	v_mfma_f32_16x16x32_bf16 v[116:119], v[132:135], v[194:197], v[116:119]
	v_mfma_f32_16x16x32_bf16 v[112:115], v[140:143], v[194:197], v[112:115]
	v_mfma_f32_16x16x32_bf16 v[108:111], v[132:135], v[202:205], v[108:111]
	v_mfma_f32_16x16x32_bf16 v[104:107], v[140:143], v[202:205], v[104:107]
	v_mfma_f32_16x16x32_bf16 v[100:103], v[132:135], v[210:213], v[100:103]
	s_setprio 0
	v_mfma_f32_16x16x32_bf16 v[96:99], v[140:143], v[210:213], v[96:99]
	s_barrier
	s_add_i32 s44, 0, 0x14000
	s_add_i32 s20, s43, s31
	s_mov_b32 m0, s20
	s_nop 0
	global_load_lds_dwordx4 v188, s[24:25]
	s_add_i32 m0, s20, 0x2000
	s_nop 0
	global_load_lds_dwordx4 v186, s[24:25]
	ds_read_b128 v[214:217], v226 offset:16384
	ds_read_b128 v[230:233], v226 offset:17408
	ds_read_b128 v[234:237], v226 offset:18432
	ds_read_b128 v[238:241], v226 offset:19456
	s_waitcnt lgkmcnt(0)
	s_setprio 1
	s_barrier
	v_mfma_f32_16x16x32_bf16 v[60:63], v[214:217], v[144:147], v[60:63]
	v_mfma_f32_16x16x32_bf16 v[56:59], v[234:237], v[144:147], v[56:59]
	v_mfma_f32_16x16x32_bf16 v[52:55], v[214:217], v[152:155], v[52:55]
	v_mfma_f32_16x16x32_bf16 v[48:51], v[234:237], v[152:155], v[48:51]
	v_mfma_f32_16x16x32_bf16 v[44:47], v[214:217], v[198:201], v[44:47]
	v_mfma_f32_16x16x32_bf16 v[40:43], v[234:237], v[198:201], v[40:43]
	v_mfma_f32_16x16x32_bf16 v[36:39], v[214:217], v[206:209], v[36:39]
	v_mfma_f32_16x16x32_bf16 v[32:35], v[234:237], v[206:209], v[32:35]
	v_mfma_f32_16x16x32_bf16 v[60:63], v[230:233], v[148:151], v[60:63]
	s_mov_b32 m0, s34
	v_mfma_f32_16x16x32_bf16 v[56:59], v[238:241], v[148:151], v[56:59]
	s_mov_b64 s[100:101], s[26:27]
	v_mfma_f32_16x16x32_bf16 v[52:55], v[230:233], v[194:197], v[52:55]
	v_mfma_f32_16x16x32_bf16 v[48:51], v[238:241], v[194:197], v[48:51]
	v_mfma_f32_16x16x32_bf16 v[44:47], v[230:233], v[202:205], v[44:47]
	v_mfma_f32_16x16x32_bf16 v[40:43], v[238:241], v[202:205], v[40:43]
	v_mfma_f32_16x16x32_bf16 v[36:39], v[230:233], v[210:213], v[36:39]
	s_setprio 0
	v_mfma_f32_16x16x32_bf16 v[32:35], v[238:241], v[210:213], v[32:35]
	s_barrier
	global_load_lds_dwordx4 v188, s[26:27]
	s_mov_b64 s[100:101], s[26:27]
	s_mov_b32 m0, s35
	s_nop 0
	global_load_lds_dwordx4 v186, s[26:27]
	ds_read_b128 v[144:147], v228 offset:16384
	ds_read_b128 v[148:151], v228 offset:17408
	ds_read_b128 v[152:155], v228 offset:18432
	ds_read_b128 v[194:197], v228 offset:19456
	ds_read_b128 v[198:201], v228 offset:20480
	ds_read_b128 v[202:205], v228 offset:21504
	ds_read_b128 v[206:209], v228 offset:22528
	ds_read_b128 v[210:213], v228 offset:23552
	s_waitcnt lgkmcnt(0)
	s_setprio 1
	s_barrier
	v_mfma_f32_16x16x32_bf16 v[92:95], v[128:131], v[144:147], v[92:95]
	v_mfma_f32_16x16x32_bf16 v[88:91], v[136:139], v[144:147], v[88:91]
	v_mfma_f32_16x16x32_bf16 v[84:87], v[128:131], v[152:155], v[84:87]
	v_mfma_f32_16x16x32_bf16 v[80:83], v[136:139], v[152:155], v[80:83]
	v_mfma_f32_16x16x32_bf16 v[76:79], v[128:131], v[198:201], v[76:79]
	v_mfma_f32_16x16x32_bf16 v[72:75], v[136:139], v[198:201], v[72:75]
	v_mfma_f32_16x16x32_bf16 v[68:71], v[128:131], v[206:209], v[68:71]
	v_mfma_f32_16x16x32_bf16 v[64:67], v[136:139], v[206:209], v[64:67]
	v_mfma_f32_16x16x32_bf16 v[92:95], v[132:135], v[148:151], v[92:95]
	v_mfma_f32_16x16x32_bf16 v[88:91], v[140:143], v[148:151], v[88:91]
	v_mfma_f32_16x16x32_bf16 v[84:87], v[132:135], v[194:197], v[84:87]
	v_mfma_f32_16x16x32_bf16 v[80:83], v[140:143], v[194:197], v[80:83]
	v_mfma_f32_16x16x32_bf16 v[76:79], v[132:135], v[202:205], v[76:79]
	v_mfma_f32_16x16x32_bf16 v[72:75], v[140:143], v[202:205], v[72:75]
	v_mfma_f32_16x16x32_bf16 v[68:71], v[132:135], v[210:213], v[68:71]
	s_setprio 0
	v_mfma_f32_16x16x32_bf16 v[64:67], v[140:143], v[210:213], v[64:67]
	s_barrier
	s_add_u32 s20, s24, 0x90000
	s_addc_u32 s21, s25, 0
	s_add_i32 s43, s44, s31
	s_mov_b32 m0, s43
	s_nop 0
	global_load_lds_dwordx4 v188, s[20:21]
	s_add_i32 m0, s43, 0x2000
	s_nop 0
	global_load_lds_dwordx4 v186, s[20:21]
	s_waitcnt vmcnt(6)
	s_setprio 1
	s_barrier
; #define PG8_STAGE(bufoff, gbase) do { _Pragma("unroll") for (int _i = 0; _i < 2; ++_i) \
;         __builtin_amdgcn_global_load_lds((const unsigned*)((const char*)(gbase) + voff[_i]), (LAS unsigned*)(lds + (bufoff) + ldsw + _i * 8192), 16, 0, 0); } while (0)
; #define PG8_LDA(dst, b, h) do { _Pragma("unroll") for (int m = 0; m < 4; ++m) _Pragma("unroll") for (int k = 0; k < 2; ++k) dst[m][k] = *(const LAS bf16x8*)(lds + PG8_SA(b, h) + aoff + m * 2048 + k * 1024); } while (0)
; #define PG8_LDB(dst, b, h) do { _Pragma("unroll") for (int n = 0; n < 2; ++n) _Pragma("unroll") for (int k = 0; k < 2; ++k) dst[n][k] = *(const LAS bf16x8*)(lds + PG8_SB(b, h) + boff + n * 2048 + k * 1024); } while (0)
; #define PG8_MMA(ai, bj, At, Bt) do { __builtin_amdgcn_s_setprio(1); _Pragma("unroll") for (int m = 0; m < 4; ++m) _Pragma("unroll") for (int n = 0; n < 2; ++n) _Pragma("unroll") for (int k = 0; k < 2; ++k) \
;         acc[ai][bj][m][n] = __builtin_amdgcn_mfma_f32_16x16x32_bf16(Bt[n][k], At[m][k], acc[ai][bj][m][n], 0, 0, 0); __builtin_amdgcn_s_setprio(0); } while (0)
; #define PG8_WAIT_V(n) asm volatile("s_waitcnt vmcnt(" #n ")" ::: "memory")
; #define PG8_WAIT_L(n) asm volatile("s_waitcnt lgkmcnt(" #n ")" ::: "memory")
; #define PG8_BAR __builtin_amdgcn_s_barrier()
; #define PG8_SCHED __builtin_amdgcn_sched_barrier(0)
; template <class Epi>
; DI void gemm_phase(LAS unsigned char* lds, const Gemm g, const StaticOrder& S, const Epi& E) {
;     ...
;             PG8_WAIT_V(6); PG8_BAR; PG8_MMA(1, 1, At, B1); PG8_BAR;
;             PG8_LDB(B0, 1, 0); PG8_SCHED; PG8_LDA(At, 1, 0); PG8_STAGE(PG8_SA(0, 1), a2 + hstep);
;             PG8_WAIT_L(8); PG8_BAR; PG8_WAIT_L(0); PG8_MMA(0, 0, At, B0); PG8_BAR; PG8_SCHED;
;             PG8_LDB(B1, 1, 1); PG8_STAGE(PG8_SB(1, 0), b3);
;             PG8_BAR; PG8_WAIT_L(0); PG8_MMA(0, 1, At, B1); PG8_BAR;
;             PG8_LDA(At, 1, 1); PG8_STAGE(PG8_SA(1, 0), a3);
;             PG8_BAR; PG8_WAIT_L(0); PG8_MMA(1, 0, At, B0); PG8_BAR; PG8_SCHED;
;             PG8_STAGE(PG8_SB(1, 1), b3 + hstep);
	v_mfma_f32_16x16x32_bf16 v[28:31], v[214:217], v[144:147], v[28:31]
	v_mfma_f32_16x16x32_bf16 v[24:27], v[234:237], v[144:147], v[24:27]
	v_mfma_f32_16x16x32_bf16 v[20:23], v[214:217], v[152:155], v[20:23]
	v_mfma_f32_16x16x32_bf16 v[16:19], v[234:237], v[152:155], v[16:19]
	v_mfma_f32_16x16x32_bf16 v[12:15], v[214:217], v[198:201], v[12:15]
	v_mfma_f32_16x16x32_bf16 v[8:11], v[234:237], v[198:201], v[8:11]
	v_mfma_f32_16x16x32_bf16 v[4:7], v[214:217], v[206:209], v[4:7]
	v_mfma_f32_16x16x32_bf16 v[0:3], v[234:237], v[206:209], v[0:3]
	v_mfma_f32_16x16x32_bf16 v[28:31], v[230:233], v[148:151], v[28:31]
	s_add_i32 s43, 0, 0x18000
	v_mfma_f32_16x16x32_bf16 v[24:27], v[238:241], v[148:151], v[24:27]
	v_mfma_f32_16x16x32_bf16 v[20:23], v[230:233], v[194:197], v[20:23]
	v_mfma_f32_16x16x32_bf16 v[16:19], v[238:241], v[194:197], v[16:19]
	v_mfma_f32_16x16x32_bf16 v[12:15], v[230:233], v[202:205], v[12:15]
	v_mfma_f32_16x16x32_bf16 v[8:11], v[238:241], v[202:205], v[8:11]
	v_mfma_f32_16x16x32_bf16 v[4:7], v[230:233], v[210:213], v[4:7]
	s_setprio 0
	v_mfma_f32_16x16x32_bf16 v[0:3], v[238:241], v[210:213], v[0:3]
	s_barrier
	s_add_u32 s20, s26, 0x90000
	s_addc_u32 s21, s27, 0
	s_mov_b32 m0, s36
	s_nop 0
	global_load_lds_dwordx4 v188, s[20:21]
	s_mov_b32 m0, s37
	s_nop 0
	global_load_lds_dwordx4 v186, s[20:21]
	ds_read_b128 v[128:131], v226 offset:32768
	ds_read_b128 v[132:135], v226 offset:33792
	ds_read_b128 v[136:139], v226 offset:34816
	ds_read_b128 v[140:143], v226 offset:35840
	ds_read_b128 v[144:147], v228 offset:32768
	ds_read_b128 v[148:151], v228 offset:33792
	ds_read_b128 v[152:155], v228 offset:34816
	ds_read_b128 v[194:197], v228 offset:35840
	ds_read_b128 v[198:201], v228 offset:36864
	ds_read_b128 v[202:205], v228 offset:37888
	ds_read_b128 v[206:209], v228 offset:38912
	ds_read_b128 v[210:213], v228 offset:39936
	s_waitcnt lgkmcnt(8)
	s_setprio 1
	s_barrier
	s_waitcnt lgkmcnt(0)
	v_mfma_f32_16x16x32_bf16 v[124:127], v[128:131], v[144:147], v[124:127]
	v_mfma_f32_16x16x32_bf16 v[120:123], v[136:139], v[144:147], v[120:123]
	v_mfma_f32_16x16x32_bf16 v[116:119], v[128:131], v[152:155], v[116:119]
	v_mfma_f32_16x16x32_bf16 v[112:115], v[136:139], v[152:155], v[112:115]
	v_mfma_f32_16x16x32_bf16 v[108:111], v[128:131], v[198:201], v[108:111]
	v_mfma_f32_16x16x32_bf16 v[104:107], v[136:139], v[198:201], v[104:107]
	v_mfma_f32_16x16x32_bf16 v[100:103], v[128:131], v[206:209], v[100:103]
	v_mfma_f32_16x16x32_bf16 v[96:99], v[136:139], v[206:209], v[96:99]
	v_mfma_f32_16x16x32_bf16 v[124:127], v[132:135], v[148:151], v[124:127]
	v_mfma_f32_16x16x32_bf16 v[120:123], v[140:143], v[148:151], v[120:123]
	v_mfma_f32_16x16x32_bf16 v[116:119], v[132:135], v[194:197], v[116:119]
	v_mfma_f32_16x16x32_bf16 v[112:115], v[140:143], v[194:197], v[112:115]
	v_mfma_f32_16x16x32_bf16 v[108:111], v[132:135], v[202:205], v[108:111]
	v_mfma_f32_16x16x32_bf16 v[104:107], v[140:143], v[202:205], v[104:107]
	v_mfma_f32_16x16x32_bf16 v[100:103], v[132:135], v[210:213], v[100:103]
	s_setprio 0
	v_mfma_f32_16x16x32_bf16 v[96:99], v[140:143], v[210:213], v[96:99]
	s_barrier
	s_add_i32 s26, 0, 0x1c000
	s_add_i32 s20, s43, s31
	s_add_i32 m0, s20, 0xffffff80
	s_nop 0
	global_load_lds_dwordx4 v188, s[24:25] offset:128
	s_add_i32 m0, s20, 0x1f80
	s_nop 0
	global_load_lds_dwordx4 v186, s[24:25] offset:128
	ds_read_b128 v[214:217], v226 offset:49152
	ds_read_b128 v[230:233], v226 offset:50176
	ds_read_b128 v[234:237], v226 offset:51200
	ds_read_b128 v[238:241], v226 offset:52224
	s_waitcnt lgkmcnt(0)
	s_setprio 1
	s_barrier
	v_mfma_f32_16x16x32_bf16 v[60:63], v[214:217], v[144:147], v[60:63]
	v_mfma_f32_16x16x32_bf16 v[56:59], v[234:237], v[144:147], v[56:59]
	v_mfma_f32_16x16x32_bf16 v[52:55], v[214:217], v[152:155], v[52:55]
	v_mfma_f32_16x16x32_bf16 v[48:51], v[234:237], v[152:155], v[48:51]
	v_mfma_f32_16x16x32_bf16 v[44:47], v[214:217], v[198:201], v[44:47]
	v_mfma_f32_16x16x32_bf16 v[40:43], v[234:237], v[198:201], v[40:43]
	v_mfma_f32_16x16x32_bf16 v[36:39], v[214:217], v[206:209], v[36:39]
	v_mfma_f32_16x16x32_bf16 v[32:35], v[234:237], v[206:209], v[32:35]
	v_mfma_f32_16x16x32_bf16 v[60:63], v[230:233], v[148:151], v[60:63]
	s_add_i32 m0, s38, 0xffffff80
	v_mfma_f32_16x16x32_bf16 v[56:59], v[238:241], v[148:151], v[56:59]
	v_mfma_f32_16x16x32_bf16 v[52:55], v[230:233], v[194:197], v[52:55]
	v_mfma_f32_16x16x32_bf16 v[48:51], v[238:241], v[194:197], v[48:51]
	v_mfma_f32_16x16x32_bf16 v[44:47], v[230:233], v[202:205], v[44:47]
	v_mfma_f32_16x16x32_bf16 v[40:43], v[238:241], v[202:205], v[40:43]
	v_mfma_f32_16x16x32_bf16 v[36:39], v[230:233], v[210:213], v[36:39]
	s_setprio 0
	v_mfma_f32_16x16x32_bf16 v[32:35], v[238:241], v[210:213], v[32:35]
	s_barrier
	global_load_lds_dwordx4 v188, s[100:101] offset:128
	s_add_i32 m0, s39, 0xffffff80
	s_nop 0
	global_load_lds_dwordx4 v186, s[100:101] offset:128
	ds_read_b128 v[144:147], v228 offset:49152
	ds_read_b128 v[148:151], v228 offset:50176
	ds_read_b128 v[152:155], v228 offset:51200
	ds_read_b128 v[194:197], v228 offset:52224
	ds_read_b128 v[198:201], v228 offset:53248
	ds_read_b128 v[202:205], v228 offset:54272
	ds_read_b128 v[206:209], v228 offset:55296
	ds_read_b128 v[210:213], v228 offset:56320
	s_waitcnt lgkmcnt(0)
	s_setprio 1
	s_barrier
; #define PG8_WAIT_V(n) asm volatile("s_waitcnt vmcnt(" #n ")" ::: "memory")
; #define PG8_BAR __builtin_amdgcn_s_barrier()
; template <class Epi>
; DI void gemm_phase(LAS unsigned char* lds, const Gemm g, const StaticOrder& S, const Epi& E) {
;     ...
;             PG8_STAGE(PG8_SB(1, 1), b3 + hstep);
;             PG8_WAIT_V(6); PG8_BAR; PG8_MMA(1, 1, At, B1); PG8_BAR;
;         }
;         E(acc, cur, wr, wc, fr, fq);
;     template <bool LN, int BJ, int LO, int HI> DI void batch(const f32x4 (&acc)[2][2][4][2], unsigned row0, unsigned col0, const f32x4 (&gv)[2], const f32x4 (&bv)[2]) const {
;         f32x4 r[HI - LO]; float mean[(HI - LO) / 2], rstd[(HI - LO) / 2];
; #pragma unroll
;         for (int i = LO; i < HI; ++i) { const int ai = i >> 3, m = (i >> 1) & 3, n = i & 1; const unsigned row = row0 + ai * HALF + m * 16;
;             if (n == 0) { mean[(i - LO) >> 1] = 0.f; rstd[(i - LO) >> 1] = 1.f;
;                 if (LN) { const float2 st = *(const float2*)(stats + row * 2u); mean[(i - LO) >> 1] = st.x; rstd[(i - LO) >> 1] = st.y; } }
;             r[i - LO] = *(const f32x4*)(src + (row * (unsigned)DM + col0 + BJ * HALF + n * 16)); }
; #pragma unroll
;         for (int i = LO; i < HI; ++i) { const int ai = i >> 3, m = (i >> 1) & 3, n = i & 1; const unsigned row = row0 + ai * HALF + m * 16;
;             *(f32x4*)(Y + (row * (unsigned)DM + col0 + BJ * HALF + n * 16)) = acc[ai][BJ][m][n] + ((r[i - LO] - mean[(i - LO) >> 1]) * rstd[(i - LO) >> 1]) * gv[n] + bv[n]; }
;         __builtin_amdgcn_sched_barrier(0);
;     }
;     template <bool LN, int BJ> DI void load_gb(unsigned col0, f32x4 (&gv)[2], f32x4 (&bv)[2]) const {
; #pragma unroll
;         for (int n = 0; n < 2; ++n) {
;             if (LN) { gv[n] = *(const f32x4*)(gam + col0 + BJ * HALF + n * 16) * ALPHA; bv[n] = *(const f32x4*)(bet + col0 + BJ * HALF + n * 16) * ALPHA; }
;             else { gv[n] = (f32x4){ALPHA, ALPHA, ALPHA, ALPHA}; bv[n] = (f32x4){0.f, 0.f, 0.f, 0.f}; }
;         }
;     }
;     template <bool LN> DI void run(const f32x4 (&acc)[2][2][4][2], const Unit& u, int wr, int wc, int fr, int fq) const {
;         const unsigned row0 = u.pm * BM + wr * 64 + fr, col0 = u.pn * BM + wc * 32 + 4 * fq;
;         f32x4 gv[2], bv[2];
;         load_gb<LN, 0>(col0, gv, bv);
;         batch<LN, 0, 0, 4>(acc, row0, col0, gv, bv);
	v_mfma_f32_16x16x32_bf16 v[92:95], v[128:131], v[144:147], v[92:95]
	v_mfma_f32_16x16x32_bf16 v[88:91], v[136:139], v[144:147], v[88:91]
	v_mfma_f32_16x16x32_bf16 v[84:87], v[128:131], v[152:155], v[84:87]
	v_mfma_f32_16x16x32_bf16 v[80:83], v[136:139], v[152:155], v[80:83]
	v_mfma_f32_16x16x32_bf16 v[76:79], v[128:131], v[198:201], v[76:79]
	v_mfma_f32_16x16x32_bf16 v[72:75], v[136:139], v[198:201], v[72:75]
	v_mfma_f32_16x16x32_bf16 v[68:71], v[128:131], v[206:209], v[68:71]
	v_mfma_f32_16x16x32_bf16 v[64:67], v[136:139], v[206:209], v[64:67]
	v_mfma_f32_16x16x32_bf16 v[92:95], v[132:135], v[148:151], v[92:95]
	v_mfma_f32_16x16x32_bf16 v[88:91], v[140:143], v[148:151], v[88:91]
	v_mfma_f32_16x16x32_bf16 v[84:87], v[132:135], v[194:197], v[84:87]
	v_mfma_f32_16x16x32_bf16 v[80:83], v[140:143], v[194:197], v[80:83]
	v_mfma_f32_16x16x32_bf16 v[76:79], v[132:135], v[202:205], v[76:79]
	v_mfma_f32_16x16x32_bf16 v[72:75], v[140:143], v[202:205], v[72:75]
	v_mfma_f32_16x16x32_bf16 v[68:71], v[132:135], v[210:213], v[68:71]
	s_setprio 0
	v_mfma_f32_16x16x32_bf16 v[64:67], v[140:143], v[210:213], v[64:67]
	s_barrier
	s_add_u32 s20, s24, 0x90080
	s_addc_u32 s21, s25, 0
	s_add_i32 s24, s26, s31
	s_mov_b32 m0, s24
	s_nop 0
	global_load_lds_dwordx4 v188, s[20:21]
	s_add_i32 m0, s24, 0x2000
	s_nop 0
	global_load_lds_dwordx4 v186, s[20:21]
	s_waitcnt vmcnt(6)
	s_setprio 1
	s_barrier
	v_mfma_f32_16x16x32_bf16 v[28:31], v[214:217], v[144:147], v[28:31]
	v_mfma_f32_16x16x32_bf16 v[24:27], v[234:237], v[144:147], v[24:27]
	v_mfma_f32_16x16x32_bf16 v[20:23], v[214:217], v[152:155], v[20:23]
	v_mfma_f32_16x16x32_bf16 v[16:19], v[234:237], v[152:155], v[16:19]
	v_mfma_f32_16x16x32_bf16 v[12:15], v[214:217], v[198:201], v[12:15]
	v_mfma_f32_16x16x32_bf16 v[8:11], v[234:237], v[198:201], v[8:11]
	v_mfma_f32_16x16x32_bf16 v[4:7], v[214:217], v[206:209], v[4:7]
	v_mfma_f32_16x16x32_bf16 v[0:3], v[234:237], v[206:209], v[0:3]
	v_mfma_f32_16x16x32_bf16 v[28:31], v[230:233], v[148:151], v[28:31]
	s_add_i32 s33, s33, 2
	v_mfma_f32_16x16x32_bf16 v[24:27], v[238:241], v[148:151], v[24:27]
	s_add_u32 s4, s4, 0x100
	v_mfma_f32_16x16x32_bf16 v[20:23], v[230:233], v[194:197], v[20:23]
	s_addc_u32 s5, s5, 0
	v_mfma_f32_16x16x32_bf16 v[16:19], v[238:241], v[194:197], v[16:19]
	s_cmp_gt_u32 s33, 33
	v_mfma_f32_16x16x32_bf16 v[12:15], v[230:233], v[202:205], v[12:15]
	s_mov_b64 s[20:21], s[22:23]
	v_mfma_f32_16x16x32_bf16 v[8:11], v[238:241], v[202:205], v[8:11]
	v_mfma_f32_16x16x32_bf16 v[4:7], v[230:233], v[210:213], v[4:7]
	s_setprio 0
	v_mfma_f32_16x16x32_bf16 v[0:3], v[238:241], v[210:213], v[0:3]
	s_barrier
	s_cbranch_scc0 .LBB0_77
	v_lshl_add_u32 v206, s3, 8, v225
	v_lshl_or_b32 v158, s2, 8, v227
	v_lshlrev_b32_e32 v232, 11, v206
	s_andn2_b64 vcc, exec, s[14:15]
	v_or_b32_e32 v231, 16, v158
	v_add_u32_e32 v194, v232, v158
	v_or_b32_e32 v230, 0x80, v158
	v_or_b32_e32 v229, 0x90, v158
	s_cbranch_vccnz .LBB0_80
	v_lshlrev_b64 v[132:133], 2, v[158:159]
	v_lshl_add_u64 v[140:141], s[16:17], 0, v[132:133]
	global_load_dwordx4 v[128:131], v[140:141], off
	v_lshl_add_u64 v[142:143], s[18:19], 0, v[132:133]
	v_readlane_b32 s2, v253, 8
	v_mov_b32_e32 v195, v159
	v_lshlrev_b32_e32 v136, 1, v206
	v_mov_b32_e32 v137, v159
	v_readlane_b32 s3, v253, 9
	v_lshlrev_b64 v[212:213], 2, v[194:195]
	v_add_u32_e32 v146, v232, v231
	v_lshl_add_u64 v[144:145], v[136:137], 2, s[2:3]
	v_lshl_add_u64 v[136:137], s[88:89], 0, v[212:213]
	v_mov_b32_e32 v147, v159
	v_lshl_add_u64 v[146:147], v[146:147], 2, s[88:89]
	v_or_b32_e32 v195, 16, v206
	v_mov_b32_e32 v201, v159
	v_mov_b32_e32 v209, v159
	v_lshl_add_u64 v[212:213], s[90:91], 0, v[212:213]
	s_waitcnt vmcnt(0)
	v_pk_mul_f32 v[152:153], v[130:131], s[78:79] op_sel_hi:[1,0]
	v_pk_mul_f32 v[154:155], v[128:129], s[78:79] op_sel_hi:[1,0]
	global_load_dwordx4 v[132:135], v[142:143], off
	global_load_dwordx4 v[128:131], v[140:141], off offset:64
	global_load_dwordx2 v[204:205], v[144:145], off
	global_load_dwordx4 v[196:199], v[146:147], off
	v_lshlrev_b32_e32 v146, 1, v195
	global_load_dwordx4 v[136:139], v[136:137], off
	v_lshlrev_b32_e32 v195, 11, v195
	v_mov_b32_e32 v147, v159
	v_add_u32_e32 v200, v195, v158
	v_lshl_add_u64 v[146:147], v[146:147], 2, s[2:3]
	v_lshl_add_u64 v[200:201], v[200:201], 2, s[88:89]
	global_load_dwordx2 v[214:215], v[146:147], off
	v_add_u32_e32 v208, v195, v231
	global_load_dwordx4 v[200:203], v[200:201], off
	v_lshl_add_u64 v[208:209], v[208:209], 2, s[88:89]
	global_load_dwordx4 v[208:211], v[208:209], off
	s_waitcnt vmcnt(0)
	v_pk_mul_f32 v[148:149], v[130:131], s[78:79] op_sel_hi:[1,0]
	v_pk_mul_f32 v[150:151], v[128:129], s[78:79] op_sel_hi:[1,0]
	global_load_dwordx4 v[128:131], v[142:143], off offset:64
	v_sub_f32_e32 v137, v137, v204
	v_sub_f32_e32 v136, v136, v204
	v_sub_f32_e32 v139, v139, v204
	v_sub_f32_e32 v138, v138, v204
	v_pk_mul_f32 v[138:139], v[204:205], v[138:139] op_sel:[1,0]
	v_pk_mul_f32 v[136:137], v[204:205], v[136:137] op_sel:[1,0]
	v_pk_fma_f32 v[138:139], v[152:153], v[138:139], v[126:127]
	v_pk_fma_f32 v[136:137], v[154:155], v[136:137], v[124:125]
	v_pk_fma_f32 v[138:139], v[134:135], s[78:79], v[138:139] op_sel_hi:[1,0,1]
	v_pk_fma_f32 v[136:137], v[132:133], s[78:79], v[136:137] op_sel_hi:[1,0,1]
	global_store_dwordx4 v[212:213], v[136:139], off
	s_nop 1
	v_sub_f32_e32 v137, v197, v204
	v_sub_f32_e32 v136, v196, v204
	v_sub_f32_e32 v139, v199, v204
	v_sub_f32_e32 v138, v198, v204
	v_pk_mul_f32 v[138:139], v[204:205], v[138:139] op_sel:[1,0]
	v_pk_mul_f32 v[136:137], v[204:205], v[136:137] op_sel:[1,0]
	v_pk_fma_f32 v[138:139], v[148:149], v[138:139], v[122:123]
	v_pk_fma_f32 v[136:137], v[150:151], v[136:137], v[120:121]
	v_or_b32_e32 v196, 16, v194
	v_mov_b32_e32 v197, v159
	v_lshl_add_u64 v[196:197], v[196:197], 2, s[90:91]
	s_waitcnt vmcnt(0)
;     template <bool LN, int BJ, int LO, int HI> DI void batch(const f32x4 (&acc)[2][2][4][2], unsigned row0, unsigned col0, const f32x4 (&gv)[2], const f32x4 (&bv)[2]) const {
;         f32x4 r[HI - LO]; float mean[(HI - LO) / 2], rstd[(HI - LO) / 2];
; #pragma unroll
;         for (int i = LO; i < HI; ++i) { const int ai = i >> 3, m = (i >> 1) & 3, n = i & 1; const unsigned row = row0 + ai * HALF + m * 16;
;             if (n == 0) { mean[(i - LO) >> 1] = 0.f; rstd[(i - LO) >> 1] = 1.f;
;                 if (LN) { const float2 st = *(const float2*)(stats + row * 2u); mean[(i - LO) >> 1] = st.x; rstd[(i - LO) >> 1] = st.y; } }
;             r[i - LO] = *(const f32x4*)(src + (row * (unsigned)DM + col0 + BJ * HALF + n * 16)); }
; #pragma unroll
;         for (int i = LO; i < HI; ++i) { const int ai = i >> 3, m = (i >> 1) & 3, n = i & 1; const unsigned row = row0 + ai * HALF + m * 16;
;             *(f32x4*)(Y + (row * (unsigned)DM + col0 + BJ * HALF + n * 16)) = acc[ai][BJ][m][n] + ((r[i - LO] - mean[(i - LO) >> 1]) * rstd[(i - LO) >> 1]) * gv[n] + bv[n]; }
;         __builtin_amdgcn_sched_barrier(0);
;     }
;     template <bool LN, int BJ> DI void load_gb(unsigned col0, f32x4 (&gv)[2], f32x4 (&bv)[2]) const {
; #pragma unroll
;         for (int n = 0; n < 2; ++n) {
;             if (LN) { gv[n] = *(const f32x4*)(gam + col0 + BJ * HALF + n * 16) * ALPHA; bv[n] = *(const f32x4*)(bet + col0 + BJ * HALF + n * 16) * ALPHA; }
;             else { gv[n] = (f32x4){ALPHA, ALPHA, ALPHA, ALPHA}; bv[n] = (f32x4){0.f, 0.f, 0.f, 0.f}; }
;         }
;     }
;     template <bool LN> DI void run(const f32x4 (&acc)[2][2][4][2], const Unit& u, int wr, int wc, int fr, int fq) const {
;         const unsigned row0 = u.pm * BM + wr * 64 + fr, col0 = u.pn * BM + wc * 32 + 4 * fq;
;         f32x4 gv[2], bv[2];
;         load_gb<LN, 0>(col0, gv, bv);
;         batch<LN, 0, 0, 4>(acc, row0, col0, gv, bv);
;         batch<LN, 0, 4, 8>(acc, row0, col0, gv, bv);
;         batch<LN, 0, 8, 12>(acc, row0, col0, gv, bv);
	v_pk_fma_f32 v[138:139], v[130:131], s[78:79], v[138:139] op_sel_hi:[1,0,1]
	v_pk_fma_f32 v[136:137], v[128:129], s[78:79], v[136:137] op_sel_hi:[1,0,1]
	global_store_dwordx4 v[196:197], v[136:139], off
	v_add_u32_e32 v196, 0x8000, v194
	v_mov_b32_e32 v197, v159
	v_sub_f32_e32 v137, v201, v214
	v_sub_f32_e32 v136, v200, v214
	v_sub_f32_e32 v139, v203, v214
	v_sub_f32_e32 v138, v202, v214
	v_pk_mul_f32 v[138:139], v[214:215], v[138:139] op_sel:[1,0]
	v_pk_mul_f32 v[136:137], v[214:215], v[136:137] op_sel:[1,0]
	v_pk_fma_f32 v[138:139], v[152:153], v[138:139], v[118:119]
	v_pk_fma_f32 v[136:137], v[154:155], v[136:137], v[116:117]
	v_pk_fma_f32 v[138:139], v[134:135], s[78:79], v[138:139] op_sel_hi:[1,0,1]
	v_pk_fma_f32 v[136:137], v[132:133], s[78:79], v[136:137] op_sel_hi:[1,0,1]
	v_lshl_add_u64 v[196:197], v[196:197], 2, s[90:91]
	global_store_dwordx4 v[196:197], v[136:139], off
	v_add_u32_e32 v196, 0x8010, v194
	v_mov_b32_e32 v197, v159
	v_sub_f32_e32 v137, v209, v214
	v_sub_f32_e32 v136, v208, v214
	v_sub_f32_e32 v139, v211, v214
	v_sub_f32_e32 v138, v210, v214
	v_pk_mul_f32 v[138:139], v[214:215], v[138:139] op_sel:[1,0]
	v_pk_mul_f32 v[136:137], v[214:215], v[136:137] op_sel:[1,0]
	v_pk_fma_f32 v[138:139], v[148:149], v[138:139], v[114:115]
	v_pk_fma_f32 v[136:137], v[150:151], v[136:137], v[112:113]
	v_pk_fma_f32 v[138:139], v[130:131], s[78:79], v[138:139] op_sel_hi:[1,0,1]
	v_pk_fma_f32 v[136:137], v[128:129], s[78:79], v[136:137] op_sel_hi:[1,0,1]
	v_lshl_add_u64 v[196:197], v[196:197], 2, s[90:91]
	global_store_dwordx4 v[196:197], v[136:139], off
	s_nop 1
	v_or_b32_e32 v138, 32, v206
	v_lshlrev_b32_e32 v136, 1, v138
	v_mov_b32_e32 v137, v159
	v_lshlrev_b32_e32 v236, 11, v138
	v_lshl_add_u64 v[200:201], v[136:137], 2, s[2:3]
	v_add_u32_e32 v136, v236, v158
	v_lshl_add_u64 v[136:137], v[136:137], 2, s[88:89]
	global_load_dwordx2 v[204:205], v[200:201], off
	v_add_u32_e32 v196, v236, v231
	global_load_dwordx4 v[136:139], v[136:137], off
	v_mov_b32_e32 v197, v159
	v_lshl_add_u64 v[196:197], v[196:197], 2, s[88:89]
	global_load_dwordx4 v[196:199], v[196:197], off
	v_or_b32_e32 v207, 48, v206
	v_lshlrev_b32_e32 v235, 11, v207
	v_lshlrev_b32_e32 v202, 1, v207
	v_mov_b32_e32 v203, v159
	v_add_u32_e32 v208, v235, v158
	v_mov_b32_e32 v209, v159
	v_lshl_add_u64 v[202:203], v[202:203], 2, s[2:3]
	v_lshl_add_u64 v[208:209], v[208:209], 2, s[88:89]
	global_load_dwordx2 v[216:217], v[202:203], off
	v_add_u32_e32 v212, v235, v231
	global_load_dwordx4 v[208:211], v[208:209], off
	v_mov_b32_e32 v213, v159
	v_lshl_add_u64 v[212:213], v[212:213], 2, s[88:89]
	global_load_dwordx4 v[212:215], v[212:213], off
	v_add_u32_e32 v218, 0x10000, v194
	v_mov_b32_e32 v219, v159
	v_lshl_add_u64 v[218:219], v[218:219], 2, s[90:91]
	s_waitcnt vmcnt(0)
	v_sub_f32_e32 v137, v137, v204
	v_sub_f32_e32 v136, v136, v204
	v_sub_f32_e32 v139, v139, v204
	v_sub_f32_e32 v138, v138, v204
	v_pk_mul_f32 v[138:139], v[204:205], v[138:139] op_sel:[1,0]
	v_pk_mul_f32 v[136:137], v[204:205], v[136:137] op_sel:[1,0]
	v_pk_fma_f32 v[138:139], v[152:153], v[138:139], v[110:111]
	v_pk_fma_f32 v[136:137], v[154:155], v[136:137], v[108:109]
	v_pk_fma_f32 v[138:139], v[134:135], s[78:79], v[138:139] op_sel_hi:[1,0,1]
	v_pk_fma_f32 v[136:137], v[132:133], s[78:79], v[136:137] op_sel_hi:[1,0,1]
	global_store_dwordx4 v[218:219], v[136:139], off
	s_nop 1
	v_sub_f32_e32 v137, v197, v204
	v_sub_f32_e32 v136, v196, v204
	v_sub_f32_e32 v139, v199, v204
	v_sub_f32_e32 v138, v198, v204
	v_pk_mul_f32 v[138:139], v[204:205], v[138:139] op_sel:[1,0]
	v_pk_mul_f32 v[136:137], v[204:205], v[136:137] op_sel:[1,0]
	v_pk_fma_f32 v[138:139], v[148:149], v[138:139], v[106:107]
	v_pk_fma_f32 v[136:137], v[150:151], v[136:137], v[104:105]
	v_add_u32_e32 v196, 0x10010, v194
	v_mov_b32_e32 v197, v159
	v_pk_fma_f32 v[138:139], v[130:131], s[78:79], v[138:139] op_sel_hi:[1,0,1]
	v_pk_fma_f32 v[136:137], v[128:129], s[78:79], v[136:137] op_sel_hi:[1,0,1]
	v_lshl_add_u64 v[196:197], v[196:197], 2, s[90:91]
	global_store_dwordx4 v[196:197], v[136:139], off
	v_add_u32_e32 v196, 0x18000, v194
	v_mov_b32_e32 v197, v159
	v_sub_f32_e32 v137, v209, v216
	v_sub_f32_e32 v136, v208, v216
	v_sub_f32_e32 v139, v211, v216
	v_sub_f32_e32 v138, v210, v216
	v_pk_mul_f32 v[138:139], v[216:217], v[138:139] op_sel:[1,0]
	v_pk_mul_f32 v[136:137], v[216:217], v[136:137] op_sel:[1,0]
	v_pk_fma_f32 v[138:139], v[152:153], v[138:139], v[102:103]
	v_pk_fma_f32 v[136:137], v[154:155], v[136:137], v[100:101]
	v_pk_fma_f32 v[138:139], v[134:135], s[78:79], v[138:139] op_sel_hi:[1,0,1]
	v_pk_fma_f32 v[136:137], v[132:133], s[78:79], v[136:137] op_sel_hi:[1,0,1]
	v_lshl_add_u64 v[196:197], v[196:197], 2, s[90:91]
	global_store_dwordx4 v[196:197], v[136:139], off
	v_add_u32_e32 v196, 0x18010, v194
	v_mov_b32_e32 v197, v159
	v_sub_f32_e32 v137, v213, v216
	v_sub_f32_e32 v136, v212, v216
	v_sub_f32_e32 v139, v215, v216
	v_sub_f32_e32 v138, v214, v216
	v_pk_mul_f32 v[138:139], v[216:217], v[138:139] op_sel:[1,0]
	v_pk_mul_f32 v[136:137], v[216:217], v[136:137] op_sel:[1,0]
	v_pk_fma_f32 v[138:139], v[148:149], v[138:139], v[98:99]
	v_pk_fma_f32 v[136:137], v[150:151], v[136:137], v[96:97]
	v_pk_fma_f32 v[138:139], v[130:131], s[78:79], v[138:139] op_sel_hi:[1,0,1]
	v_pk_fma_f32 v[136:137], v[128:129], s[78:79], v[136:137] op_sel_hi:[1,0,1]
	v_lshl_add_u64 v[196:197], v[196:197], 2, s[90:91]
	global_store_dwordx4 v[196:197], v[136:139], off
	s_nop 1
	v_add_u32_e32 v138, 0x80, v206
	v_lshlrev_b32_e32 v136, 1, v138
	v_mov_b32_e32 v137, v159
	v_lshlrev_b32_e32 v233, 11, v138
	v_lshl_add_u64 v[196:197], v[136:137], 2, s[2:3]
	v_add_u32_e32 v136, v233, v158
	v_lshl_add_u64 v[136:137], v[136:137], 2, s[88:89]
	global_load_dwordx2 v[204:205], v[196:197], off
	v_add_u32_e32 v198, v233, v231
	global_load_dwordx4 v[136:139], v[136:137], off
	v_mov_b32_e32 v199, v159
	v_add_u32_e32 v207, 0x90, v206
	v_lshl_add_u64 v[198:199], v[198:199], 2, s[88:89]
	v_lshlrev_b32_e32 v234, 11, v207
	global_load_dwordx4 v[208:211], v[198:199], off
	v_add_u32_e32 v212, v234, v158
	v_mov_b32_e32 v213, v159
	v_lshl_add_u64 v[212:213], v[212:213], 2, s[88:89]
	global_load_dwordx4 v[212:215], v[212:213], off
	v_lshlrev_b32_e32 v198, 1, v207
	v_mov_b32_e32 v199, v159
	v_lshl_add_u64 v[198:199], v[198:199], 2, s[2:3]
	global_load_dwordx2 v[220:221], v[198:199], off
	v_add_u32_e32 v216, v234, v231
	v_mov_b32_e32 v217, v159
	v_lshl_add_u64 v[216:217], v[216:217], 2, s[88:89]
	global_load_dwordx4 v[216:219], v[216:217], off
	v_add_u32_e32 v238, 0x40000, v194
	v_mov_b32_e32 v239, v159
	v_lshl_add_u64 v[238:239], v[238:239], 2, s[90:91]
	s_waitcnt vmcnt(0)
;     template <bool LN, int BJ, int LO, int HI> DI void batch(const f32x4 (&acc)[2][2][4][2], unsigned row0, unsigned col0, const f32x4 (&gv)[2], const f32x4 (&bv)[2]) const {
;         f32x4 r[HI - LO]; float mean[(HI - LO) / 2], rstd[(HI - LO) / 2];
; #pragma unroll
;         for (int i = LO; i < HI; ++i) { const int ai = i >> 3, m = (i >> 1) & 3, n = i & 1; const unsigned row = row0 + ai * HALF + m * 16;
;             if (n == 0) { mean[(i - LO) >> 1] = 0.f; rstd[(i - LO) >> 1] = 1.f;
;                 if (LN) { const float2 st = *(const float2*)(stats + row * 2u); mean[(i - LO) >> 1] = st.x; rstd[(i - LO) >> 1] = st.y; } }
;             r[i - LO] = *(const f32x4*)(src + (row * (unsigned)DM + col0 + BJ * HALF + n * 16)); }
; #pragma unroll
;         for (int i = LO; i < HI; ++i) { const int ai = i >> 3, m = (i >> 1) & 3, n = i & 1; const unsigned row = row0 + ai * HALF + m * 16;
;             *(f32x4*)(Y + (row * (unsigned)DM + col0 + BJ * HALF + n * 16)) = acc[ai][BJ][m][n] + ((r[i - LO] - mean[(i - LO) >> 1]) * rstd[(i - LO) >> 1]) * gv[n] + bv[n]; }
;         __builtin_amdgcn_sched_barrier(0);
;     }
;     template <bool LN, int BJ> DI void load_gb(unsigned col0, f32x4 (&gv)[2], f32x4 (&bv)[2]) const {
; #pragma unroll
;         for (int n = 0; n < 2; ++n) {
;             if (LN) { gv[n] = *(const f32x4*)(gam + col0 + BJ * HALF + n * 16) * ALPHA; bv[n] = *(const f32x4*)(bet + col0 + BJ * HALF + n * 16) * ALPHA; }
;             else { gv[n] = (f32x4){ALPHA, ALPHA, ALPHA, ALPHA}; bv[n] = (f32x4){0.f, 0.f, 0.f, 0.f}; }
;         }
;     }
;     template <bool LN> DI void run(const f32x4 (&acc)[2][2][4][2], const Unit& u, int wr, int wc, int fr, int fq) const {
;         const unsigned row0 = u.pm * BM + wr * 64 + fr, col0 = u.pn * BM + wc * 32 + 4 * fq;
;         f32x4 gv[2], bv[2];
;         load_gb<LN, 0>(col0, gv, bv);
;         batch<LN, 0, 0, 4>(acc, row0, col0, gv, bv);
;         batch<LN, 0, 4, 8>(acc, row0, col0, gv, bv);
;         batch<LN, 0, 8, 12>(acc, row0, col0, gv, bv);
;         batch<LN, 0, 12, 16>(acc, row0, col0, gv, bv);
;         load_gb<LN, 1>(col0, gv, bv);
	v_sub_f32_e32 v137, v137, v204
	v_sub_f32_e32 v136, v136, v204
	v_sub_f32_e32 v139, v139, v204
	v_sub_f32_e32 v138, v138, v204
	v_pk_mul_f32 v[138:139], v[204:205], v[138:139] op_sel:[1,0]
	v_pk_mul_f32 v[136:137], v[204:205], v[136:137] op_sel:[1,0]
	v_pk_fma_f32 v[138:139], v[152:153], v[138:139], v[94:95]
	v_pk_fma_f32 v[136:137], v[154:155], v[136:137], v[92:93]
	v_pk_fma_f32 v[138:139], v[134:135], s[78:79], v[138:139] op_sel_hi:[1,0,1]
	v_pk_fma_f32 v[136:137], v[132:133], s[78:79], v[136:137] op_sel_hi:[1,0,1]
	global_store_dwordx4 v[238:239], v[136:139], off
	s_nop 1
	v_sub_f32_e32 v137, v209, v204
	v_sub_f32_e32 v136, v208, v204
	v_sub_f32_e32 v139, v211, v204
	v_sub_f32_e32 v138, v210, v204
	v_pk_mul_f32 v[138:139], v[204:205], v[138:139] op_sel:[1,0]
	v_pk_mul_f32 v[136:137], v[204:205], v[136:137] op_sel:[1,0]
	v_pk_fma_f32 v[138:139], v[148:149], v[138:139], v[90:91]
	v_pk_fma_f32 v[136:137], v[150:151], v[136:137], v[88:89]
	v_add_u32_e32 v204, 0x40010, v194
	v_mov_b32_e32 v205, v159
	v_pk_fma_f32 v[138:139], v[130:131], s[78:79], v[138:139] op_sel_hi:[1,0,1]
	v_pk_fma_f32 v[136:137], v[128:129], s[78:79], v[136:137] op_sel_hi:[1,0,1]
	v_lshl_add_u64 v[204:205], v[204:205], 2, s[90:91]
	global_store_dwordx4 v[204:205], v[136:139], off
	v_add_u32_e32 v204, 0x48000, v194
	v_mov_b32_e32 v205, v159
	v_sub_f32_e32 v137, v213, v220
	v_sub_f32_e32 v136, v212, v220
	v_sub_f32_e32 v139, v215, v220
	v_sub_f32_e32 v138, v214, v220
	v_pk_mul_f32 v[138:139], v[220:221], v[138:139] op_sel:[1,0]
	v_pk_mul_f32 v[136:137], v[220:221], v[136:137] op_sel:[1,0]
	v_pk_fma_f32 v[138:139], v[152:153], v[138:139], v[86:87]
	v_pk_fma_f32 v[136:137], v[154:155], v[136:137], v[84:85]
	v_pk_fma_f32 v[138:139], v[134:135], s[78:79], v[138:139] op_sel_hi:[1,0,1]
	v_pk_fma_f32 v[136:137], v[132:133], s[78:79], v[136:137] op_sel_hi:[1,0,1]
	v_lshl_add_u64 v[204:205], v[204:205], 2, s[90:91]
	global_store_dwordx4 v[204:205], v[136:139], off
	v_add_u32_e32 v204, 0x48010, v194
	v_mov_b32_e32 v205, v159
	v_sub_f32_e32 v137, v217, v220
	v_sub_f32_e32 v136, v216, v220
	v_sub_f32_e32 v139, v219, v220
	v_sub_f32_e32 v138, v218, v220
	v_pk_mul_f32 v[138:139], v[220:221], v[138:139] op_sel:[1,0]
	v_pk_mul_f32 v[136:137], v[220:221], v[136:137] op_sel:[1,0]
	v_pk_fma_f32 v[138:139], v[148:149], v[138:139], v[82:83]
	v_pk_fma_f32 v[136:137], v[150:151], v[136:137], v[80:81]
	v_pk_fma_f32 v[138:139], v[130:131], s[78:79], v[138:139] op_sel_hi:[1,0,1]
	v_pk_fma_f32 v[136:137], v[128:129], s[78:79], v[136:137] op_sel_hi:[1,0,1]
	v_lshl_add_u64 v[204:205], v[204:205], 2, s[90:91]
	global_store_dwordx4 v[204:205], v[136:139], off
	s_nop 1
	v_add_u32_e32 v138, 0xa0, v206
	v_lshlrev_b32_e32 v136, 1, v138
	v_mov_b32_e32 v137, v159
	v_lshlrev_b32_e32 v237, 11, v138
	v_lshl_add_u64 v[204:205], v[136:137], 2, s[2:3]
	v_add_u32_e32 v136, v237, v158
	v_lshl_add_u64 v[136:137], v[136:137], 2, s[88:89]
	global_load_dwordx2 v[220:221], v[204:205], off
	v_add_u32_e32 v208, v237, v231
	global_load_dwordx4 v[136:139], v[136:137], off
	v_mov_b32_e32 v209, v159
	v_lshl_add_u64 v[208:209], v[208:209], 2, s[88:89]
	global_load_dwordx4 v[212:215], v[208:209], off
	v_add_u32_e32 v208, 0xb0, v206
	v_lshlrev_b32_e32 v206, 1, v208
	v_mov_b32_e32 v207, v159
	v_lshlrev_b32_e32 v238, 11, v208
	v_lshl_add_u64 v[210:211], v[206:207], 2, s[2:3]
	v_add_u32_e32 v206, v238, v158
	v_lshl_add_u64 v[206:207], v[206:207], 2, s[88:89]
	global_load_dwordx2 v[240:241], v[210:211], off
	v_add_u32_e32 v216, v238, v231
	global_load_dwordx4 v[206:209], v[206:207], off
	v_mov_b32_e32 v217, v159
	v_lshl_add_u64 v[216:217], v[216:217], 2, s[88:89]
	global_load_dwordx4 v[216:219], v[216:217], off
	v_add_u32_e32 v242, 0x50000, v194
	v_mov_b32_e32 v243, v159
	v_lshl_add_u64 v[242:243], v[242:243], 2, s[90:91]
	s_waitcnt vmcnt(0)
	v_sub_f32_e32 v137, v137, v220
	v_sub_f32_e32 v136, v136, v220
	v_sub_f32_e32 v139, v139, v220
	v_sub_f32_e32 v138, v138, v220
	v_pk_mul_f32 v[138:139], v[220:221], v[138:139] op_sel:[1,0]
	v_pk_mul_f32 v[136:137], v[220:221], v[136:137] op_sel:[1,0]
	v_pk_fma_f32 v[138:139], v[152:153], v[138:139], v[78:79]
	v_pk_fma_f32 v[136:137], v[154:155], v[136:137], v[76:77]
	v_pk_fma_f32 v[138:139], v[134:135], s[78:79], v[138:139] op_sel_hi:[1,0,1]
	v_pk_fma_f32 v[136:137], v[132:133], s[78:79], v[136:137] op_sel_hi:[1,0,1]
	global_store_dwordx4 v[242:243], v[136:139], off
	s_nop 1
	v_sub_f32_e32 v137, v213, v220
	v_sub_f32_e32 v136, v212, v220
	v_sub_f32_e32 v139, v215, v220
	v_sub_f32_e32 v138, v214, v220
	v_pk_mul_f32 v[138:139], v[220:221], v[138:139] op_sel:[1,0]
	v_pk_mul_f32 v[136:137], v[220:221], v[136:137] op_sel:[1,0]
	v_pk_fma_f32 v[138:139], v[148:149], v[138:139], v[74:75]
	v_pk_fma_f32 v[136:137], v[150:151], v[136:137], v[72:73]
	v_add_u32_e32 v212, 0x50010, v194
	v_mov_b32_e32 v213, v159
	v_pk_fma_f32 v[138:139], v[130:131], s[78:79], v[138:139] op_sel_hi:[1,0,1]
	v_pk_fma_f32 v[136:137], v[128:129], s[78:79], v[136:137] op_sel_hi:[1,0,1]
	v_lshl_add_u64 v[212:213], v[212:213], 2, s[90:91]
	global_store_dwordx4 v[212:213], v[136:139], off
	s_nop 1
	v_sub_f32_e32 v137, v207, v240
	v_sub_f32_e32 v136, v206, v240
	v_sub_f32_e32 v139, v209, v240
	v_sub_f32_e32 v138, v208, v240
	v_pk_mul_f32 v[136:137], v[240:241], v[136:137] op_sel:[1,0]
	v_pk_mul_f32 v[138:139], v[240:241], v[138:139] op_sel:[1,0]
	v_pk_fma_f32 v[136:137], v[154:155], v[136:137], v[68:69]
	v_pk_fma_f32 v[138:139], v[152:153], v[138:139], v[70:71]
	v_pk_fma_f32 v[132:133], v[132:133], s[78:79], v[136:137] op_sel_hi:[1,0,1]
	v_add_u32_e32 v136, 0x58000, v194
	v_mov_b32_e32 v137, v159
	v_pk_fma_f32 v[134:135], v[134:135], s[78:79], v[138:139] op_sel_hi:[1,0,1]
	v_lshl_add_u64 v[136:137], v[136:137], 2, s[90:91]
	global_store_dwordx4 v[136:137], v[132:135], off
	s_nop 1
	v_sub_f32_e32 v133, v217, v240
	v_sub_f32_e32 v132, v216, v240
	v_sub_f32_e32 v135, v219, v240
	v_sub_f32_e32 v134, v218, v240
	v_pk_mul_f32 v[132:133], v[240:241], v[132:133] op_sel:[1,0]
	v_pk_mul_f32 v[134:135], v[240:241], v[134:135] op_sel:[1,0]
	v_pk_fma_f32 v[132:133], v[150:151], v[132:133], v[64:65]
	v_pk_fma_f32 v[134:135], v[148:149], v[134:135], v[66:67]
	v_pk_fma_f32 v[128:129], v[128:129], s[78:79], v[132:133] op_sel_hi:[1,0,1]
	v_add_u32_e32 v132, 0x58010, v194
	v_mov_b32_e32 v133, v159
	v_pk_fma_f32 v[130:131], v[130:131], s[78:79], v[134:135] op_sel_hi:[1,0,1]
	v_lshl_add_u64 v[132:133], v[132:133], 2, s[90:91]
	global_store_dwordx4 v[132:133], v[128:131], off
	global_load_dwordx4 v[128:131], v[140:141], off offset:512
	v_add_u32_e32 v136, v232, v230
	v_mov_b32_e32 v137, v159
	v_lshl_add_u64 v[136:137], v[136:137], 2, s[88:89]
	s_waitcnt vmcnt(0)
;     template <bool LN, int BJ, int LO, int HI> DI void batch(const f32x4 (&acc)[2][2][4][2], unsigned row0, unsigned col0, const f32x4 (&gv)[2], const f32x4 (&bv)[2]) const {
;         f32x4 r[HI - LO]; float mean[(HI - LO) / 2], rstd[(HI - LO) / 2];
; #pragma unroll
;         for (int i = LO; i < HI; ++i) { const int ai = i >> 3, m = (i >> 1) & 3, n = i & 1; const unsigned row = row0 + ai * HALF + m * 16;
;             if (n == 0) { mean[(i - LO) >> 1] = 0.f; rstd[(i - LO) >> 1] = 1.f;
;                 if (LN) { const float2 st = *(const float2*)(stats + row * 2u); mean[(i - LO) >> 1] = st.x; rstd[(i - LO) >> 1] = st.y; } }
;             r[i - LO] = *(const f32x4*)(src + (row * (unsigned)DM + col0 + BJ * HALF + n * 16)); }
; #pragma unroll
;         for (int i = LO; i < HI; ++i) { const int ai = i >> 3, m = (i >> 1) & 3, n = i & 1; const unsigned row = row0 + ai * HALF + m * 16;
;             *(f32x4*)(Y + (row * (unsigned)DM + col0 + BJ * HALF + n * 16)) = acc[ai][BJ][m][n] + ((r[i - LO] - mean[(i - LO) >> 1]) * rstd[(i - LO) >> 1]) * gv[n] + bv[n]; }
;         __builtin_amdgcn_sched_barrier(0);
;     }
;     template <bool LN, int BJ> DI void load_gb(unsigned col0, f32x4 (&gv)[2], f32x4 (&bv)[2]) const {
; #pragma unroll
;         for (int n = 0; n < 2; ++n) {
;             if (LN) { gv[n] = *(const f32x4*)(gam + col0 + BJ * HALF + n * 16) * ALPHA; bv[n] = *(const f32x4*)(bet + col0 + BJ * HALF + n * 16) * ALPHA; }
;             else { gv[n] = (f32x4){ALPHA, ALPHA, ALPHA, ALPHA}; bv[n] = (f32x4){0.f, 0.f, 0.f, 0.f}; }
;         }
;     }
;     template <bool LN> DI void run(const f32x4 (&acc)[2][2][4][2], const Unit& u, int wr, int wc, int fr, int fq) const {
;         const unsigned row0 = u.pm * BM + wr * 64 + fr, col0 = u.pn * BM + wc * 32 + 4 * fq;
;         f32x4 gv[2], bv[2];
;         load_gb<LN, 0>(col0, gv, bv);
;         batch<LN, 0, 0, 4>(acc, row0, col0, gv, bv);
;         batch<LN, 0, 4, 8>(acc, row0, col0, gv, bv);
;         batch<LN, 0, 8, 12>(acc, row0, col0, gv, bv);
;         batch<LN, 0, 12, 16>(acc, row0, col0, gv, bv);
;         load_gb<LN, 1>(col0, gv, bv);
;         batch<LN, 1, 0, 8>(acc, row0, col0, gv, bv);
;         batch<LN, 1, 8, 16>(acc, row0, col0, gv, bv);
	v_pk_mul_f32 v[212:213], v[130:131], s[78:79] op_sel_hi:[1,0]
	v_pk_mul_f32 v[214:215], v[128:129], s[78:79] op_sel_hi:[1,0]
	global_load_dwordx4 v[132:135], v[142:143], off offset:512
	global_load_dwordx4 v[128:131], v[140:141], off offset:576
	s_waitcnt vmcnt(0)
	v_pk_mul_f32 v[206:207], v[130:131], s[78:79] op_sel_hi:[1,0]
	v_pk_mul_f32 v[208:209], v[128:129], s[78:79] op_sel_hi:[1,0]
	global_load_dwordx4 v[128:131], v[142:143], off offset:576
	global_load_dwordx2 v[220:221], v[144:145], off
	global_load_dwordx4 v[240:243], v[136:137], off
	v_add_u32_e32 v136, v232, v229
	v_mov_b32_e32 v137, v159
	v_lshl_add_u64 v[136:137], v[136:137], 2, s[88:89]
	global_load_dwordx4 v[244:247], v[136:137], off
	global_load_dwordx2 v[218:219], v[146:147], off
	v_add_u32_e32 v136, v195, v230
	v_mov_b32_e32 v137, v159
	v_lshl_add_u64 v[136:137], v[136:137], 2, s[88:89]
	global_load_dwordx4 v[248:251], v[136:137], off
	v_add_u32_e32 v136, v195, v229
	v_mov_b32_e32 v137, v159
	v_lshl_add_u64 v[136:137], v[136:137], 2, s[88:89]
	global_load_dwordx4 v[152:155], v[136:137], off
	global_load_dwordx2 v[216:217], v[200:201], off
	v_add_u32_e32 v136, v236, v230
	v_mov_b32_e32 v137, v159
	v_lshl_add_u64 v[136:137], v[136:137], 2, s[88:89]
	global_load_dwordx4 v[148:151], v[136:137], off
	v_add_u32_e32 v136, v236, v229
	v_mov_b32_e32 v137, v159
	v_lshl_add_u64 v[136:137], v[136:137], 2, s[88:89]
	global_load_dwordx4 v[144:147], v[136:137], off
	global_load_dwordx2 v[200:201], v[202:203], off
	v_add_u32_e32 v136, v235, v230
	v_mov_b32_e32 v137, v159
	v_lshl_add_u64 v[136:137], v[136:137], 2, s[88:89]
	global_load_dwordx4 v[140:143], v[136:137], off
	v_add_u32_e32 v136, v235, v229
	v_mov_b32_e32 v137, v159
	v_lshl_add_u64 v[136:137], v[136:137], 2, s[88:89]
	global_load_dwordx4 v[136:139], v[136:137], off
	v_add_u32_e32 v202, 0x80, v194
	v_mov_b32_e32 v203, v159
	v_lshl_add_u64 v[202:203], v[202:203], 2, s[90:91]
	s_waitcnt vmcnt(0)
	v_sub_f32_e32 v241, v241, v220
	v_sub_f32_e32 v240, v240, v220
	v_sub_f32_e32 v243, v243, v220
	v_sub_f32_e32 v242, v242, v220
	v_pk_mul_f32 v[242:243], v[220:221], v[242:243] op_sel:[1,0]
	v_pk_mul_f32 v[240:241], v[220:221], v[240:241] op_sel:[1,0]
	v_pk_fma_f32 v[242:243], v[212:213], v[242:243], v[62:63]
	v_pk_fma_f32 v[240:241], v[214:215], v[240:241], v[60:61]
	v_pk_fma_f32 v[242:243], v[134:135], s[78:79], v[242:243] op_sel_hi:[1,0,1]
	v_pk_fma_f32 v[240:241], v[132:133], s[78:79], v[240:241] op_sel_hi:[1,0,1]
	global_store_dwordx4 v[202:203], v[240:243], off
	v_sub_f32_e32 v203, v245, v220
	v_sub_f32_e32 v202, v244, v220
	v_sub_f32_e32 v241, v247, v220
	v_sub_f32_e32 v240, v246, v220
	v_pk_mul_f32 v[202:203], v[220:221], v[202:203] op_sel:[1,0]
	v_pk_mul_f32 v[240:241], v[220:221], v[240:241] op_sel:[1,0]
	v_pk_fma_f32 v[202:203], v[208:209], v[202:203], v[56:57]
	v_pk_fma_f32 v[220:221], v[206:207], v[240:241], v[58:59]
	v_pk_fma_f32 v[240:241], v[128:129], s[78:79], v[202:203] op_sel_hi:[1,0,1]
	v_add_u32_e32 v202, 0x90, v194
	v_mov_b32_e32 v203, v159
	v_pk_fma_f32 v[242:243], v[130:131], s[78:79], v[220:221] op_sel_hi:[1,0,1]
	v_lshl_add_u64 v[202:203], v[202:203], 2, s[90:91]
	global_store_dwordx4 v[202:203], v[240:243], off
	v_sub_f32_e32 v203, v249, v218
	v_sub_f32_e32 v202, v248, v218
	v_sub_f32_e32 v221, v251, v218
	v_sub_f32_e32 v220, v250, v218
	v_pk_mul_f32 v[202:203], v[218:219], v[202:203] op_sel:[1,0]
	v_pk_mul_f32 v[220:221], v[218:219], v[220:221] op_sel:[1,0]
	v_pk_fma_f32 v[202:203], v[214:215], v[202:203], v[52:53]
	v_pk_fma_f32 v[220:221], v[212:213], v[220:221], v[54:55]
	v_pk_fma_f32 v[240:241], v[132:133], s[78:79], v[202:203] op_sel_hi:[1,0,1]
	v_add_u32_e32 v202, 0x8080, v194
	v_mov_b32_e32 v203, v159
	v_sub_f32_e32 v153, v153, v218
	v_sub_f32_e32 v152, v152, v218
	v_sub_f32_e32 v155, v155, v218
	v_sub_f32_e32 v154, v154, v218
	v_pk_fma_f32 v[242:243], v[134:135], s[78:79], v[220:221] op_sel_hi:[1,0,1]
	v_lshl_add_u64 v[202:203], v[202:203], 2, s[90:91]
	v_pk_mul_f32 v[154:155], v[218:219], v[154:155] op_sel:[1,0]
	v_pk_mul_f32 v[152:153], v[218:219], v[152:153] op_sel:[1,0]
	global_store_dwordx4 v[202:203], v[240:243], off
	v_pk_fma_f32 v[152:153], v[208:209], v[152:153], v[48:49]
	v_pk_fma_f32 v[154:155], v[206:207], v[154:155], v[50:51]
	v_add_u32_e32 v202, 0x8090, v194
	v_mov_b32_e32 v203, v159
	v_sub_f32_e32 v149, v149, v216
	v_sub_f32_e32 v148, v148, v216
	v_sub_f32_e32 v151, v151, v216
	v_sub_f32_e32 v150, v150, v216
	v_pk_fma_f32 v[154:155], v[130:131], s[78:79], v[154:155] op_sel_hi:[1,0,1]
	v_pk_fma_f32 v[152:153], v[128:129], s[78:79], v[152:153] op_sel_hi:[1,0,1]
	v_lshl_add_u64 v[202:203], v[202:203], 2, s[90:91]
	v_pk_mul_f32 v[150:151], v[216:217], v[150:151] op_sel:[1,0]
	v_pk_mul_f32 v[148:149], v[216:217], v[148:149] op_sel:[1,0]
	global_store_dwordx4 v[202:203], v[152:155], off
	v_pk_fma_f32 v[148:149], v[214:215], v[148:149], v[44:45]
	v_pk_fma_f32 v[150:151], v[212:213], v[150:151], v[46:47]
	v_add_u32_e32 v152, 0x10080, v194
	v_mov_b32_e32 v153, v159
	v_sub_f32_e32 v145, v145, v216
	v_sub_f32_e32 v144, v144, v216
	v_sub_f32_e32 v147, v147, v216
	v_sub_f32_e32 v146, v146, v216
	v_pk_fma_f32 v[150:151], v[134:135], s[78:79], v[150:151] op_sel_hi:[1,0,1]
	v_pk_fma_f32 v[148:149], v[132:133], s[78:79], v[148:149] op_sel_hi:[1,0,1]
	v_lshl_add_u64 v[152:153], v[152:153], 2, s[90:91]
	v_pk_mul_f32 v[146:147], v[216:217], v[146:147] op_sel:[1,0]
	v_pk_mul_f32 v[144:145], v[216:217], v[144:145] op_sel:[1,0]
	global_store_dwordx4 v[152:153], v[148:151], off
	v_pk_fma_f32 v[144:145], v[208:209], v[144:145], v[40:41]
	v_pk_fma_f32 v[146:147], v[206:207], v[146:147], v[42:43]
;     template <bool LN, int BJ, int LO, int HI> DI void batch(const f32x4 (&acc)[2][2][4][2], unsigned row0, unsigned col0, const f32x4 (&gv)[2], const f32x4 (&bv)[2]) const {
;         f32x4 r[HI - LO]; float mean[(HI - LO) / 2], rstd[(HI - LO) / 2];
; #pragma unroll
;         for (int i = LO; i < HI; ++i) { const int ai = i >> 3, m = (i >> 1) & 3, n = i & 1; const unsigned row = row0 + ai * HALF + m * 16;
;             if (n == 0) { mean[(i - LO) >> 1] = 0.f; rstd[(i - LO) >> 1] = 1.f;
;                 if (LN) { const float2 st = *(const float2*)(stats + row * 2u); mean[(i - LO) >> 1] = st.x; rstd[(i - LO) >> 1] = st.y; } }
;             r[i - LO] = *(const f32x4*)(src + (row * (unsigned)DM + col0 + BJ * HALF + n * 16)); }
; #pragma unroll
;         for (int i = LO; i < HI; ++i) { const int ai = i >> 3, m = (i >> 1) & 3, n = i & 1; const unsigned row = row0 + ai * HALF + m * 16;
;             *(f32x4*)(Y + (row * (unsigned)DM + col0 + BJ * HALF + n * 16)) = acc[ai][BJ][m][n] + ((r[i - LO] - mean[(i - LO) >> 1]) * rstd[(i - LO) >> 1]) * gv[n] + bv[n]; }
;         __builtin_amdgcn_sched_barrier(0);
;     }
;     template <bool LN, int BJ> DI void load_gb(unsigned col0, f32x4 (&gv)[2], f32x4 (&bv)[2]) const {
; #pragma unroll
;         for (int n = 0; n < 2; ++n) {
;             if (LN) { gv[n] = *(const f32x4*)(gam + col0 + BJ * HALF + n * 16) * ALPHA; bv[n] = *(const f32x4*)(bet + col0 + BJ * HALF + n * 16) * ALPHA; }
;             else { gv[n] = (f32x4){ALPHA, ALPHA, ALPHA, ALPHA}; bv[n] = (f32x4){0.f, 0.f, 0.f, 0.f}; }
;         }
;     }
;     template <bool LN> DI void run(const f32x4 (&acc)[2][2][4][2], const Unit& u, int wr, int wc, int fr, int fq) const {
;         const unsigned row0 = u.pm * BM + wr * 64 + fr, col0 = u.pn * BM + wc * 32 + 4 * fq;
;         f32x4 gv[2], bv[2];
;         load_gb<LN, 0>(col0, gv, bv);
;         batch<LN, 0, 0, 4>(acc, row0, col0, gv, bv);
;         batch<LN, 0, 4, 8>(acc, row0, col0, gv, bv);
;         batch<LN, 0, 8, 12>(acc, row0, col0, gv, bv);
;         batch<LN, 0, 12, 16>(acc, row0, col0, gv, bv);
;         load_gb<LN, 1>(col0, gv, bv);
;         batch<LN, 1, 0, 8>(acc, row0, col0, gv, bv);
;         batch<LN, 1, 8, 16>(acc, row0, col0, gv, bv);
	v_add_u32_e32 v148, 0x10090, v194
	v_mov_b32_e32 v149, v159
	v_sub_f32_e32 v141, v141, v200
	v_sub_f32_e32 v140, v140, v200
	v_sub_f32_e32 v143, v143, v200
	v_sub_f32_e32 v142, v142, v200
	v_pk_fma_f32 v[146:147], v[130:131], s[78:79], v[146:147] op_sel_hi:[1,0,1]
	v_pk_fma_f32 v[144:145], v[128:129], s[78:79], v[144:145] op_sel_hi:[1,0,1]
	v_lshl_add_u64 v[148:149], v[148:149], 2, s[90:91]
	v_pk_mul_f32 v[142:143], v[200:201], v[142:143] op_sel:[1,0]
	v_pk_mul_f32 v[140:141], v[200:201], v[140:141] op_sel:[1,0]
	global_store_dwordx4 v[148:149], v[144:147], off
	v_pk_fma_f32 v[140:141], v[214:215], v[140:141], v[36:37]
	v_pk_fma_f32 v[142:143], v[212:213], v[142:143], v[38:39]
	v_add_u32_e32 v144, 0x18080, v194
	v_mov_b32_e32 v145, v159
	v_sub_f32_e32 v137, v137, v200
	v_sub_f32_e32 v136, v136, v200
	v_sub_f32_e32 v139, v139, v200
	v_sub_f32_e32 v138, v138, v200
	v_pk_fma_f32 v[142:143], v[134:135], s[78:79], v[142:143] op_sel_hi:[1,0,1]
	v_pk_fma_f32 v[140:141], v[132:133], s[78:79], v[140:141] op_sel_hi:[1,0,1]
	v_lshl_add_u64 v[144:145], v[144:145], 2, s[90:91]
	v_pk_mul_f32 v[138:139], v[200:201], v[138:139] op_sel:[1,0]
	v_pk_mul_f32 v[136:137], v[200:201], v[136:137] op_sel:[1,0]
	global_store_dwordx4 v[144:145], v[140:143], off
	v_pk_fma_f32 v[136:137], v[208:209], v[136:137], v[32:33]
	v_pk_fma_f32 v[138:139], v[206:207], v[138:139], v[34:35]
	v_add_u32_e32 v140, 0x18090, v194
	v_mov_b32_e32 v141, v159
	v_pk_fma_f32 v[138:139], v[130:131], s[78:79], v[138:139] op_sel_hi:[1,0,1]
	v_pk_fma_f32 v[136:137], v[128:129], s[78:79], v[136:137] op_sel_hi:[1,0,1]
	v_lshl_add_u64 v[140:141], v[140:141], 2, s[90:91]
	global_store_dwordx4 v[140:141], v[136:139], off
	s_nop 1
	v_add_u32_e32 v136, v233, v230
	v_mov_b32_e32 v137, v159
	v_lshl_add_u64 v[136:137], v[136:137], 2, s[88:89]
	global_load_dwordx2 v[220:221], v[196:197], off
	global_load_dwordx4 v[216:219], v[136:137], off
	v_add_u32_e32 v136, v233, v229
	v_mov_b32_e32 v137, v159
	v_lshl_add_u64 v[136:137], v[136:137], 2, s[88:89]
	global_load_dwordx4 v[240:243], v[136:137], off
	global_load_dwordx2 v[200:201], v[198:199], off
	v_add_u32_e32 v136, v234, v230
	v_mov_b32_e32 v137, v159
	v_lshl_add_u64 v[136:137], v[136:137], 2, s[88:89]
	global_load_dwordx4 v[244:247], v[136:137], off
	v_add_u32_e32 v136, v234, v229
	v_mov_b32_e32 v137, v159
	v_lshl_add_u64 v[136:137], v[136:137], 2, s[88:89]
	global_load_dwordx4 v[152:155], v[136:137], off
	global_load_dwordx2 v[198:199], v[204:205], off
	v_add_u32_e32 v136, v237, v230
	v_mov_b32_e32 v137, v159
	v_lshl_add_u64 v[136:137], v[136:137], 2, s[88:89]
	global_load_dwordx4 v[148:151], v[136:137], off
	v_add_u32_e32 v136, v237, v229
	v_mov_b32_e32 v137, v159
	v_lshl_add_u64 v[136:137], v[136:137], 2, s[88:89]
	global_load_dwordx4 v[144:147], v[136:137], off
	global_load_dwordx2 v[196:197], v[210:211], off
	v_add_u32_e32 v136, v238, v230
	v_mov_b32_e32 v137, v159
	v_lshl_add_u64 v[136:137], v[136:137], 2, s[88:89]
	global_load_dwordx4 v[140:143], v[136:137], off
	v_add_u32_e32 v136, v238, v229
	v_mov_b32_e32 v137, v159
	v_lshl_add_u64 v[136:137], v[136:137], 2, s[88:89]
	global_load_dwordx4 v[136:139], v[136:137], off
	v_add_u32_e32 v210, 0x40080, v194
	v_mov_b32_e32 v211, v159
	v_lshl_add_u64 v[210:211], v[210:211], 2, s[90:91]
	s_waitcnt vmcnt(0)
;     template <bool LN, int BJ, int LO, int HI> DI void batch(const f32x4 (&acc)[2][2][4][2], unsigned row0, unsigned col0, const f32x4 (&gv)[2], const f32x4 (&bv)[2]) const {
;         f32x4 r[HI - LO]; float mean[(HI - LO) / 2], rstd[(HI - LO) / 2];
; #pragma unroll
;         for (int i = LO; i < HI; ++i) { const int ai = i >> 3, m = (i >> 1) & 3, n = i & 1; const unsigned row = row0 + ai * HALF + m * 16;
;             if (n == 0) { mean[(i - LO) >> 1] = 0.f; rstd[(i - LO) >> 1] = 1.f;
;                 if (LN) { const float2 st = *(const float2*)(stats + row * 2u); mean[(i - LO) >> 1] = st.x; rstd[(i - LO) >> 1] = st.y; } }
;             r[i - LO] = *(const f32x4*)(src + (row * (unsigned)DM + col0 + BJ * HALF + n * 16)); }
; #pragma unroll
;         for (int i = LO; i < HI; ++i) { const int ai = i >> 3, m = (i >> 1) & 3, n = i & 1; const unsigned row = row0 + ai * HALF + m * 16;
;             *(f32x4*)(Y + (row * (unsigned)DM + col0 + BJ * HALF + n * 16)) = acc[ai][BJ][m][n] + ((r[i - LO] - mean[(i - LO) >> 1]) * rstd[(i - LO) >> 1]) * gv[n] + bv[n]; }
;         __builtin_amdgcn_sched_barrier(0);
;     }
;     template <bool LN, int BJ> DI void load_gb(unsigned col0, f32x4 (&gv)[2], f32x4 (&bv)[2]) const {
; #pragma unroll
;         for (int n = 0; n < 2; ++n) {
;             if (LN) { gv[n] = *(const f32x4*)(gam + col0 + BJ * HALF + n * 16) * ALPHA; bv[n] = *(const f32x4*)(bet + col0 + BJ * HALF + n * 16) * ALPHA; }
;             else { gv[n] = (f32x4){ALPHA, ALPHA, ALPHA, ALPHA}; bv[n] = (f32x4){0.f, 0.f, 0.f, 0.f}; }
;         }
;     }
;     template <bool LN> DI void run(const f32x4 (&acc)[2][2][4][2], const Unit& u, int wr, int wc, int fr, int fq) const {
;         const unsigned row0 = u.pm * BM + wr * 64 + fr, col0 = u.pn * BM + wc * 32 + 4 * fq;
;         f32x4 gv[2], bv[2];
;         load_gb<LN, 0>(col0, gv, bv);
;         batch<LN, 0, 0, 4>(acc, row0, col0, gv, bv);
;         batch<LN, 0, 4, 8>(acc, row0, col0, gv, bv);
;         batch<LN, 0, 8, 12>(acc, row0, col0, gv, bv);
;         batch<LN, 0, 12, 16>(acc, row0, col0, gv, bv);
;         load_gb<LN, 1>(col0, gv, bv);
;         batch<LN, 1, 0, 8>(acc, row0, col0, gv, bv);
;         batch<LN, 1, 8, 16>(acc, row0, col0, gv, bv);
	v_sub_f32_e32 v203, v217, v220
	v_sub_f32_e32 v202, v216, v220
	v_sub_f32_e32 v205, v219, v220
	v_sub_f32_e32 v204, v218, v220
	v_pk_mul_f32 v[204:205], v[220:221], v[204:205] op_sel:[1,0]
	v_pk_mul_f32 v[202:203], v[220:221], v[202:203] op_sel:[1,0]
	v_pk_fma_f32 v[204:205], v[212:213], v[204:205], v[30:31]
	v_pk_fma_f32 v[202:203], v[214:215], v[202:203], v[28:29]
	v_pk_fma_f32 v[204:205], v[134:135], s[78:79], v[204:205] op_sel_hi:[1,0,1]
	v_pk_fma_f32 v[202:203], v[132:133], s[78:79], v[202:203] op_sel_hi:[1,0,1]
	global_store_dwordx4 v[210:211], v[202:205], off
	v_add_u32_e32 v210, 0x40090, v194
	v_mov_b32_e32 v211, v159
	v_sub_f32_e32 v203, v241, v220
	v_sub_f32_e32 v202, v240, v220
	v_sub_f32_e32 v205, v243, v220
	v_sub_f32_e32 v204, v242, v220
	v_pk_mul_f32 v[204:205], v[220:221], v[204:205] op_sel:[1,0]
	v_pk_mul_f32 v[202:203], v[220:221], v[202:203] op_sel:[1,0]
	v_pk_fma_f32 v[204:205], v[206:207], v[204:205], v[26:27]
	v_pk_fma_f32 v[202:203], v[208:209], v[202:203], v[24:25]
	v_pk_fma_f32 v[204:205], v[130:131], s[78:79], v[204:205] op_sel_hi:[1,0,1]
	v_pk_fma_f32 v[202:203], v[128:129], s[78:79], v[202:203] op_sel_hi:[1,0,1]
	v_lshl_add_u64 v[210:211], v[210:211], 2, s[90:91]
	global_store_dwordx4 v[210:211], v[202:205], off
	v_sub_f32_e32 v149, v149, v198
	v_sub_f32_e32 v148, v148, v198
	v_sub_f32_e32 v203, v245, v200
	v_sub_f32_e32 v202, v244, v200
	v_sub_f32_e32 v141, v141, v196
	v_sub_f32_e32 v140, v140, v196
	v_sub_f32_e32 v205, v247, v200
	v_sub_f32_e32 v204, v246, v200
	v_pk_mul_f32 v[202:203], v[200:201], v[202:203] op_sel:[1,0]
	v_sub_f32_e32 v151, v151, v198
	v_sub_f32_e32 v150, v150, v198
	v_pk_mul_f32 v[148:149], v[198:199], v[148:149] op_sel:[1,0]
	v_sub_f32_e32 v143, v143, v196
	v_sub_f32_e32 v142, v142, v196
	v_pk_mul_f32 v[140:141], v[196:197], v[140:141] op_sel:[1,0]
	v_pk_mul_f32 v[204:205], v[200:201], v[204:205] op_sel:[1,0]
	v_pk_fma_f32 v[202:203], v[214:215], v[202:203], v[20:21]
	v_sub_f32_e32 v153, v153, v200
	v_sub_f32_e32 v152, v152, v200
	v_sub_f32_e32 v155, v155, v200
	v_sub_f32_e32 v154, v154, v200
	v_pk_mul_f32 v[150:151], v[198:199], v[150:151] op_sel:[1,0]
	v_pk_fma_f32 v[148:149], v[214:215], v[148:149], v[12:13]
	v_pk_mul_f32 v[142:143], v[196:197], v[142:143] op_sel:[1,0]
	v_pk_fma_f32 v[140:141], v[214:215], v[140:141], v[4:5]
	v_pk_fma_f32 v[204:205], v[212:213], v[204:205], v[22:23]
	v_pk_fma_f32 v[202:203], v[132:133], s[78:79], v[202:203] op_sel_hi:[1,0,1]
	v_pk_mul_f32 v[154:155], v[200:201], v[154:155] op_sel:[1,0]
	v_pk_mul_f32 v[152:153], v[200:201], v[152:153] op_sel:[1,0]
	v_pk_fma_f32 v[150:151], v[212:213], v[150:151], v[14:15]
	v_pk_fma_f32 v[148:149], v[132:133], s[78:79], v[148:149] op_sel_hi:[1,0,1]
	v_pk_fma_f32 v[142:143], v[212:213], v[142:143], v[6:7]
	v_pk_fma_f32 v[132:133], v[132:133], s[78:79], v[140:141] op_sel_hi:[1,0,1]
	v_add_u32_e32 v140, 0x58080, v194
	v_mov_b32_e32 v141, v159
	v_pk_fma_f32 v[204:205], v[134:135], s[78:79], v[204:205] op_sel_hi:[1,0,1]
	v_pk_fma_f32 v[152:153], v[208:209], v[152:153], v[16:17]
	v_pk_fma_f32 v[154:155], v[206:207], v[154:155], v[18:19]
	v_add_u32_e32 v200, 0x48090, v194
	v_mov_b32_e32 v201, v159
	v_pk_fma_f32 v[150:151], v[134:135], s[78:79], v[150:151] op_sel_hi:[1,0,1]
	v_pk_fma_f32 v[134:135], v[134:135], s[78:79], v[142:143] op_sel_hi:[1,0,1]
	v_lshl_add_u64 v[140:141], v[140:141], 2, s[90:91]
	v_pk_fma_f32 v[154:155], v[130:131], s[78:79], v[154:155] op_sel_hi:[1,0,1]
	v_pk_fma_f32 v[152:153], v[128:129], s[78:79], v[152:153] op_sel_hi:[1,0,1]
	v_lshl_add_u64 v[200:201], v[200:201], 2, s[90:91]
	v_sub_f32_e32 v145, v145, v198
	v_sub_f32_e32 v144, v144, v198
	global_store_dwordx4 v[140:141], v[132:135], off
	global_store_dwordx4 v[200:201], v[152:155], off
	v_sub_f32_e32 v147, v147, v198
	v_sub_f32_e32 v133, v137, v196
	v_sub_f32_e32 v132, v136, v196
	v_add_u32_e32 v152, 0x50080, v194
	v_mov_b32_e32 v153, v159
	v_sub_f32_e32 v146, v146, v198
	v_pk_mul_f32 v[144:145], v[198:199], v[144:145] op_sel:[1,0]
	v_sub_f32_e32 v135, v139, v196
	v_sub_f32_e32 v134, v138, v196
	v_pk_mul_f32 v[132:133], v[196:197], v[132:133] op_sel:[1,0]
	v_lshl_add_u64 v[152:153], v[152:153], 2, s[90:91]
	v_pk_mul_f32 v[146:147], v[198:199], v[146:147] op_sel:[1,0]
	v_pk_fma_f32 v[144:145], v[208:209], v[144:145], v[8:9]
	v_pk_mul_f32 v[134:135], v[196:197], v[134:135] op_sel:[1,0]
	v_pk_fma_f32 v[132:133], v[208:209], v[132:133], v[0:1]
	v_add_u32_e32 v210, 0x48080, v194
	v_mov_b32_e32 v211, v159
	global_store_dwordx4 v[152:153], v[148:151], off
	v_pk_fma_f32 v[146:147], v[206:207], v[146:147], v[10:11]
	v_pk_fma_f32 v[144:145], v[128:129], s[78:79], v[144:145] op_sel_hi:[1,0,1]
	v_add_u32_e32 v148, 0x50090, v194
	v_mov_b32_e32 v149, v159
	v_pk_fma_f32 v[134:135], v[206:207], v[134:135], v[2:3]
	v_pk_fma_f32 v[128:129], v[128:129], s[78:79], v[132:133] op_sel_hi:[1,0,1]
	v_add_u32_e32 v132, 0x58090, v194
	v_mov_b32_e32 v133, v159
	v_lshl_add_u64 v[210:211], v[210:211], 2, s[90:91]
	v_pk_fma_f32 v[146:147], v[130:131], s[78:79], v[146:147] op_sel_hi:[1,0,1]
	v_lshl_add_u64 v[148:149], v[148:149], 2, s[90:91]
	v_pk_fma_f32 v[130:131], v[130:131], s[78:79], v[134:135] op_sel_hi:[1,0,1]
	v_lshl_add_u64 v[132:133], v[132:133], 2, s[90:91]
	global_store_dwordx4 v[210:211], v[202:205], off
	global_store_dwordx4 v[148:149], v[144:147], off
	global_store_dwordx4 v[132:133], v[128:131], off
	s_mov_b64 s[20:21], 0
	s_branch .LBB0_81

; #define PG8_STAGE(bufoff, gbase) do { _Pragma("unroll") for (int _i = 0; _i < 2; ++_i) \
;         __builtin_amdgcn_global_load_lds((const unsigned*)((const char*)(gbase) + voff[_i]), (LAS unsigned*)(lds + (bufoff) + ldsw + _i * 8192), 16, 0, 0); } while (0)
; #define PG8_LDA(dst, b, h) do { _Pragma("unroll") for (int m = 0; m < 4; ++m) _Pragma("unroll") for (int k = 0; k < 2; ++k) dst[m][k] = *(const LAS bf16x8*)(lds + PG8_SA(b, h) + aoff + m * 2048 + k * 1024); } while (0)
; #define PG8_LDB(dst, b, h) do { _Pragma("unroll") for (int n = 0; n < 2; ++n) _Pragma("unroll") for (int k = 0; k < 2; ++k) dst[n][k] = *(const LAS bf16x8*)(lds + PG8_SB(b, h) + boff + n * 2048 + k * 1024); } while (0)
; #define PG8_MMA(ai, bj, At, Bt) do { __builtin_amdgcn_s_setprio(1); _Pragma("unroll") for (int m = 0; m < 4; ++m) _Pragma("unroll") for (int n = 0; n < 2; ++n) _Pragma("unroll") for (int k = 0; k < 2; ++k) \
;         acc[ai][bj][m][n] = __builtin_amdgcn_mfma_f32_16x16x32_bf16(Bt[n][k], At[m][k], acc[ai][bj][m][n], 0, 0, 0); __builtin_amdgcn_s_setprio(0); } while (0)
; #define PG8_WAIT_V(n) asm volatile("s_waitcnt vmcnt(" #n ")" ::: "memory")
; #define PG8_WAIT_L(n) asm volatile("s_waitcnt lgkmcnt(" #n ")" ::: "memory")
; #define PG8_BAR __builtin_amdgcn_s_barrier()
; #define PG8_SCHED __builtin_amdgcn_sched_barrier(0)
; template <class Epi>
; DI void gemm_phase(LAS unsigned char* lds, const Gemm g, const StaticOrder& S, const Epi& E) {
;     ...
;         for (int t = 0; t < nt; t += 2) {
;             const bool last = (t == nt - 2);
;             const char* a1 = cA + (size_t)(t + 1) * kstep;
;             const char* a2 = last ? nA : cA + (size_t)(t + 2) * kstep; const char* b2 = last ? nB : cB + (size_t)(t + 2) * kstep;
;             const char* a3 = a2 + kstep; const char* b3 = b2 + kstep;
;             PG8_LDB(B0, 0, 0); PG8_SCHED; PG8_LDA(At, 0, 0); PG8_STAGE(PG8_SA(1, 1), a1 + hstep);
;             PG8_WAIT_L(8); PG8_BAR; PG8_WAIT_L(0); PG8_MMA(0, 0, At, B0); PG8_BAR; PG8_SCHED;
;             PG8_LDB(B1, 0, 1); PG8_STAGE(PG8_SB(0, 0), b2);
;             PG8_BAR; PG8_WAIT_L(0); PG8_MMA(0, 1, At, B1); PG8_BAR;
;             PG8_LDA(At, 0, 1); PG8_STAGE(PG8_SA(0, 0), a2);
;             PG8_BAR; PG8_WAIT_L(0); PG8_MMA(1, 0, At, B0); PG8_BAR; PG8_SCHED;
;             PG8_STAGE(PG8_SB(0, 1), b2 + hstep);
;             PG8_WAIT_V(6); PG8_BAR; PG8_MMA(1, 1, At, B1); PG8_BAR;
.LBB0_134:
	s_add_u32 s18, s16, 0x100
	s_addc_u32 s19, s17, 0
	s_add_i32 s39, 0, 0x10000
	s_cmpk_eq_i32 s33, 0x54
	s_cselect_b32 s23, s9, s19
	s_cselect_b32 s22, s8, s18
	s_cselect_b32 s21, s11, s5
	s_cselect_b32 s20, s10, s4
	s_add_i32 m0, s28, 0xc000
	s_nop 0
	global_load_lds_dwordx4 v144, s[16:17]
	s_add_i32 m0, s28, 0xe000
	s_nop 0
	global_load_lds_dwordx4 v146, s[16:17]
	ds_read_b128 v[96:99], v199
	ds_read_b128 v[100:103], v199 offset:1024
	ds_read_b128 v[136:139], v199 offset:2048
	ds_read_b128 v[148:151], v199 offset:3072
	ds_read_b128 v[152:155], v201
	ds_read_b128 v[186:189], v201 offset:1024
	ds_read_b128 v[190:193], v201 offset:2048
	ds_read_b128 v[194:197], v201 offset:3072
	ds_read_b128 v[202:205], v201 offset:4096
	ds_read_b128 v[206:209], v201 offset:5120
	ds_read_b128 v[210:213], v201 offset:6144
	ds_read_b128 v[214:217], v201 offset:7168
	s_waitcnt lgkmcnt(8)
	s_setprio 1
	s_barrier
	s_waitcnt lgkmcnt(0)
	v_mfma_f32_16x16x32_bf16 v[132:135], v[96:99], v[152:155], v[132:135]
	v_mfma_f32_16x16x32_bf16 v[128:131], v[136:139], v[152:155], v[128:131]
	v_mfma_f32_16x16x32_bf16 v[124:127], v[96:99], v[190:193], v[124:127]
	v_mfma_f32_16x16x32_bf16 v[120:123], v[136:139], v[190:193], v[120:123]
	v_mfma_f32_16x16x32_bf16 v[116:119], v[96:99], v[202:205], v[116:119]
	v_mfma_f32_16x16x32_bf16 v[112:115], v[136:139], v[202:205], v[112:115]
	v_mfma_f32_16x16x32_bf16 v[108:111], v[96:99], v[210:213], v[108:111]
	v_mfma_f32_16x16x32_bf16 v[104:107], v[136:139], v[210:213], v[104:107]
	v_mfma_f32_16x16x32_bf16 v[132:135], v[100:103], v[186:189], v[132:135]
	v_mfma_f32_16x16x32_bf16 v[128:131], v[148:151], v[186:189], v[128:131]
	v_mfma_f32_16x16x32_bf16 v[124:127], v[100:103], v[194:197], v[124:127]
	v_mfma_f32_16x16x32_bf16 v[120:123], v[148:151], v[194:197], v[120:123]
	v_mfma_f32_16x16x32_bf16 v[116:119], v[100:103], v[206:209], v[116:119]
	v_mfma_f32_16x16x32_bf16 v[112:115], v[148:151], v[206:209], v[112:115]
	v_mfma_f32_16x16x32_bf16 v[108:111], v[100:103], v[214:217], v[108:111]
	s_setprio 0
	v_mfma_f32_16x16x32_bf16 v[104:107], v[148:151], v[214:217], v[104:107]
	s_barrier
	s_add_i32 s40, 0, 0x14000
	s_add_i32 s16, s39, s27
	s_mov_b32 m0, s16
	s_nop 0
	global_load_lds_dwordx4 v142, s[20:21]
	s_add_i32 m0, s16, 0x2000
	s_nop 0
	global_load_lds_dwordx4 v140, s[20:21]
	ds_read_b128 v[226:229], v199 offset:16384
	ds_read_b128 v[230:233], v199 offset:17408
	ds_read_b128 v[234:237], v199 offset:18432
	ds_read_b128 v[238:241], v199 offset:19456
	s_waitcnt lgkmcnt(0)
	s_setprio 1
	s_barrier
	v_mfma_f32_16x16x32_bf16 v[60:63], v[226:229], v[152:155], v[60:63]
	v_mfma_f32_16x16x32_bf16 v[56:59], v[234:237], v[152:155], v[56:59]
	v_mfma_f32_16x16x32_bf16 v[52:55], v[226:229], v[190:193], v[52:55]
	v_mfma_f32_16x16x32_bf16 v[48:51], v[234:237], v[190:193], v[48:51]
	v_mfma_f32_16x16x32_bf16 v[44:47], v[226:229], v[202:205], v[44:47]
	v_mfma_f32_16x16x32_bf16 v[40:43], v[234:237], v[202:205], v[40:43]
	v_mfma_f32_16x16x32_bf16 v[36:39], v[226:229], v[210:213], v[36:39]
	v_mfma_f32_16x16x32_bf16 v[32:35], v[234:237], v[210:213], v[32:35]
	v_mfma_f32_16x16x32_bf16 v[60:63], v[230:233], v[186:189], v[60:63]
	s_mov_b32 m0, s28
	v_mfma_f32_16x16x32_bf16 v[56:59], v[238:241], v[186:189], v[56:59]
	s_mov_b64 s[100:101], s[22:23]
	v_mfma_f32_16x16x32_bf16 v[52:55], v[230:233], v[194:197], v[52:55]
	v_mfma_f32_16x16x32_bf16 v[48:51], v[238:241], v[194:197], v[48:51]
	v_mfma_f32_16x16x32_bf16 v[44:47], v[230:233], v[206:209], v[44:47]
	v_mfma_f32_16x16x32_bf16 v[40:43], v[238:241], v[206:209], v[40:43]
	v_mfma_f32_16x16x32_bf16 v[36:39], v[230:233], v[214:217], v[36:39]
	s_setprio 0
	v_mfma_f32_16x16x32_bf16 v[32:35], v[238:241], v[214:217], v[32:35]
	s_barrier
	global_load_lds_dwordx4 v142, s[22:23]
	s_mov_b64 s[100:101], s[22:23]
	s_mov_b32 m0, s29
	s_nop 0
	global_load_lds_dwordx4 v140, s[22:23]
	ds_read_b128 v[152:155], v201 offset:16384
	ds_read_b128 v[186:189], v201 offset:17408
	ds_read_b128 v[190:193], v201 offset:18432
	ds_read_b128 v[194:197], v201 offset:19456
	ds_read_b128 v[202:205], v201 offset:20480
	ds_read_b128 v[206:209], v201 offset:21504
	ds_read_b128 v[210:213], v201 offset:22528
	ds_read_b128 v[214:217], v201 offset:23552
	s_waitcnt lgkmcnt(0)
	s_setprio 1
	s_barrier
	v_mfma_f32_16x16x32_bf16 v[92:95], v[96:99], v[152:155], v[92:95]
	v_mfma_f32_16x16x32_bf16 v[88:91], v[136:139], v[152:155], v[88:91]
	v_mfma_f32_16x16x32_bf16 v[84:87], v[96:99], v[190:193], v[84:87]
	v_mfma_f32_16x16x32_bf16 v[80:83], v[136:139], v[190:193], v[80:83]
	v_mfma_f32_16x16x32_bf16 v[76:79], v[96:99], v[202:205], v[76:79]
	v_mfma_f32_16x16x32_bf16 v[72:75], v[136:139], v[202:205], v[72:75]
	v_mfma_f32_16x16x32_bf16 v[68:71], v[96:99], v[210:213], v[68:71]
	v_mfma_f32_16x16x32_bf16 v[64:67], v[136:139], v[210:213], v[64:67]
	v_mfma_f32_16x16x32_bf16 v[92:95], v[100:103], v[186:189], v[92:95]
	v_mfma_f32_16x16x32_bf16 v[88:91], v[148:151], v[186:189], v[88:91]
	v_mfma_f32_16x16x32_bf16 v[84:87], v[100:103], v[194:197], v[84:87]
	v_mfma_f32_16x16x32_bf16 v[80:83], v[148:151], v[194:197], v[80:83]
	v_mfma_f32_16x16x32_bf16 v[76:79], v[100:103], v[206:209], v[76:79]
	v_mfma_f32_16x16x32_bf16 v[72:75], v[148:151], v[206:209], v[72:75]
	v_mfma_f32_16x16x32_bf16 v[68:71], v[100:103], v[214:217], v[68:71]
	s_setprio 0
	v_mfma_f32_16x16x32_bf16 v[64:67], v[148:151], v[214:217], v[64:67]
	s_barrier
	s_add_u32 s16, s20, 0x160000
	s_addc_u32 s17, s21, 0
	s_add_i32 s39, s40, s27
	s_mov_b32 m0, s39
	s_nop 0
	global_load_lds_dwordx4 v142, s[16:17]
	s_add_i32 m0, s39, 0x2000
	s_nop 0
	global_load_lds_dwordx4 v140, s[16:17]
	s_waitcnt vmcnt(6)
	s_setprio 1
	s_barrier
; #define PG8_STAGE(bufoff, gbase) do { _Pragma("unroll") for (int _i = 0; _i < 2; ++_i) \
;         __builtin_amdgcn_global_load_lds((const unsigned*)((const char*)(gbase) + voff[_i]), (LAS unsigned*)(lds + (bufoff) + ldsw + _i * 8192), 16, 0, 0); } while (0)
; #define PG8_LDA(dst, b, h) do { _Pragma("unroll") for (int m = 0; m < 4; ++m) _Pragma("unroll") for (int k = 0; k < 2; ++k) dst[m][k] = *(const LAS bf16x8*)(lds + PG8_SA(b, h) + aoff + m * 2048 + k * 1024); } while (0)
; #define PG8_LDB(dst, b, h) do { _Pragma("unroll") for (int n = 0; n < 2; ++n) _Pragma("unroll") for (int k = 0; k < 2; ++k) dst[n][k] = *(const LAS bf16x8*)(lds + PG8_SB(b, h) + boff + n * 2048 + k * 1024); } while (0)
; #define PG8_MMA(ai, bj, At, Bt) do { __builtin_amdgcn_s_setprio(1); _Pragma("unroll") for (int m = 0; m < 4; ++m) _Pragma("unroll") for (int n = 0; n < 2; ++n) _Pragma("unroll") for (int k = 0; k < 2; ++k) \
;         acc[ai][bj][m][n] = __builtin_amdgcn_mfma_f32_16x16x32_bf16(Bt[n][k], At[m][k], acc[ai][bj][m][n], 0, 0, 0); __builtin_amdgcn_s_setprio(0); } while (0)
; #define PG8_WAIT_V(n) asm volatile("s_waitcnt vmcnt(" #n ")" ::: "memory")
; #define PG8_WAIT_L(n) asm volatile("s_waitcnt lgkmcnt(" #n ")" ::: "memory")
; #define PG8_BAR __builtin_amdgcn_s_barrier()
; #define PG8_SCHED __builtin_amdgcn_sched_barrier(0)
; template <class Epi>
; DI void gemm_phase(LAS unsigned char* lds, const Gemm g, const StaticOrder& S, const Epi& E) {
;     ...
;             PG8_WAIT_V(6); PG8_BAR; PG8_MMA(1, 1, At, B1); PG8_BAR;
;             PG8_LDB(B0, 1, 0); PG8_SCHED; PG8_LDA(At, 1, 0); PG8_STAGE(PG8_SA(0, 1), a2 + hstep);
;             PG8_WAIT_L(8); PG8_BAR; PG8_WAIT_L(0); PG8_MMA(0, 0, At, B0); PG8_BAR; PG8_SCHED;
;             PG8_LDB(B1, 1, 1); PG8_STAGE(PG8_SB(1, 0), b3);
;             PG8_BAR; PG8_WAIT_L(0); PG8_MMA(0, 1, At, B1); PG8_BAR;
;             PG8_LDA(At, 1, 1); PG8_STAGE(PG8_SA(1, 0), a3);
;             PG8_BAR; PG8_WAIT_L(0); PG8_MMA(1, 0, At, B0); PG8_BAR; PG8_SCHED;
	v_mfma_f32_16x16x32_bf16 v[28:31], v[226:229], v[152:155], v[28:31]
	v_mfma_f32_16x16x32_bf16 v[24:27], v[234:237], v[152:155], v[24:27]
	v_mfma_f32_16x16x32_bf16 v[20:23], v[226:229], v[190:193], v[20:23]
	v_mfma_f32_16x16x32_bf16 v[16:19], v[234:237], v[190:193], v[16:19]
	v_mfma_f32_16x16x32_bf16 v[12:15], v[226:229], v[202:205], v[12:15]
	v_mfma_f32_16x16x32_bf16 v[8:11], v[234:237], v[202:205], v[8:11]
	v_mfma_f32_16x16x32_bf16 v[4:7], v[226:229], v[210:213], v[4:7]
	v_mfma_f32_16x16x32_bf16 v[0:3], v[234:237], v[210:213], v[0:3]
	v_mfma_f32_16x16x32_bf16 v[28:31], v[230:233], v[186:189], v[28:31]
	s_add_i32 s39, 0, 0x18000
	v_mfma_f32_16x16x32_bf16 v[24:27], v[238:241], v[186:189], v[24:27]
	v_mfma_f32_16x16x32_bf16 v[20:23], v[230:233], v[194:197], v[20:23]
	v_mfma_f32_16x16x32_bf16 v[16:19], v[238:241], v[194:197], v[16:19]
	v_mfma_f32_16x16x32_bf16 v[12:15], v[230:233], v[206:209], v[12:15]
	v_mfma_f32_16x16x32_bf16 v[8:11], v[238:241], v[206:209], v[8:11]
	v_mfma_f32_16x16x32_bf16 v[4:7], v[230:233], v[214:217], v[4:7]
	s_setprio 0
	v_mfma_f32_16x16x32_bf16 v[0:3], v[238:241], v[214:217], v[0:3]
	s_barrier
	s_add_u32 s16, s22, 0x160000
	s_addc_u32 s17, s23, 0
	s_mov_b32 m0, s30
	s_nop 0
	global_load_lds_dwordx4 v142, s[16:17]
	s_mov_b32 m0, s31
	s_nop 0
	global_load_lds_dwordx4 v140, s[16:17]
	ds_read_b128 v[96:99], v199 offset:32768
	ds_read_b128 v[100:103], v199 offset:33792
	ds_read_b128 v[136:139], v199 offset:34816
	ds_read_b128 v[148:151], v199 offset:35840
	ds_read_b128 v[152:155], v201 offset:32768
	ds_read_b128 v[186:189], v201 offset:33792
	ds_read_b128 v[190:193], v201 offset:34816
	ds_read_b128 v[194:197], v201 offset:35840
	ds_read_b128 v[202:205], v201 offset:36864
	ds_read_b128 v[206:209], v201 offset:37888
	ds_read_b128 v[210:213], v201 offset:38912
	ds_read_b128 v[214:217], v201 offset:39936
	s_waitcnt lgkmcnt(8)
	s_setprio 1
	s_barrier
	s_waitcnt lgkmcnt(0)
	v_mfma_f32_16x16x32_bf16 v[132:135], v[96:99], v[152:155], v[132:135]
	v_mfma_f32_16x16x32_bf16 v[128:131], v[136:139], v[152:155], v[128:131]
	v_mfma_f32_16x16x32_bf16 v[124:127], v[96:99], v[190:193], v[124:127]
	v_mfma_f32_16x16x32_bf16 v[120:123], v[136:139], v[190:193], v[120:123]
	v_mfma_f32_16x16x32_bf16 v[116:119], v[96:99], v[202:205], v[116:119]
	v_mfma_f32_16x16x32_bf16 v[112:115], v[136:139], v[202:205], v[112:115]
	v_mfma_f32_16x16x32_bf16 v[108:111], v[96:99], v[210:213], v[108:111]
	v_mfma_f32_16x16x32_bf16 v[104:107], v[136:139], v[210:213], v[104:107]
	v_mfma_f32_16x16x32_bf16 v[132:135], v[100:103], v[186:189], v[132:135]
	v_mfma_f32_16x16x32_bf16 v[128:131], v[148:151], v[186:189], v[128:131]
	v_mfma_f32_16x16x32_bf16 v[124:127], v[100:103], v[194:197], v[124:127]
	v_mfma_f32_16x16x32_bf16 v[120:123], v[148:151], v[194:197], v[120:123]
	v_mfma_f32_16x16x32_bf16 v[116:119], v[100:103], v[206:209], v[116:119]
	v_mfma_f32_16x16x32_bf16 v[112:115], v[148:151], v[206:209], v[112:115]
	v_mfma_f32_16x16x32_bf16 v[108:111], v[100:103], v[214:217], v[108:111]
	s_setprio 0
	v_mfma_f32_16x16x32_bf16 v[104:107], v[148:151], v[214:217], v[104:107]
	s_barrier
	s_add_i32 s22, 0, 0x1c000
	s_add_i32 s16, s39, s27
	s_add_i32 m0, s16, 0xffffff80
	s_nop 0
	global_load_lds_dwordx4 v142, s[20:21] offset:128
	s_add_i32 m0, s16, 0x1f80
	s_nop 0
	global_load_lds_dwordx4 v140, s[20:21] offset:128
	ds_read_b128 v[226:229], v199 offset:49152
	ds_read_b128 v[230:233], v199 offset:50176
	ds_read_b128 v[234:237], v199 offset:51200
	ds_read_b128 v[238:241], v199 offset:52224
	s_waitcnt lgkmcnt(0)
	s_setprio 1
	s_barrier
	v_mfma_f32_16x16x32_bf16 v[60:63], v[226:229], v[152:155], v[60:63]
	v_mfma_f32_16x16x32_bf16 v[56:59], v[234:237], v[152:155], v[56:59]
	v_mfma_f32_16x16x32_bf16 v[52:55], v[226:229], v[190:193], v[52:55]
	v_mfma_f32_16x16x32_bf16 v[48:51], v[234:237], v[190:193], v[48:51]
	v_mfma_f32_16x16x32_bf16 v[44:47], v[226:229], v[202:205], v[44:47]
	v_mfma_f32_16x16x32_bf16 v[40:43], v[234:237], v[202:205], v[40:43]
	v_mfma_f32_16x16x32_bf16 v[36:39], v[226:229], v[210:213], v[36:39]
	v_mfma_f32_16x16x32_bf16 v[32:35], v[234:237], v[210:213], v[32:35]
	v_mfma_f32_16x16x32_bf16 v[60:63], v[230:233], v[186:189], v[60:63]
	s_add_i32 m0, s34, 0xffffff80
	v_mfma_f32_16x16x32_bf16 v[56:59], v[238:241], v[186:189], v[56:59]
	v_mfma_f32_16x16x32_bf16 v[52:55], v[230:233], v[194:197], v[52:55]
	v_mfma_f32_16x16x32_bf16 v[48:51], v[238:241], v[194:197], v[48:51]
	v_mfma_f32_16x16x32_bf16 v[44:47], v[230:233], v[206:209], v[44:47]
	v_mfma_f32_16x16x32_bf16 v[40:43], v[238:241], v[206:209], v[40:43]
	v_mfma_f32_16x16x32_bf16 v[36:39], v[230:233], v[214:217], v[36:39]
	s_setprio 0
	v_mfma_f32_16x16x32_bf16 v[32:35], v[238:241], v[214:217], v[32:35]
	s_barrier
	global_load_lds_dwordx4 v142, s[100:101] offset:128
	s_add_i32 m0, s35, 0xffffff80
	s_nop 0
	global_load_lds_dwordx4 v140, s[100:101] offset:128
	ds_read_b128 v[152:155], v201 offset:49152
	ds_read_b128 v[186:189], v201 offset:50176
	ds_read_b128 v[190:193], v201 offset:51200
	ds_read_b128 v[194:197], v201 offset:52224
	ds_read_b128 v[202:205], v201 offset:53248
	ds_read_b128 v[206:209], v201 offset:54272
	ds_read_b128 v[210:213], v201 offset:55296
	ds_read_b128 v[214:217], v201 offset:56320
	s_waitcnt lgkmcnt(0)
	s_setprio 1
	s_barrier
; #define PG8_WAIT_V(n) asm volatile("s_waitcnt vmcnt(" #n ")" ::: "memory")
; #define PG8_WAIT_L(n) asm volatile("s_waitcnt lgkmcnt(" #n ")" ::: "memory")
; #define PG8_BAR __builtin_amdgcn_s_barrier()
; template <class Epi>
; DI void gemm_phase(LAS unsigned char* lds, const Gemm g, const StaticOrder& S, const Epi& E) {
;     ...
;             PG8_BAR; PG8_WAIT_L(0); PG8_MMA(1, 0, At, B0); PG8_BAR; PG8_SCHED;
;             PG8_STAGE(PG8_SB(1, 1), b3 + hstep);
;             PG8_WAIT_V(6); PG8_BAR; PG8_MMA(1, 1, At, B1); PG8_BAR;
;         }
;     template <bool LN, int BJ, int LO, int HI> DI void batch(const f32x4 (&acc)[2][2][4][2], unsigned row0, unsigned col0, const f32x4 (&gv)[2], const f32x4 (&bv)[2]) const {
;         f32x4 r[HI - LO]; float mean[(HI - LO) / 2], rstd[(HI - LO) / 2];
; #pragma unroll
;         for (int i = LO; i < HI; ++i) { const int ai = i >> 3, m = (i >> 1) & 3, n = i & 1; const unsigned row = row0 + ai * HALF + m * 16;
;             if (n == 0) { mean[(i - LO) >> 1] = 0.f; rstd[(i - LO) >> 1] = 1.f;
;                 if (LN) { const float2 st = *(const float2*)(stats + row * 2u); mean[(i - LO) >> 1] = st.x; rstd[(i - LO) >> 1] = st.y; } }
;             r[i - LO] = *(const f32x4*)(src + (row * (unsigned)DM + col0 + BJ * HALF + n * 16)); }
; #pragma unroll
;         for (int i = LO; i < HI; ++i) { const int ai = i >> 3, m = (i >> 1) & 3, n = i & 1; const unsigned row = row0 + ai * HALF + m * 16;
;             *(f32x4*)(Y + (row * (unsigned)DM + col0 + BJ * HALF + n * 16)) = acc[ai][BJ][m][n] + ((r[i - LO] - mean[(i - LO) >> 1]) * rstd[(i - LO) >> 1]) * gv[n] + bv[n]; }
;         __builtin_amdgcn_sched_barrier(0);
;     }
;     template <bool LN, int BJ> DI void load_gb(unsigned col0, f32x4 (&gv)[2], f32x4 (&bv)[2]) const {
; #pragma unroll
;         for (int n = 0; n < 2; ++n) {
;             if (LN) { gv[n] = *(const f32x4*)(gam + col0 + BJ * HALF + n * 16) * ALPHA; bv[n] = *(const f32x4*)(bet + col0 + BJ * HALF + n * 16) * ALPHA; }
;             else { gv[n] = (f32x4){ALPHA, ALPHA, ALPHA, ALPHA}; bv[n] = (f32x4){0.f, 0.f, 0.f, 0.f}; }
;         }
;     }
;     template <bool LN> DI void run(const f32x4 (&acc)[2][2][4][2], const Unit& u, int wr, int wc, int fr, int fq) const {
;         const unsigned row0 = u.pm * BM + wr * 64 + fr, col0 = u.pn * BM + wc * 32 + 4 * fq;
;         f32x4 gv[2], bv[2];
;         load_gb<LN, 0>(col0, gv, bv);
	v_mfma_f32_16x16x32_bf16 v[92:95], v[96:99], v[152:155], v[92:95]
	v_mfma_f32_16x16x32_bf16 v[88:91], v[136:139], v[152:155], v[88:91]
	v_mfma_f32_16x16x32_bf16 v[84:87], v[96:99], v[190:193], v[84:87]
	v_mfma_f32_16x16x32_bf16 v[80:83], v[136:139], v[190:193], v[80:83]
	v_mfma_f32_16x16x32_bf16 v[76:79], v[96:99], v[202:205], v[76:79]
	v_mfma_f32_16x16x32_bf16 v[72:75], v[136:139], v[202:205], v[72:75]
	v_mfma_f32_16x16x32_bf16 v[68:71], v[96:99], v[210:213], v[68:71]
	v_mfma_f32_16x16x32_bf16 v[64:67], v[136:139], v[210:213], v[64:67]
	v_mfma_f32_16x16x32_bf16 v[92:95], v[100:103], v[186:189], v[92:95]
	v_mfma_f32_16x16x32_bf16 v[88:91], v[148:151], v[186:189], v[88:91]
	v_mfma_f32_16x16x32_bf16 v[84:87], v[100:103], v[194:197], v[84:87]
	v_mfma_f32_16x16x32_bf16 v[80:83], v[148:151], v[194:197], v[80:83]
	v_mfma_f32_16x16x32_bf16 v[76:79], v[100:103], v[206:209], v[76:79]
	v_mfma_f32_16x16x32_bf16 v[72:75], v[148:151], v[206:209], v[72:75]
	v_mfma_f32_16x16x32_bf16 v[68:71], v[100:103], v[214:217], v[68:71]
	s_setprio 0
	v_mfma_f32_16x16x32_bf16 v[64:67], v[148:151], v[214:217], v[64:67]
	s_barrier
	s_add_u32 s16, s20, 0x160080
	s_addc_u32 s17, s21, 0
	s_add_i32 s20, s22, s27
	s_mov_b32 m0, s20
	s_nop 0
	global_load_lds_dwordx4 v142, s[16:17]
	s_add_i32 m0, s20, 0x2000
	s_nop 0
	global_load_lds_dwordx4 v140, s[16:17]
	s_waitcnt vmcnt(6)
	s_setprio 1
	s_barrier
	v_mfma_f32_16x16x32_bf16 v[28:31], v[226:229], v[152:155], v[28:31]
	v_mfma_f32_16x16x32_bf16 v[24:27], v[234:237], v[152:155], v[24:27]
	v_mfma_f32_16x16x32_bf16 v[20:23], v[226:229], v[190:193], v[20:23]
	v_mfma_f32_16x16x32_bf16 v[16:19], v[234:237], v[190:193], v[16:19]
	v_mfma_f32_16x16x32_bf16 v[12:15], v[226:229], v[202:205], v[12:15]
	v_mfma_f32_16x16x32_bf16 v[8:11], v[234:237], v[202:205], v[8:11]
	v_mfma_f32_16x16x32_bf16 v[4:7], v[226:229], v[210:213], v[4:7]
	v_mfma_f32_16x16x32_bf16 v[0:3], v[234:237], v[210:213], v[0:3]
	v_mfma_f32_16x16x32_bf16 v[28:31], v[230:233], v[186:189], v[28:31]
	s_add_i32 s33, s33, 2
	v_mfma_f32_16x16x32_bf16 v[24:27], v[238:241], v[186:189], v[24:27]
	s_add_u32 s4, s4, 0x100
	v_mfma_f32_16x16x32_bf16 v[20:23], v[230:233], v[194:197], v[20:23]
	s_addc_u32 s5, s5, 0
	v_mfma_f32_16x16x32_bf16 v[16:19], v[238:241], v[194:197], v[16:19]
	s_cmpk_gt_u32 s33, 0x55
	v_mfma_f32_16x16x32_bf16 v[12:15], v[230:233], v[206:209], v[12:15]
	s_mov_b64 s[16:17], s[18:19]
	v_mfma_f32_16x16x32_bf16 v[8:11], v[238:241], v[206:209], v[8:11]
	v_mfma_f32_16x16x32_bf16 v[4:7], v[230:233], v[214:217], v[4:7]
	s_setprio 0
	v_mfma_f32_16x16x32_bf16 v[0:3], v[238:241], v[214:217], v[0:3]
	s_barrier
	s_cbranch_scc0 .LBB0_134
	v_lshl_or_b32 v158, s2, 8, v200
	v_lshlrev_b64 v[100:101], 2, v[158:159]
	v_lshl_add_u64 v[150:151], s[12:13], 0, v[100:101]
	global_load_dwordx4 v[96:99], v[150:151], off
	v_lshl_add_u64 v[152:153], s[14:15], 0, v[100:101]
	v_lshl_add_u32 v203, s3, 8, v198
	v_lshlrev_b32_e32 v202, 11, v203
	v_add_u32_e32 v148, v202, v158
	v_mov_b32_e32 v149, v159
	v_lshlrev_b32_e32 v136, 1, v203
	v_mov_b32_e32 v137, v159
	v_lshlrev_b64 v[220:221], 2, v[148:149]
	v_lshl_add_u64 v[154:155], v[136:137], 2, s[96:97]
	v_lshl_add_u64 v[136:137], s[90:91], 0, v[220:221]
	v_or_b32_e32 v204, 16, v158
	v_or_b32_e32 v138, 16, v203
	v_lshlrev_b32_e32 v149, 11, v138
	s_waitcnt vmcnt(0)
	v_pk_mul_f32 v[192:193], v[98:99], s[78:79] op_sel_hi:[1,0]
	v_pk_mul_f32 v[194:195], v[96:97], s[78:79] op_sel_hi:[1,0]
	global_load_dwordx4 v[100:103], v[152:153], off
	global_load_dwordx4 v[96:99], v[150:151], off offset:64
	global_load_dwordx2 v[218:219], v[154:155], off
	global_load_dwordx4 v[206:209], v[136:137], off
	v_add_u32_e32 v136, v202, v204
	v_mov_b32_e32 v137, v159
	v_lshl_add_u64 v[136:137], v[136:137], 2, s[90:91]
	global_load_dwordx4 v[210:213], v[136:137], off
	v_lshlrev_b32_e32 v136, 1, v138
	v_mov_b32_e32 v137, v159
	v_lshl_add_u64 v[186:187], v[136:137], 2, s[96:97]
	v_add_u32_e32 v136, v149, v158
	v_lshl_add_u64 v[136:137], v[136:137], 2, s[90:91]
	global_load_dwordx2 v[196:197], v[186:187], off
	global_load_dwordx4 v[214:217], v[136:137], off
	v_add_u32_e32 v136, v149, v204
	v_mov_b32_e32 v137, v159
	v_lshl_add_u64 v[136:137], v[136:137], 2, s[90:91]
	global_load_dwordx4 v[136:139], v[136:137], off
	s_waitcnt vmcnt(0)
	v_pk_mul_f32 v[188:189], v[98:99], s[78:79] op_sel_hi:[1,0]
	v_pk_mul_f32 v[190:191], v[96:97], s[78:79] op_sel_hi:[1,0]
	global_load_dwordx4 v[96:99], v[152:153], off offset:64
	v_sub_f32_e32 v207, v207, v218
	v_sub_f32_e32 v206, v206, v218
	v_sub_f32_e32 v209, v209, v218
	v_sub_f32_e32 v208, v208, v218
	v_pk_mul_f32 v[208:209], v[218:219], v[208:209] op_sel:[1,0]
	v_pk_mul_f32 v[206:207], v[218:219], v[206:207] op_sel:[1,0]
	v_pk_fma_f32 v[134:135], v[192:193], v[208:209], v[134:135]
	v_pk_fma_f32 v[132:133], v[194:195], v[206:207], v[132:133]
	v_pk_fma_f32 v[134:135], v[102:103], s[78:79], v[134:135] op_sel_hi:[1,0,1]
	v_pk_fma_f32 v[132:133], v[100:101], s[78:79], v[132:133] op_sel_hi:[1,0,1]
	v_lshl_add_u64 v[206:207], s[88:89], 0, v[220:221]
	global_store_dwordx4 v[206:207], v[132:135], off
	s_nop 1
	v_sub_f32_e32 v133, v211, v218
	v_sub_f32_e32 v132, v210, v218
	v_sub_f32_e32 v135, v213, v218
	v_sub_f32_e32 v134, v212, v218
	v_pk_mul_f32 v[134:135], v[218:219], v[134:135] op_sel:[1,0]
	v_pk_mul_f32 v[132:133], v[218:219], v[132:133] op_sel:[1,0]
	v_pk_fma_f32 v[130:131], v[188:189], v[134:135], v[130:131]
	v_pk_fma_f32 v[128:129], v[190:191], v[132:133], v[128:129]
	v_or_b32_e32 v132, 16, v148
	v_mov_b32_e32 v133, v159
	v_lshl_add_u64 v[132:133], v[132:133], 2, s[88:89]
	s_waitcnt vmcnt(0)
;     template <bool LN, int BJ, int LO, int HI> DI void batch(const f32x4 (&acc)[2][2][4][2], unsigned row0, unsigned col0, const f32x4 (&gv)[2], const f32x4 (&bv)[2]) const {
;         f32x4 r[HI - LO]; float mean[(HI - LO) / 2], rstd[(HI - LO) / 2];
; #pragma unroll
;         for (int i = LO; i < HI; ++i) { const int ai = i >> 3, m = (i >> 1) & 3, n = i & 1; const unsigned row = row0 + ai * HALF + m * 16;
;             if (n == 0) { mean[(i - LO) >> 1] = 0.f; rstd[(i - LO) >> 1] = 1.f;
;                 if (LN) { const float2 st = *(const float2*)(stats + row * 2u); mean[(i - LO) >> 1] = st.x; rstd[(i - LO) >> 1] = st.y; } }
;             r[i - LO] = *(const f32x4*)(src + (row * (unsigned)DM + col0 + BJ * HALF + n * 16)); }
; #pragma unroll
;         for (int i = LO; i < HI; ++i) { const int ai = i >> 3, m = (i >> 1) & 3, n = i & 1; const unsigned row = row0 + ai * HALF + m * 16;
;             *(f32x4*)(Y + (row * (unsigned)DM + col0 + BJ * HALF + n * 16)) = acc[ai][BJ][m][n] + ((r[i - LO] - mean[(i - LO) >> 1]) * rstd[(i - LO) >> 1]) * gv[n] + bv[n]; }
	v_pk_fma_f32 v[130:131], v[98:99], s[78:79], v[130:131] op_sel_hi:[1,0,1]
	v_pk_fma_f32 v[128:129], v[96:97], s[78:79], v[128:129] op_sel_hi:[1,0,1]
	global_store_dwordx4 v[132:133], v[128:131], off
	s_nop 1
	v_sub_f32_e32 v129, v215, v196
	v_sub_f32_e32 v128, v214, v196
	v_sub_f32_e32 v131, v217, v196
	v_sub_f32_e32 v130, v216, v196
	v_pk_mul_f32 v[130:131], v[196:197], v[130:131] op_sel:[1,0]
	v_pk_mul_f32 v[128:129], v[196:197], v[128:129] op_sel:[1,0]
	v_pk_fma_f32 v[126:127], v[192:193], v[130:131], v[126:127]
	v_pk_fma_f32 v[124:125], v[194:195], v[128:129], v[124:125]
	v_add_u32_e32 v128, 0x8000, v148
	v_mov_b32_e32 v129, v159
	v_pk_fma_f32 v[126:127], v[102:103], s[78:79], v[126:127] op_sel_hi:[1,0,1]
	v_pk_fma_f32 v[124:125], v[100:101], s[78:79], v[124:125] op_sel_hi:[1,0,1]
	v_lshl_add_u64 v[128:129], v[128:129], 2, s[88:89]
	global_store_dwordx4 v[128:129], v[124:127], off
	s_nop 1
	v_sub_f32_e32 v125, v137, v196
	v_sub_f32_e32 v124, v136, v196
	v_sub_f32_e32 v127, v139, v196
	v_sub_f32_e32 v126, v138, v196
	v_pk_mul_f32 v[126:127], v[196:197], v[126:127] op_sel:[1,0]
	v_pk_mul_f32 v[124:125], v[196:197], v[124:125] op_sel:[1,0]
	v_pk_fma_f32 v[122:123], v[188:189], v[126:127], v[122:123]
	v_pk_fma_f32 v[120:121], v[190:191], v[124:125], v[120:121]
	v_add_u32_e32 v124, 0x8010, v148
	v_mov_b32_e32 v125, v159
	v_pk_fma_f32 v[122:123], v[98:99], s[78:79], v[122:123] op_sel_hi:[1,0,1]
	v_pk_fma_f32 v[120:121], v[96:97], s[78:79], v[120:121] op_sel_hi:[1,0,1]
	v_lshl_add_u64 v[124:125], v[124:125], 2, s[88:89]
	global_store_dwordx4 v[124:125], v[120:123], off
	s_nop 1
	v_or_b32_e32 v122, 32, v203
	v_lshlrev_b32_e32 v124, 11, v122
	v_lshlrev_b32_e32 v120, 1, v122
	v_mov_b32_e32 v121, v159
	v_add_u32_e32 v122, v124, v158
	v_mov_b32_e32 v123, v159
	v_lshl_add_u64 v[120:121], v[120:121], 2, s[96:97]
	v_lshl_add_u64 v[122:123], v[122:123], 2, s[90:91]
	global_load_dwordx2 v[138:139], v[120:121], off
	global_load_dwordx4 v[126:129], v[122:123], off
	v_add_u32_e32 v122, v124, v204
	v_mov_b32_e32 v123, v159
	v_lshl_add_u64 v[122:123], v[122:123], 2, s[90:91]
	global_load_dwordx4 v[130:133], v[122:123], off
	v_or_b32_e32 v125, 48, v203
	v_lshlrev_b32_e32 v122, 1, v125
	v_lshlrev_b32_e32 v125, 11, v125
	v_mov_b32_e32 v123, v159
	v_add_u32_e32 v134, v125, v158
	v_mov_b32_e32 v135, v159
	v_lshl_add_u64 v[122:123], v[122:123], 2, s[96:97]
	v_lshl_add_u64 v[134:135], v[134:135], 2, s[90:91]
	global_load_dwordx2 v[196:197], v[122:123], off
	v_add_u32_e32 v206, v125, v204
	global_load_dwordx4 v[134:137], v[134:135], off
	v_mov_b32_e32 v207, v159
	v_lshl_add_u64 v[206:207], v[206:207], 2, s[90:91]
	global_load_dwordx4 v[206:209], v[206:207], off
	s_waitcnt vmcnt(0)
	v_sub_f32_e32 v127, v127, v138
	v_sub_f32_e32 v126, v126, v138
	v_sub_f32_e32 v129, v129, v138
	v_sub_f32_e32 v128, v128, v138
	v_pk_mul_f32 v[128:129], v[138:139], v[128:129] op_sel:[1,0]
	v_pk_mul_f32 v[126:127], v[138:139], v[126:127] op_sel:[1,0]
	v_pk_fma_f32 v[118:119], v[192:193], v[128:129], v[118:119]
	v_pk_fma_f32 v[116:117], v[194:195], v[126:127], v[116:117]
	v_add_u32_e32 v126, 0x10000, v148
	v_mov_b32_e32 v127, v159
	v_pk_fma_f32 v[118:119], v[102:103], s[78:79], v[118:119] op_sel_hi:[1,0,1]
	v_pk_fma_f32 v[116:117], v[100:101], s[78:79], v[116:117] op_sel_hi:[1,0,1]
	v_lshl_add_u64 v[126:127], v[126:127], 2, s[88:89]
	global_store_dwordx4 v[126:127], v[116:119], off
	s_nop 1
	v_sub_f32_e32 v117, v131, v138
	v_sub_f32_e32 v116, v130, v138
	v_sub_f32_e32 v119, v133, v138
	v_sub_f32_e32 v118, v132, v138
	v_pk_mul_f32 v[118:119], v[138:139], v[118:119] op_sel:[1,0]
	v_pk_mul_f32 v[116:117], v[138:139], v[116:117] op_sel:[1,0]
	v_pk_fma_f32 v[114:115], v[188:189], v[118:119], v[114:115]
	v_pk_fma_f32 v[112:113], v[190:191], v[116:117], v[112:113]
	v_add_u32_e32 v116, 0x10010, v148
	v_mov_b32_e32 v117, v159
	v_pk_fma_f32 v[114:115], v[98:99], s[78:79], v[114:115] op_sel_hi:[1,0,1]
	v_pk_fma_f32 v[112:113], v[96:97], s[78:79], v[112:113] op_sel_hi:[1,0,1]
	v_lshl_add_u64 v[116:117], v[116:117], 2, s[88:89]
	global_store_dwordx4 v[116:117], v[112:115], off
	s_nop 1
	v_sub_f32_e32 v113, v135, v196
	v_sub_f32_e32 v112, v134, v196
	v_sub_f32_e32 v115, v137, v196
	v_sub_f32_e32 v114, v136, v196
	v_pk_mul_f32 v[114:115], v[196:197], v[114:115] op_sel:[1,0]
	v_pk_mul_f32 v[112:113], v[196:197], v[112:113] op_sel:[1,0]
	v_pk_fma_f32 v[110:111], v[192:193], v[114:115], v[110:111]
	v_pk_fma_f32 v[108:109], v[194:195], v[112:113], v[108:109]
	v_add_u32_e32 v112, 0x18000, v148
	v_mov_b32_e32 v113, v159
	v_pk_fma_f32 v[110:111], v[102:103], s[78:79], v[110:111] op_sel_hi:[1,0,1]
	v_pk_fma_f32 v[108:109], v[100:101], s[78:79], v[108:109] op_sel_hi:[1,0,1]
	v_lshl_add_u64 v[112:113], v[112:113], 2, s[88:89]
	global_store_dwordx4 v[112:113], v[108:111], off
	s_nop 1
	v_sub_f32_e32 v109, v207, v196
	v_sub_f32_e32 v108, v206, v196
	v_sub_f32_e32 v111, v209, v196
	v_sub_f32_e32 v110, v208, v196
	v_pk_mul_f32 v[110:111], v[196:197], v[110:111] op_sel:[1,0]
	v_pk_mul_f32 v[108:109], v[196:197], v[108:109] op_sel:[1,0]
	v_pk_fma_f32 v[106:107], v[188:189], v[110:111], v[106:107]
	v_pk_fma_f32 v[104:105], v[190:191], v[108:109], v[104:105]
	v_add_u32_e32 v108, 0x18010, v148
	v_mov_b32_e32 v109, v159
	v_pk_fma_f32 v[106:107], v[98:99], s[78:79], v[106:107] op_sel_hi:[1,0,1]
	v_pk_fma_f32 v[104:105], v[96:97], s[78:79], v[104:105] op_sel_hi:[1,0,1]
	v_lshl_add_u64 v[108:109], v[108:109], 2, s[88:89]
	global_store_dwordx4 v[108:109], v[104:107], off
	s_nop 1
	v_add_u32_e32 v106, 0x80, v203
	v_lshlrev_b32_e32 v114, 11, v106
	v_lshlrev_b32_e32 v104, 1, v106
	v_mov_b32_e32 v105, v159
	v_add_u32_e32 v106, v114, v158
	v_mov_b32_e32 v107, v159
	v_lshl_add_u64 v[104:105], v[104:105], 2, s[96:97]
	v_lshl_add_u64 v[106:107], v[106:107], 2, s[90:91]
	global_load_dwordx2 v[112:113], v[104:105], off
	global_load_dwordx4 v[108:111], v[106:107], off
	v_add_u32_e32 v106, v114, v204
	v_mov_b32_e32 v107, v159
	v_lshl_add_u64 v[106:107], v[106:107], 2, s[90:91]
	global_load_dwordx4 v[116:119], v[106:107], off
	v_add_u32_e32 v115, 0x90, v203
	v_lshlrev_b32_e32 v106, 1, v115
	v_lshlrev_b32_e32 v115, 11, v115
	v_mov_b32_e32 v107, v159
	v_add_u32_e32 v126, v115, v158
	v_mov_b32_e32 v127, v159
	v_lshl_add_u64 v[106:107], v[106:107], 2, s[96:97]
	v_lshl_add_u64 v[126:127], v[126:127], 2, s[90:91]
	global_load_dwordx2 v[134:135], v[106:107], off
	v_add_u32_e32 v130, v115, v204
	global_load_dwordx4 v[126:129], v[126:127], off
	v_mov_b32_e32 v131, v159
	v_lshl_add_u64 v[130:131], v[130:131], 2, s[90:91]
	global_load_dwordx4 v[130:133], v[130:131], off
	s_waitcnt vmcnt(0)
;     template <bool LN, int BJ, int LO, int HI> DI void batch(const f32x4 (&acc)[2][2][4][2], unsigned row0, unsigned col0, const f32x4 (&gv)[2], const f32x4 (&bv)[2]) const {
;         f32x4 r[HI - LO]; float mean[(HI - LO) / 2], rstd[(HI - LO) / 2];
; #pragma unroll
;         for (int i = LO; i < HI; ++i) { const int ai = i >> 3, m = (i >> 1) & 3, n = i & 1; const unsigned row = row0 + ai * HALF + m * 16;
;             if (n == 0) { mean[(i - LO) >> 1] = 0.f; rstd[(i - LO) >> 1] = 1.f;
;                 if (LN) { const float2 st = *(const float2*)(stats + row * 2u); mean[(i - LO) >> 1] = st.x; rstd[(i - LO) >> 1] = st.y; } }
;             r[i - LO] = *(const f32x4*)(src + (row * (unsigned)DM + col0 + BJ * HALF + n * 16)); }
; #pragma unroll
;         for (int i = LO; i < HI; ++i) { const int ai = i >> 3, m = (i >> 1) & 3, n = i & 1; const unsigned row = row0 + ai * HALF + m * 16;
;             *(f32x4*)(Y + (row * (unsigned)DM + col0 + BJ * HALF + n * 16)) = acc[ai][BJ][m][n] + ((r[i - LO] - mean[(i - LO) >> 1]) * rstd[(i - LO) >> 1]) * gv[n] + bv[n]; }
	v_sub_f32_e32 v109, v109, v112
	v_sub_f32_e32 v108, v108, v112
	v_sub_f32_e32 v111, v111, v112
	v_sub_f32_e32 v110, v110, v112
	v_pk_mul_f32 v[110:111], v[112:113], v[110:111] op_sel:[1,0]
	v_pk_mul_f32 v[108:109], v[112:113], v[108:109] op_sel:[1,0]
	v_pk_fma_f32 v[94:95], v[192:193], v[110:111], v[94:95]
	v_pk_fma_f32 v[92:93], v[194:195], v[108:109], v[92:93]
	v_add_u32_e32 v108, 0x40000, v148
	v_mov_b32_e32 v109, v159
	v_pk_fma_f32 v[94:95], v[102:103], s[78:79], v[94:95] op_sel_hi:[1,0,1]
	v_pk_fma_f32 v[92:93], v[100:101], s[78:79], v[92:93] op_sel_hi:[1,0,1]
	v_lshl_add_u64 v[108:109], v[108:109], 2, s[88:89]
	global_store_dwordx4 v[108:109], v[92:95], off
	s_nop 1
	v_sub_f32_e32 v93, v117, v112
	v_sub_f32_e32 v92, v116, v112
	v_sub_f32_e32 v95, v119, v112
	v_sub_f32_e32 v94, v118, v112
	v_pk_mul_f32 v[94:95], v[112:113], v[94:95] op_sel:[1,0]
	v_pk_mul_f32 v[92:93], v[112:113], v[92:93] op_sel:[1,0]
	v_pk_fma_f32 v[90:91], v[188:189], v[94:95], v[90:91]
	v_pk_fma_f32 v[88:89], v[190:191], v[92:93], v[88:89]
	v_add_u32_e32 v92, 0x40010, v148
	v_mov_b32_e32 v93, v159
	v_pk_fma_f32 v[90:91], v[98:99], s[78:79], v[90:91] op_sel_hi:[1,0,1]
	v_pk_fma_f32 v[88:89], v[96:97], s[78:79], v[88:89] op_sel_hi:[1,0,1]
	v_lshl_add_u64 v[92:93], v[92:93], 2, s[88:89]
	global_store_dwordx4 v[92:93], v[88:91], off
	s_nop 1
	v_sub_f32_e32 v89, v127, v134
	v_sub_f32_e32 v88, v126, v134
	v_sub_f32_e32 v91, v129, v134
	v_sub_f32_e32 v90, v128, v134
	v_pk_mul_f32 v[90:91], v[134:135], v[90:91] op_sel:[1,0]
	v_pk_mul_f32 v[88:89], v[134:135], v[88:89] op_sel:[1,0]
	v_pk_fma_f32 v[86:87], v[192:193], v[90:91], v[86:87]
	v_pk_fma_f32 v[84:85], v[194:195], v[88:89], v[84:85]
	v_add_u32_e32 v88, 0x48000, v148
	v_mov_b32_e32 v89, v159
	v_pk_fma_f32 v[86:87], v[102:103], s[78:79], v[86:87] op_sel_hi:[1,0,1]
	v_pk_fma_f32 v[84:85], v[100:101], s[78:79], v[84:85] op_sel_hi:[1,0,1]
	v_lshl_add_u64 v[88:89], v[88:89], 2, s[88:89]
	global_store_dwordx4 v[88:89], v[84:87], off
	s_nop 1
	v_sub_f32_e32 v85, v131, v134
	v_sub_f32_e32 v84, v130, v134
	v_sub_f32_e32 v87, v133, v134
	v_sub_f32_e32 v86, v132, v134
	v_pk_mul_f32 v[86:87], v[134:135], v[86:87] op_sel:[1,0]
	v_pk_mul_f32 v[84:85], v[134:135], v[84:85] op_sel:[1,0]
	v_pk_fma_f32 v[82:83], v[188:189], v[86:87], v[82:83]
	v_pk_fma_f32 v[80:81], v[190:191], v[84:85], v[80:81]
	v_add_u32_e32 v84, 0x48010, v148
	v_mov_b32_e32 v85, v159
	v_pk_fma_f32 v[82:83], v[98:99], s[78:79], v[82:83] op_sel_hi:[1,0,1]
	v_pk_fma_f32 v[80:81], v[96:97], s[78:79], v[80:81] op_sel_hi:[1,0,1]
	v_lshl_add_u64 v[84:85], v[84:85], 2, s[88:89]
	global_store_dwordx4 v[84:85], v[80:83], off
	s_nop 1
	v_add_u32_e32 v82, 0xa0, v203
	v_lshlrev_b32_e32 v80, 1, v82
	v_mov_b32_e32 v81, v159
	v_lshlrev_b32_e32 v116, 11, v82
	v_lshl_add_u64 v[108:109], v[80:81], 2, s[96:97]
	v_add_u32_e32 v80, v116, v158
	v_lshl_add_u64 v[80:81], v[80:81], 2, s[90:91]
	global_load_dwordx2 v[112:113], v[108:109], off
	v_add_u32_e32 v84, v116, v204
	global_load_dwordx4 v[80:83], v[80:81], off
	v_mov_b32_e32 v85, v159
	v_lshl_add_u64 v[84:85], v[84:85], 2, s[90:91]
	global_load_dwordx4 v[84:87], v[84:85], off
	v_add_u32_e32 v90, 0xb0, v203
	v_lshlrev_b32_e32 v88, 1, v90
	v_mov_b32_e32 v89, v159
	v_lshlrev_b32_e32 v117, 11, v90
	v_lshl_add_u64 v[110:111], v[88:89], 2, s[96:97]
	v_add_u32_e32 v88, v117, v158
	v_lshl_add_u64 v[88:89], v[88:89], 2, s[90:91]
	global_load_dwordx2 v[118:119], v[110:111], off
	v_add_u32_e32 v92, v117, v204
	global_load_dwordx4 v[88:91], v[88:89], off
	v_mov_b32_e32 v93, v159
	v_lshl_add_u64 v[92:93], v[92:93], 2, s[90:91]
	global_load_dwordx4 v[92:95], v[92:93], off
	s_waitcnt vmcnt(0)
	v_sub_f32_e32 v81, v81, v112
	v_sub_f32_e32 v80, v80, v112
	v_sub_f32_e32 v83, v83, v112
	v_sub_f32_e32 v82, v82, v112
	v_pk_mul_f32 v[82:83], v[112:113], v[82:83] op_sel:[1,0]
	v_pk_mul_f32 v[80:81], v[112:113], v[80:81] op_sel:[1,0]
	v_pk_fma_f32 v[78:79], v[192:193], v[82:83], v[78:79]
	v_pk_fma_f32 v[76:77], v[194:195], v[80:81], v[76:77]
	v_add_u32_e32 v80, 0x50000, v148
	v_mov_b32_e32 v81, v159
	v_pk_fma_f32 v[78:79], v[102:103], s[78:79], v[78:79] op_sel_hi:[1,0,1]
	v_pk_fma_f32 v[76:77], v[100:101], s[78:79], v[76:77] op_sel_hi:[1,0,1]
	v_lshl_add_u64 v[80:81], v[80:81], 2, s[88:89]
	global_store_dwordx4 v[80:81], v[76:79], off
	s_nop 1
	v_sub_f32_e32 v77, v85, v112
	v_sub_f32_e32 v76, v84, v112
	v_sub_f32_e32 v79, v87, v112
	v_sub_f32_e32 v78, v86, v112
	v_pk_mul_f32 v[78:79], v[112:113], v[78:79] op_sel:[1,0]
	v_pk_mul_f32 v[76:77], v[112:113], v[76:77] op_sel:[1,0]
	v_pk_fma_f32 v[74:75], v[188:189], v[78:79], v[74:75]
	v_pk_fma_f32 v[72:73], v[190:191], v[76:77], v[72:73]
	v_add_u32_e32 v76, 0x50010, v148
	v_mov_b32_e32 v77, v159
	v_pk_fma_f32 v[74:75], v[98:99], s[78:79], v[74:75] op_sel_hi:[1,0,1]
	v_pk_fma_f32 v[72:73], v[96:97], s[78:79], v[72:73] op_sel_hi:[1,0,1]
	v_lshl_add_u64 v[76:77], v[76:77], 2, s[88:89]
	global_store_dwordx4 v[76:77], v[72:75], off
	s_nop 1
	v_sub_f32_e32 v73, v89, v118
	v_sub_f32_e32 v72, v88, v118
	v_sub_f32_e32 v75, v91, v118
	v_sub_f32_e32 v74, v90, v118
	v_pk_mul_f32 v[74:75], v[118:119], v[74:75] op_sel:[1,0]
	v_pk_mul_f32 v[72:73], v[118:119], v[72:73] op_sel:[1,0]
	v_pk_fma_f32 v[70:71], v[192:193], v[74:75], v[70:71]
	v_pk_fma_f32 v[68:69], v[194:195], v[72:73], v[68:69]
	v_add_u32_e32 v72, 0x58000, v148
	v_mov_b32_e32 v73, v159
	v_pk_fma_f32 v[70:71], v[102:103], s[78:79], v[70:71] op_sel_hi:[1,0,1]
	v_pk_fma_f32 v[68:69], v[100:101], s[78:79], v[68:69] op_sel_hi:[1,0,1]
	v_lshl_add_u64 v[72:73], v[72:73], 2, s[88:89]
	global_store_dwordx4 v[72:73], v[68:71], off
	s_nop 1
	v_sub_f32_e32 v69, v93, v118
	v_sub_f32_e32 v68, v92, v118
	v_sub_f32_e32 v71, v95, v118
	v_sub_f32_e32 v70, v94, v118
	v_pk_mul_f32 v[70:71], v[118:119], v[70:71] op_sel:[1,0]
	v_pk_mul_f32 v[68:69], v[118:119], v[68:69] op_sel:[1,0]
	v_pk_fma_f32 v[66:67], v[188:189], v[70:71], v[66:67]
	v_pk_fma_f32 v[64:65], v[190:191], v[68:69], v[64:65]
	v_add_u32_e32 v68, 0x58010, v148
	v_mov_b32_e32 v69, v159
	v_pk_fma_f32 v[66:67], v[98:99], s[78:79], v[66:67] op_sel_hi:[1,0,1]
	v_pk_fma_f32 v[64:65], v[96:97], s[78:79], v[64:65] op_sel_hi:[1,0,1]
	v_lshl_add_u64 v[68:69], v[68:69], 2, s[88:89]
	global_store_dwordx4 v[68:69], v[64:67], off
	global_load_dwordx4 v[64:67], v[150:151], off offset:512
	v_or_b32_e32 v119, 0x80, v158
	v_add_u32_e32 v72, v202, v119
	v_mov_b32_e32 v73, v159
	v_lshl_add_u64 v[72:73], v[72:73], 2, s[90:91]
	v_or_b32_e32 v118, 0x90, v158
	v_add_u32_e32 v158, v202, v118
	s_waitcnt vmcnt(0)
;     template <bool LN, int BJ, int LO, int HI> DI void batch(const f32x4 (&acc)[2][2][4][2], unsigned row0, unsigned col0, const f32x4 (&gv)[2], const f32x4 (&bv)[2]) const {
;         f32x4 r[HI - LO]; float mean[(HI - LO) / 2], rstd[(HI - LO) / 2];
; #pragma unroll
;         for (int i = LO; i < HI; ++i) { const int ai = i >> 3, m = (i >> 1) & 3, n = i & 1; const unsigned row = row0 + ai * HALF + m * 16;
;             if (n == 0) { mean[(i - LO) >> 1] = 0.f; rstd[(i - LO) >> 1] = 1.f;
;                 if (LN) { const float2 st = *(const float2*)(stats + row * 2u); mean[(i - LO) >> 1] = st.x; rstd[(i - LO) >> 1] = st.y; } }
;             r[i - LO] = *(const f32x4*)(src + (row * (unsigned)DM + col0 + BJ * HALF + n * 16)); }
; #pragma unroll
;         for (int i = LO; i < HI; ++i) { const int ai = i >> 3, m = (i >> 1) & 3, n = i & 1; const unsigned row = row0 + ai * HALF + m * 16;
;             *(f32x4*)(Y + (row * (unsigned)DM + col0 + BJ * HALF + n * 16)) = acc[ai][BJ][m][n] + ((r[i - LO] - mean[(i - LO) >> 1]) * rstd[(i - LO) >> 1]) * gv[n] + bv[n]; }
;         __builtin_amdgcn_sched_barrier(0);
;     }
;     template <bool LN, int BJ> DI void load_gb(unsigned col0, f32x4 (&gv)[2], f32x4 (&bv)[2]) const {
; #pragma unroll
;         for (int n = 0; n < 2; ++n) {
;             if (LN) { gv[n] = *(const f32x4*)(gam + col0 + BJ * HALF + n * 16) * ALPHA; bv[n] = *(const f32x4*)(bet + col0 + BJ * HALF + n * 16) * ALPHA; }
;             else { gv[n] = (f32x4){ALPHA, ALPHA, ALPHA, ALPHA}; bv[n] = (f32x4){0.f, 0.f, 0.f, 0.f}; }
;         }
;     }
	v_pk_mul_f32 v[96:97], v[66:67], s[78:79] op_sel_hi:[1,0]
	v_pk_mul_f32 v[98:99], v[64:65], s[78:79] op_sel_hi:[1,0]
	global_load_dwordx4 v[68:71], v[152:153], off offset:512
	global_load_dwordx4 v[64:67], v[150:151], off offset:576
	global_load_dwordx2 v[138:139], v[154:155], off
	global_load_dwordx4 v[126:129], v[72:73], off
	v_lshl_add_u64 v[72:73], v[158:159], 2, s[90:91]
	v_add_u32_e32 v158, v149, v119
	s_waitcnt vmcnt(0)
	v_pk_mul_f32 v[92:93], v[66:67], s[78:79] op_sel_hi:[1,0]
	v_pk_mul_f32 v[94:95], v[64:65], s[78:79] op_sel_hi:[1,0]
	global_load_dwordx4 v[64:67], v[152:153], off offset:576
	global_load_dwordx4 v[130:133], v[72:73], off
	global_load_dwordx2 v[112:113], v[186:187], off
	v_lshl_add_u64 v[72:73], v[158:159], 2, s[90:91]
	global_load_dwordx4 v[134:137], v[72:73], off
	v_add_u32_e32 v158, v149, v118
	v_lshl_add_u64 v[72:73], v[158:159], 2, s[90:91]
	global_load_dwordx4 v[88:91], v[72:73], off
	global_load_dwordx2 v[102:103], v[120:121], off
	v_add_u32_e32 v158, v124, v119
	v_lshl_add_u64 v[72:73], v[158:159], 2, s[90:91]
	global_load_dwordx4 v[84:87], v[72:73], off
	v_add_u32_e32 v158, v124, v118
	v_lshl_add_u64 v[72:73], v[158:159], 2, s[90:91]
	global_load_dwordx4 v[80:83], v[72:73], off
	global_load_dwordx2 v[100:101], v[122:123], off
	v_add_u32_e32 v158, v125, v119
	v_lshl_add_u64 v[72:73], v[158:159], 2, s[90:91]
	global_load_dwordx4 v[76:79], v[72:73], off
	v_add_u32_e32 v158, v125, v118
	v_lshl_add_u64 v[72:73], v[158:159], 2, s[90:91]
	global_load_dwordx4 v[72:75], v[72:73], off
	v_sub_f32_e32 v121, v127, v138
	v_sub_f32_e32 v120, v126, v138
	v_sub_f32_e32 v123, v129, v138
	v_sub_f32_e32 v122, v128, v138
	v_pk_mul_f32 v[122:123], v[138:139], v[122:123] op_sel:[1,0]
	v_pk_mul_f32 v[120:121], v[138:139], v[120:121] op_sel:[1,0]
	v_or_b32_e32 v158, 0x80, v148
	v_pk_fma_f32 v[60:61], v[98:99], v[120:121], v[60:61]
	v_pk_fma_f32 v[62:63], v[96:97], v[122:123], v[62:63]
	v_pk_fma_f32 v[60:61], v[68:69], s[78:79], v[60:61] op_sel_hi:[1,0,1]
	v_pk_fma_f32 v[62:63], v[70:71], s[78:79], v[62:63] op_sel_hi:[1,0,1]
	v_lshl_add_u64 v[120:121], v[158:159], 2, s[88:89]
	global_store_dwordx4 v[120:121], v[60:63], off
	v_or_b32_e32 v158, 0x90, v148
	s_waitcnt vmcnt(0)
	v_sub_f32_e32 v61, v131, v138
	v_sub_f32_e32 v60, v130, v138
	v_sub_f32_e32 v63, v133, v138
	v_sub_f32_e32 v62, v132, v138
	v_pk_mul_f32 v[62:63], v[138:139], v[62:63] op_sel:[1,0]
	v_pk_mul_f32 v[60:61], v[138:139], v[60:61] op_sel:[1,0]
	v_pk_fma_f32 v[58:59], v[92:93], v[62:63], v[58:59]
	v_pk_fma_f32 v[56:57], v[94:95], v[60:61], v[56:57]
	v_pk_fma_f32 v[58:59], v[66:67], s[78:79], v[58:59] op_sel_hi:[1,0,1]
	v_pk_fma_f32 v[56:57], v[64:65], s[78:79], v[56:57] op_sel_hi:[1,0,1]
	v_lshl_add_u64 v[60:61], v[158:159], 2, s[88:89]
	global_store_dwordx4 v[60:61], v[56:59], off
	v_add_u32_e32 v158, 0x8080, v148
	s_nop 0
	v_sub_f32_e32 v57, v135, v112
	v_sub_f32_e32 v56, v134, v112
	v_sub_f32_e32 v59, v137, v112
	v_sub_f32_e32 v58, v136, v112
	v_pk_mul_f32 v[58:59], v[112:113], v[58:59] op_sel:[1,0]
	v_pk_mul_f32 v[56:57], v[112:113], v[56:57] op_sel:[1,0]
	v_pk_fma_f32 v[54:55], v[96:97], v[58:59], v[54:55]
	v_pk_fma_f32 v[52:53], v[98:99], v[56:57], v[52:53]
	v_pk_fma_f32 v[54:55], v[70:71], s[78:79], v[54:55] op_sel_hi:[1,0,1]
	v_pk_fma_f32 v[52:53], v[68:69], s[78:79], v[52:53] op_sel_hi:[1,0,1]
	v_lshl_add_u64 v[56:57], v[158:159], 2, s[88:89]
	global_store_dwordx4 v[56:57], v[52:55], off
	v_add_u32_e32 v158, 0x8090, v148
	s_nop 0
	v_sub_f32_e32 v53, v89, v112
	v_sub_f32_e32 v52, v88, v112
	v_sub_f32_e32 v55, v91, v112
	v_sub_f32_e32 v54, v90, v112
	v_pk_mul_f32 v[54:55], v[112:113], v[54:55] op_sel:[1,0]
	v_pk_mul_f32 v[52:53], v[112:113], v[52:53] op_sel:[1,0]
	v_pk_fma_f32 v[50:51], v[92:93], v[54:55], v[50:51]
	v_pk_fma_f32 v[48:49], v[94:95], v[52:53], v[48:49]
	v_pk_fma_f32 v[50:51], v[66:67], s[78:79], v[50:51] op_sel_hi:[1,0,1]
	v_pk_fma_f32 v[48:49], v[64:65], s[78:79], v[48:49] op_sel_hi:[1,0,1]
	v_lshl_add_u64 v[52:53], v[158:159], 2, s[88:89]
	global_store_dwordx4 v[52:53], v[48:51], off
	v_add_u32_e32 v158, 0x10080, v148
	s_nop 0
	v_sub_f32_e32 v49, v85, v102
	v_sub_f32_e32 v48, v84, v102
	v_sub_f32_e32 v51, v87, v102
	v_sub_f32_e32 v50, v86, v102
	v_pk_mul_f32 v[50:51], v[102:103], v[50:51] op_sel:[1,0]
	v_pk_mul_f32 v[48:49], v[102:103], v[48:49] op_sel:[1,0]
	v_pk_fma_f32 v[46:47], v[96:97], v[50:51], v[46:47]
	v_pk_fma_f32 v[44:45], v[98:99], v[48:49], v[44:45]
	v_pk_fma_f32 v[46:47], v[70:71], s[78:79], v[46:47] op_sel_hi:[1,0,1]
	v_pk_fma_f32 v[44:45], v[68:69], s[78:79], v[44:45] op_sel_hi:[1,0,1]
	v_lshl_add_u64 v[48:49], v[158:159], 2, s[88:89]
	global_store_dwordx4 v[48:49], v[44:47], off
	v_add_u32_e32 v158, 0x10090, v148
	s_nop 0
	v_sub_f32_e32 v45, v81, v102
	v_sub_f32_e32 v44, v80, v102
	v_sub_f32_e32 v47, v83, v102
	v_sub_f32_e32 v46, v82, v102
	v_pk_mul_f32 v[46:47], v[102:103], v[46:47] op_sel:[1,0]
	v_pk_mul_f32 v[44:45], v[102:103], v[44:45] op_sel:[1,0]
	v_pk_fma_f32 v[42:43], v[92:93], v[46:47], v[42:43]
	v_pk_fma_f32 v[40:41], v[94:95], v[44:45], v[40:41]
	v_pk_fma_f32 v[42:43], v[66:67], s[78:79], v[42:43] op_sel_hi:[1,0,1]
	v_pk_fma_f32 v[40:41], v[64:65], s[78:79], v[40:41] op_sel_hi:[1,0,1]
	v_lshl_add_u64 v[44:45], v[158:159], 2, s[88:89]
	global_store_dwordx4 v[44:45], v[40:43], off
	v_add_u32_e32 v158, 0x18080, v148
	s_nop 0
	v_sub_f32_e32 v41, v77, v100
	v_sub_f32_e32 v40, v76, v100
	v_sub_f32_e32 v43, v79, v100
	v_sub_f32_e32 v42, v78, v100
	v_pk_mul_f32 v[42:43], v[100:101], v[42:43] op_sel:[1,0]
	v_pk_mul_f32 v[40:41], v[100:101], v[40:41] op_sel:[1,0]
	v_pk_fma_f32 v[38:39], v[96:97], v[42:43], v[38:39]
;     template <bool LN, int BJ, int LO, int HI> DI void batch(const f32x4 (&acc)[2][2][4][2], unsigned row0, unsigned col0, const f32x4 (&gv)[2], const f32x4 (&bv)[2]) const {
;         f32x4 r[HI - LO]; float mean[(HI - LO) / 2], rstd[(HI - LO) / 2];
; #pragma unroll
;         for (int i = LO; i < HI; ++i) { const int ai = i >> 3, m = (i >> 1) & 3, n = i & 1; const unsigned row = row0 + ai * HALF + m * 16;
;             if (n == 0) { mean[(i - LO) >> 1] = 0.f; rstd[(i - LO) >> 1] = 1.f;
;                 if (LN) { const float2 st = *(const float2*)(stats + row * 2u); mean[(i - LO) >> 1] = st.x; rstd[(i - LO) >> 1] = st.y; } }
;             r[i - LO] = *(const f32x4*)(src + (row * (unsigned)DM + col0 + BJ * HALF + n * 16)); }
; #pragma unroll
;         for (int i = LO; i < HI; ++i) { const int ai = i >> 3, m = (i >> 1) & 3, n = i & 1; const unsigned row = row0 + ai * HALF + m * 16;
;             *(f32x4*)(Y + (row * (unsigned)DM + col0 + BJ * HALF + n * 16)) = acc[ai][BJ][m][n] + ((r[i - LO] - mean[(i - LO) >> 1]) * rstd[(i - LO) >> 1]) * gv[n] + bv[n]; }
	v_pk_fma_f32 v[36:37], v[98:99], v[40:41], v[36:37]
	v_pk_fma_f32 v[38:39], v[70:71], s[78:79], v[38:39] op_sel_hi:[1,0,1]
	v_pk_fma_f32 v[36:37], v[68:69], s[78:79], v[36:37] op_sel_hi:[1,0,1]
	v_lshl_add_u64 v[40:41], v[158:159], 2, s[88:89]
	global_store_dwordx4 v[40:41], v[36:39], off
	v_add_u32_e32 v158, 0x18090, v148
	s_nop 0
	v_sub_f32_e32 v37, v73, v100
	v_sub_f32_e32 v36, v72, v100
	v_sub_f32_e32 v39, v75, v100
	v_sub_f32_e32 v38, v74, v100
	v_pk_mul_f32 v[38:39], v[100:101], v[38:39] op_sel:[1,0]
	v_pk_mul_f32 v[36:37], v[100:101], v[36:37] op_sel:[1,0]
	v_pk_fma_f32 v[34:35], v[92:93], v[38:39], v[34:35]
	v_pk_fma_f32 v[32:33], v[94:95], v[36:37], v[32:33]
	v_pk_fma_f32 v[34:35], v[66:67], s[78:79], v[34:35] op_sel_hi:[1,0,1]
	v_pk_fma_f32 v[32:33], v[64:65], s[78:79], v[32:33] op_sel_hi:[1,0,1]
	v_lshl_add_u64 v[36:37], v[158:159], 2, s[88:89]
	global_store_dwordx4 v[36:37], v[32:35], off
	v_add_u32_e32 v158, v114, v119
	s_nop 0
	v_lshl_add_u64 v[32:33], v[158:159], 2, s[90:91]
	global_load_dwordx2 v[62:63], v[104:105], off
	global_load_dwordx4 v[54:57], v[32:33], off
	v_add_u32_e32 v158, v114, v118
	v_lshl_add_u64 v[32:33], v[158:159], 2, s[90:91]
	global_load_dwordx4 v[58:61], v[32:33], off
	global_load_dwordx2 v[52:53], v[106:107], off
	v_add_u32_e32 v158, v115, v119
	v_lshl_add_u64 v[32:33], v[158:159], 2, s[90:91]
	global_load_dwordx4 v[72:75], v[32:33], off
	v_add_u32_e32 v158, v115, v118
	v_lshl_add_u64 v[32:33], v[158:159], 2, s[90:91]
	global_load_dwordx4 v[76:79], v[32:33], off
	global_load_dwordx2 v[50:51], v[108:109], off
	v_add_u32_e32 v158, v116, v119
	v_lshl_add_u64 v[32:33], v[158:159], 2, s[90:91]
	global_load_dwordx4 v[44:47], v[32:33], off
	v_add_u32_e32 v158, v116, v118
	v_lshl_add_u64 v[32:33], v[158:159], 2, s[90:91]
	global_load_dwordx4 v[40:43], v[32:33], off
	global_load_dwordx2 v[48:49], v[110:111], off
	v_add_u32_e32 v158, v117, v119
	v_lshl_add_u64 v[32:33], v[158:159], 2, s[90:91]
	global_load_dwordx4 v[36:39], v[32:33], off
	v_add_u32_e32 v158, v117, v118
	v_lshl_add_u64 v[32:33], v[158:159], 2, s[90:91]
	global_load_dwordx4 v[32:35], v[32:33], off
	v_add_u32_e32 v158, 0x40080, v148
	s_waitcnt vmcnt(0)
; #define PG8_WAIT_V(n) asm volatile("s_waitcnt vmcnt(" #n ")" ::: "memory")
; #define PG8_BAR __builtin_amdgcn_s_barrier()
; template <class Epi>
; DI void gemm_phase(LAS unsigned char* lds, const Gemm g, const StaticOrder& S, const Epi& E) {
;     ...
;         if (!has_next) break;
; #pragma unroll
;         for (int a = 0; a < 2; ++a)
; #pragma unroll
;             for (int b = 0; b < 2; ++b)
; #pragma unroll
;                 for (int m = 0; m < 4; ++m)
; #pragma unroll
;                     for (int n = 0; n < 2; ++n) acc[a][b][m][n] = (f32x4){0.f, 0.f, 0.f, 0.f};
;         cur = nxt; cA = nA; cB = nB; ++ui;
;     }
;     PG8_WAIT_V(0);
;     if (wr == 0) PG8_BAR;
;     PG8_BAR;
;     template <bool LN, int BJ, int LO, int HI> DI void batch(const f32x4 (&acc)[2][2][4][2], unsigned row0, unsigned col0, const f32x4 (&gv)[2], const f32x4 (&bv)[2]) const {
;         f32x4 r[HI - LO]; float mean[(HI - LO) / 2], rstd[(HI - LO) / 2];
; #pragma unroll
;         for (int i = LO; i < HI; ++i) { const int ai = i >> 3, m = (i >> 1) & 3, n = i & 1; const unsigned row = row0 + ai * HALF + m * 16;
;             if (n == 0) { mean[(i - LO) >> 1] = 0.f; rstd[(i - LO) >> 1] = 1.f;
;                 if (LN) { const float2 st = *(const float2*)(stats + row * 2u); mean[(i - LO) >> 1] = st.x; rstd[(i - LO) >> 1] = st.y; } }
;             r[i - LO] = *(const f32x4*)(src + (row * (unsigned)DM + col0 + BJ * HALF + n * 16)); }
; #pragma unroll
;         for (int i = LO; i < HI; ++i) { const int ai = i >> 3, m = (i >> 1) & 3, n = i & 1; const unsigned row = row0 + ai * HALF + m * 16;
;             *(f32x4*)(Y + (row * (unsigned)DM + col0 + BJ * HALF + n * 16)) = acc[ai][BJ][m][n] + ((r[i - LO] - mean[(i - LO) >> 1]) * rstd[(i - LO) >> 1]) * gv[n] + bv[n]; }
	v_sub_f32_e32 v55, v55, v62
	v_sub_f32_e32 v54, v54, v62
	v_sub_f32_e32 v57, v57, v62
	v_sub_f32_e32 v56, v56, v62
	v_pk_mul_f32 v[56:57], v[62:63], v[56:57] op_sel:[1,0]
	v_pk_mul_f32 v[54:55], v[62:63], v[54:55] op_sel:[1,0]
	v_pk_fma_f32 v[30:31], v[96:97], v[56:57], v[30:31]
	v_pk_fma_f32 v[28:29], v[98:99], v[54:55], v[28:29]
	v_pk_fma_f32 v[30:31], v[70:71], s[78:79], v[30:31] op_sel_hi:[1,0,1]
	v_pk_fma_f32 v[28:29], v[68:69], s[78:79], v[28:29] op_sel_hi:[1,0,1]
	v_lshl_add_u64 v[54:55], v[158:159], 2, s[88:89]
	global_store_dwordx4 v[54:55], v[28:31], off
	v_add_u32_e32 v158, 0x40090, v148
	s_nop 0
	v_sub_f32_e32 v29, v59, v62
	v_sub_f32_e32 v28, v58, v62
	v_sub_f32_e32 v31, v61, v62
	v_sub_f32_e32 v30, v60, v62
	v_pk_mul_f32 v[30:31], v[62:63], v[30:31] op_sel:[1,0]
	v_pk_mul_f32 v[28:29], v[62:63], v[28:29] op_sel:[1,0]
	v_pk_fma_f32 v[26:27], v[92:93], v[30:31], v[26:27]
	v_pk_fma_f32 v[24:25], v[94:95], v[28:29], v[24:25]
	v_pk_fma_f32 v[26:27], v[66:67], s[78:79], v[26:27] op_sel_hi:[1,0,1]
	v_pk_fma_f32 v[24:25], v[64:65], s[78:79], v[24:25] op_sel_hi:[1,0,1]
	v_lshl_add_u64 v[28:29], v[158:159], 2, s[88:89]
	global_store_dwordx4 v[28:29], v[24:27], off
	v_add_u32_e32 v158, 0x48080, v148
	s_nop 0
	v_sub_f32_e32 v25, v73, v52
	v_sub_f32_e32 v24, v72, v52
	v_sub_f32_e32 v27, v75, v52
	v_sub_f32_e32 v26, v74, v52
	v_pk_mul_f32 v[26:27], v[52:53], v[26:27] op_sel:[1,0]
	v_pk_mul_f32 v[24:25], v[52:53], v[24:25] op_sel:[1,0]
	v_pk_fma_f32 v[22:23], v[96:97], v[26:27], v[22:23]
	v_pk_fma_f32 v[20:21], v[98:99], v[24:25], v[20:21]
	v_pk_fma_f32 v[22:23], v[70:71], s[78:79], v[22:23] op_sel_hi:[1,0,1]
	v_pk_fma_f32 v[20:21], v[68:69], s[78:79], v[20:21] op_sel_hi:[1,0,1]
	v_lshl_add_u64 v[24:25], v[158:159], 2, s[88:89]
	global_store_dwordx4 v[24:25], v[20:23], off
	v_add_u32_e32 v158, 0x48090, v148
	s_nop 0
	v_sub_f32_e32 v21, v77, v52
	v_sub_f32_e32 v20, v76, v52
	v_sub_f32_e32 v23, v79, v52
	v_sub_f32_e32 v22, v78, v52
	v_pk_mul_f32 v[22:23], v[52:53], v[22:23] op_sel:[1,0]
	v_pk_mul_f32 v[20:21], v[52:53], v[20:21] op_sel:[1,0]
	v_pk_fma_f32 v[18:19], v[92:93], v[22:23], v[18:19]
	v_pk_fma_f32 v[16:17], v[94:95], v[20:21], v[16:17]
	v_pk_fma_f32 v[18:19], v[66:67], s[78:79], v[18:19] op_sel_hi:[1,0,1]
	v_pk_fma_f32 v[16:17], v[64:65], s[78:79], v[16:17] op_sel_hi:[1,0,1]
	v_lshl_add_u64 v[20:21], v[158:159], 2, s[88:89]
	global_store_dwordx4 v[20:21], v[16:19], off
	v_add_u32_e32 v158, 0x50080, v148
	s_nop 0
	v_sub_f32_e32 v17, v45, v50
	v_sub_f32_e32 v16, v44, v50
	v_sub_f32_e32 v19, v47, v50
	v_sub_f32_e32 v18, v46, v50
	v_pk_mul_f32 v[18:19], v[50:51], v[18:19] op_sel:[1,0]
	v_pk_mul_f32 v[16:17], v[50:51], v[16:17] op_sel:[1,0]
	v_pk_fma_f32 v[14:15], v[96:97], v[18:19], v[14:15]
	v_pk_fma_f32 v[12:13], v[98:99], v[16:17], v[12:13]
	v_pk_fma_f32 v[14:15], v[70:71], s[78:79], v[14:15] op_sel_hi:[1,0,1]
	v_pk_fma_f32 v[12:13], v[68:69], s[78:79], v[12:13] op_sel_hi:[1,0,1]
	v_lshl_add_u64 v[16:17], v[158:159], 2, s[88:89]
	global_store_dwordx4 v[16:17], v[12:15], off
	v_add_u32_e32 v158, 0x50090, v148
	s_nop 0
	v_sub_f32_e32 v13, v41, v50
	v_sub_f32_e32 v12, v40, v50
	v_sub_f32_e32 v15, v43, v50
	v_sub_f32_e32 v14, v42, v50
	v_pk_mul_f32 v[14:15], v[50:51], v[14:15] op_sel:[1,0]
	v_pk_mul_f32 v[12:13], v[50:51], v[12:13] op_sel:[1,0]
	v_pk_fma_f32 v[10:11], v[92:93], v[14:15], v[10:11]
	v_pk_fma_f32 v[8:9], v[94:95], v[12:13], v[8:9]
	v_pk_fma_f32 v[10:11], v[66:67], s[78:79], v[10:11] op_sel_hi:[1,0,1]
	v_pk_fma_f32 v[8:9], v[64:65], s[78:79], v[8:9] op_sel_hi:[1,0,1]
	v_lshl_add_u64 v[12:13], v[158:159], 2, s[88:89]
	global_store_dwordx4 v[12:13], v[8:11], off
	v_add_u32_e32 v158, 0x58080, v148
	s_nop 0
	v_sub_f32_e32 v9, v37, v48
	v_sub_f32_e32 v8, v36, v48
	v_sub_f32_e32 v11, v39, v48
	v_sub_f32_e32 v10, v38, v48
	v_pk_mul_f32 v[10:11], v[48:49], v[10:11] op_sel:[1,0]
	v_pk_mul_f32 v[8:9], v[48:49], v[8:9] op_sel:[1,0]
	v_pk_fma_f32 v[6:7], v[96:97], v[10:11], v[6:7]
	v_pk_fma_f32 v[4:5], v[98:99], v[8:9], v[4:5]
	v_pk_fma_f32 v[6:7], v[70:71], s[78:79], v[6:7] op_sel_hi:[1,0,1]
	v_pk_fma_f32 v[4:5], v[68:69], s[78:79], v[4:5] op_sel_hi:[1,0,1]
	v_lshl_add_u64 v[8:9], v[158:159], 2, s[88:89]
	global_store_dwordx4 v[8:9], v[4:7], off
	v_add_u32_e32 v158, 0x58090, v148
	s_nop 0
	v_sub_f32_e32 v5, v33, v48
	v_sub_f32_e32 v4, v32, v48
	v_sub_f32_e32 v7, v35, v48
	v_sub_f32_e32 v6, v34, v48
	v_pk_mul_f32 v[6:7], v[48:49], v[6:7] op_sel:[1,0]
	v_pk_mul_f32 v[4:5], v[48:49], v[4:5] op_sel:[1,0]
	v_pk_fma_f32 v[2:3], v[92:93], v[6:7], v[2:3]
	v_pk_fma_f32 v[0:1], v[94:95], v[4:5], v[0:1]
	v_pk_fma_f32 v[2:3], v[66:67], s[78:79], v[2:3] op_sel_hi:[1,0,1]
	v_pk_fma_f32 v[0:1], v[64:65], s[78:79], v[0:1] op_sel_hi:[1,0,1]
	v_lshl_add_u64 v[4:5], v[158:159], 2, s[88:89]
	global_store_dwordx4 v[4:5], v[0:3], off
	s_and_b64 vcc, exec, s[6:7]
	s_mov_b32 s2, s37
	s_mov_b32 s3, s38
	s_mov_b64 s[18:19], s[10:11]
	s_mov_b64 s[16:17], s[8:9]
	v_readlane_b32 s33, v255, 39
	s_cbranch_vccz .LBB0_123
	s_waitcnt vmcnt(0)
	s_cmpk_gt_u32 s24, 0xff
	s_cbranch_scc1 .LBB0_138
	s_barrier

; #define PG8_STAGE(bufoff, gbase) do { _Pragma("unroll") for (int _i = 0; _i < 2; ++_i) \
;         __builtin_amdgcn_global_load_lds((const unsigned*)((const char*)(gbase) + voff[_i]), (LAS unsigned*)(lds + (bufoff) + ldsw + _i * 8192), 16, 0, 0); } while (0)
; #define PG8_LDA(dst, b, h) do { _Pragma("unroll") for (int m = 0; m < 4; ++m) _Pragma("unroll") for (int k = 0; k < 2; ++k) dst[m][k] = *(const LAS bf16x8*)(lds + PG8_SA(b, h) + aoff + m * 2048 + k * 1024); } while (0)
; #define PG8_LDB(dst, b, h) do { _Pragma("unroll") for (int n = 0; n < 2; ++n) _Pragma("unroll") for (int k = 0; k < 2; ++k) dst[n][k] = *(const LAS bf16x8*)(lds + PG8_SB(b, h) + boff + n * 2048 + k * 1024); } while (0)
; #define PG8_MMA(ai, bj, At, Bt) do { __builtin_amdgcn_s_setprio(1); _Pragma("unroll") for (int m = 0; m < 4; ++m) _Pragma("unroll") for (int n = 0; n < 2; ++n) _Pragma("unroll") for (int k = 0; k < 2; ++k) \
;         acc[ai][bj][m][n] = __builtin_amdgcn_mfma_f32_16x16x32_bf16(Bt[n][k], At[m][k], acc[ai][bj][m][n], 0, 0, 0); __builtin_amdgcn_s_setprio(0); } while (0)
; #define PG8_WAIT_V(n) asm volatile("s_waitcnt vmcnt(" #n ")" ::: "memory")
; #define PG8_WAIT_L(n) asm volatile("s_waitcnt lgkmcnt(" #n ")" ::: "memory")
; #define PG8_BAR __builtin_amdgcn_s_barrier()
; #define PG8_SCHED __builtin_amdgcn_sched_barrier(0)
; template <class Epi>
; DI void gemm_phase(LAS unsigned char* lds, const Gemm g, const StaticOrder& S, const Epi& E) {
;     ...
;         for (int t = 0; t < nt; t += 2) {
;             const bool last = (t == nt - 2);
;             const char* a1 = cA + (size_t)(t + 1) * kstep;
;             const char* a2 = last ? nA : cA + (size_t)(t + 2) * kstep; const char* b2 = last ? nB : cB + (size_t)(t + 2) * kstep;
;             const char* a3 = a2 + kstep; const char* b3 = b2 + kstep;
;             PG8_LDB(B0, 0, 0); PG8_SCHED; PG8_LDA(At, 0, 0); PG8_STAGE(PG8_SA(1, 1), a1 + hstep);
;             PG8_WAIT_L(8); PG8_BAR; PG8_WAIT_L(0); PG8_MMA(0, 0, At, B0); PG8_BAR; PG8_SCHED;
;             PG8_LDB(B1, 0, 1); PG8_STAGE(PG8_SB(0, 0), b2);
;             PG8_BAR; PG8_WAIT_L(0); PG8_MMA(0, 1, At, B1); PG8_BAR;
;             PG8_LDA(At, 0, 1); PG8_STAGE(PG8_SA(0, 0), a2);
;             PG8_BAR; PG8_WAIT_L(0); PG8_MMA(1, 0, At, B0); PG8_BAR; PG8_SCHED;
;             PG8_STAGE(PG8_SB(0, 1), b2 + hstep);
;             PG8_WAIT_V(6); PG8_BAR; PG8_MMA(1, 1, At, B1); PG8_BAR;
.LBB0_202:
	s_add_u32 s18, s8, 0xfff80080
	s_addc_u32 s19, s9, -1
	s_add_i32 s37, 0, 0x10000
	s_waitcnt lgkmcnt(0)
	s_cmp_eq_u32 s36, 28
	s_cselect_b32 s21, s4, s19
	s_cselect_b32 s20, s5, s18
	s_cselect_b32 s19, s11, s35
	s_cselect_b32 s18, s13, s33
	s_add_i32 m0, s26, 0xc000
	s_nop 0
	global_load_lds_dwordx4 v150, s[8:9]
	s_add_i32 m0, s26, 0xe000
	s_nop 0
	global_load_lds_dwordx4 v152, s[8:9]
	ds_read_b128 v[128:131], v187
	ds_read_b128 v[132:135], v187 offset:1024
	ds_read_b128 v[136:139], v187 offset:2048
	ds_read_b128 v[190:193], v187 offset:3072
	ds_read_b128 v[194:197], v189
	ds_read_b128 v[198:201], v189 offset:1024
	ds_read_b128 v[202:205], v189 offset:2048
	ds_read_b128 v[206:209], v189 offset:3072
	ds_read_b128 v[210:213], v189 offset:4096
	ds_read_b128 v[214:217], v189 offset:5120
	ds_read_b128 v[226:229], v189 offset:6144
	ds_read_b128 v[230:233], v189 offset:7168
	s_waitcnt lgkmcnt(8)
	s_setprio 1
	s_barrier
	s_waitcnt lgkmcnt(0)
	v_mfma_f32_16x16x32_bf16 v[124:127], v[128:131], v[194:197], v[124:127]
	v_mfma_f32_16x16x32_bf16 v[120:123], v[136:139], v[194:197], v[120:123]
	v_mfma_f32_16x16x32_bf16 v[108:111], v[128:131], v[202:205], v[108:111]
	v_mfma_f32_16x16x32_bf16 v[104:107], v[136:139], v[202:205], v[104:107]
	v_mfma_f32_16x16x32_bf16 v[92:95], v[128:131], v[210:213], v[92:95]
	v_mfma_f32_16x16x32_bf16 v[88:91], v[136:139], v[210:213], v[88:91]
	v_mfma_f32_16x16x32_bf16 v[76:79], v[128:131], v[226:229], v[76:79]
	v_mfma_f32_16x16x32_bf16 v[72:75], v[136:139], v[226:229], v[72:75]
	v_mfma_f32_16x16x32_bf16 v[124:127], v[132:135], v[198:201], v[124:127]
	v_mfma_f32_16x16x32_bf16 v[120:123], v[190:193], v[198:201], v[120:123]
	v_mfma_f32_16x16x32_bf16 v[108:111], v[132:135], v[206:209], v[108:111]
	v_mfma_f32_16x16x32_bf16 v[104:107], v[190:193], v[206:209], v[104:107]
	v_mfma_f32_16x16x32_bf16 v[92:95], v[132:135], v[214:217], v[92:95]
	v_mfma_f32_16x16x32_bf16 v[88:91], v[190:193], v[214:217], v[88:91]
	v_mfma_f32_16x16x32_bf16 v[76:79], v[132:135], v[230:233], v[76:79]
	s_setprio 0
	v_mfma_f32_16x16x32_bf16 v[72:75], v[190:193], v[230:233], v[72:75]
	s_barrier
	s_add_i32 s40, 0, 0x14000
	s_add_i32 s37, s37, s25
	s_mov_b32 m0, s37
	s_nop 0
	global_load_lds_dwordx4 v144, s[18:19]
	s_add_i32 m0, s37, 0x2000
	s_nop 0
	global_load_lds_dwordx4 v142, s[18:19]
	ds_read_b128 v[234:237], v187 offset:16384
	ds_read_b128 v[238:241], v187 offset:17408
	ds_read_b128 v[242:245], v187 offset:18432
	ds_read_b128 v[246:249], v187 offset:19456
	s_waitcnt lgkmcnt(0)
	s_setprio 1
	s_barrier
	v_mfma_f32_16x16x32_bf16 v[116:119], v[234:237], v[194:197], v[116:119]
	v_mfma_f32_16x16x32_bf16 v[112:115], v[242:245], v[194:197], v[112:115]
	v_mfma_f32_16x16x32_bf16 v[100:103], v[234:237], v[202:205], v[100:103]
	v_mfma_f32_16x16x32_bf16 v[96:99], v[242:245], v[202:205], v[96:99]
	v_mfma_f32_16x16x32_bf16 v[84:87], v[234:237], v[210:213], v[84:87]
	v_mfma_f32_16x16x32_bf16 v[80:83], v[242:245], v[210:213], v[80:83]
	v_mfma_f32_16x16x32_bf16 v[68:71], v[234:237], v[226:229], v[68:71]
	v_mfma_f32_16x16x32_bf16 v[64:67], v[242:245], v[226:229], v[64:67]
	v_mfma_f32_16x16x32_bf16 v[116:119], v[238:241], v[198:201], v[116:119]
	s_mov_b32 m0, s26
	v_mfma_f32_16x16x32_bf16 v[112:115], v[246:249], v[198:201], v[112:115]
	s_mov_b64 s[100:101], s[20:21]
	v_mfma_f32_16x16x32_bf16 v[100:103], v[238:241], v[206:209], v[100:103]
	v_mfma_f32_16x16x32_bf16 v[96:99], v[246:249], v[206:209], v[96:99]
	v_mfma_f32_16x16x32_bf16 v[84:87], v[238:241], v[214:217], v[84:87]
	v_mfma_f32_16x16x32_bf16 v[80:83], v[246:249], v[214:217], v[80:83]
	v_mfma_f32_16x16x32_bf16 v[68:71], v[238:241], v[230:233], v[68:71]
	s_setprio 0
	v_mfma_f32_16x16x32_bf16 v[64:67], v[246:249], v[230:233], v[64:67]
	s_barrier
	global_load_lds_dwordx4 v144, s[20:21]
	s_mov_b64 s[100:101], s[20:21]
	s_mov_b32 m0, s27
	s_nop 0
	global_load_lds_dwordx4 v142, s[20:21]
	ds_read_b128 v[194:197], v189 offset:16384
	ds_read_b128 v[198:201], v189 offset:17408
	ds_read_b128 v[202:205], v189 offset:18432
	ds_read_b128 v[206:209], v189 offset:19456
	ds_read_b128 v[210:213], v189 offset:20480
	ds_read_b128 v[214:217], v189 offset:21504
	ds_read_b128 v[226:229], v189 offset:22528
	ds_read_b128 v[230:233], v189 offset:23552
	s_waitcnt lgkmcnt(0)
	s_setprio 1
	s_barrier
	v_mfma_f32_16x16x32_bf16 v[60:63], v[128:131], v[194:197], v[60:63]
	v_mfma_f32_16x16x32_bf16 v[56:59], v[136:139], v[194:197], v[56:59]
	v_mfma_f32_16x16x32_bf16 v[44:47], v[128:131], v[202:205], v[44:47]
	v_mfma_f32_16x16x32_bf16 v[40:43], v[136:139], v[202:205], v[40:43]
	v_mfma_f32_16x16x32_bf16 v[28:31], v[128:131], v[210:213], v[28:31]
	v_mfma_f32_16x16x32_bf16 v[24:27], v[136:139], v[210:213], v[24:27]
	v_mfma_f32_16x16x32_bf16 v[12:15], v[128:131], v[226:229], v[12:15]
	v_mfma_f32_16x16x32_bf16 v[8:11], v[136:139], v[226:229], v[8:11]
	v_mfma_f32_16x16x32_bf16 v[60:63], v[132:135], v[198:201], v[60:63]
	v_mfma_f32_16x16x32_bf16 v[56:59], v[190:193], v[198:201], v[56:59]
	v_mfma_f32_16x16x32_bf16 v[44:47], v[132:135], v[206:209], v[44:47]
	v_mfma_f32_16x16x32_bf16 v[40:43], v[190:193], v[206:209], v[40:43]
	v_mfma_f32_16x16x32_bf16 v[28:31], v[132:135], v[214:217], v[28:31]
	v_mfma_f32_16x16x32_bf16 v[24:27], v[190:193], v[214:217], v[24:27]
	v_mfma_f32_16x16x32_bf16 v[12:15], v[132:135], v[230:233], v[12:15]
	s_setprio 0
	v_mfma_f32_16x16x32_bf16 v[8:11], v[190:193], v[230:233], v[8:11]
	s_barrier
	s_add_u32 s38, s18, 0x80000
	s_addc_u32 s39, s19, 0
	s_add_i32 s37, s40, s25
	s_mov_b32 m0, s37
	s_nop 0
	global_load_lds_dwordx4 v144, s[38:39]
	s_add_i32 m0, s37, 0x2000
	s_nop 0
	global_load_lds_dwordx4 v142, s[38:39]
	s_waitcnt vmcnt(6)
	s_setprio 1
	s_barrier
; #define PG8_STAGE(bufoff, gbase) do { _Pragma("unroll") for (int _i = 0; _i < 2; ++_i) \
;         __builtin_amdgcn_global_load_lds((const unsigned*)((const char*)(gbase) + voff[_i]), (LAS unsigned*)(lds + (bufoff) + ldsw + _i * 8192), 16, 0, 0); } while (0)
; #define PG8_LDA(dst, b, h) do { _Pragma("unroll") for (int m = 0; m < 4; ++m) _Pragma("unroll") for (int k = 0; k < 2; ++k) dst[m][k] = *(const LAS bf16x8*)(lds + PG8_SA(b, h) + aoff + m * 2048 + k * 1024); } while (0)
; #define PG8_LDB(dst, b, h) do { _Pragma("unroll") for (int n = 0; n < 2; ++n) _Pragma("unroll") for (int k = 0; k < 2; ++k) dst[n][k] = *(const LAS bf16x8*)(lds + PG8_SB(b, h) + boff + n * 2048 + k * 1024); } while (0)
; #define PG8_MMA(ai, bj, At, Bt) do { __builtin_amdgcn_s_setprio(1); _Pragma("unroll") for (int m = 0; m < 4; ++m) _Pragma("unroll") for (int n = 0; n < 2; ++n) _Pragma("unroll") for (int k = 0; k < 2; ++k) \
;         acc[ai][bj][m][n] = __builtin_amdgcn_mfma_f32_16x16x32_bf16(Bt[n][k], At[m][k], acc[ai][bj][m][n], 0, 0, 0); __builtin_amdgcn_s_setprio(0); } while (0)
; #define PG8_WAIT_V(n) asm volatile("s_waitcnt vmcnt(" #n ")" ::: "memory")
; #define PG8_WAIT_L(n) asm volatile("s_waitcnt lgkmcnt(" #n ")" ::: "memory")
; #define PG8_BAR __builtin_amdgcn_s_barrier()
; #define PG8_SCHED __builtin_amdgcn_sched_barrier(0)
; template <class Epi>
; DI void gemm_phase(LAS unsigned char* lds, const Gemm g, const StaticOrder& S, const Epi& E) {
;     ...
;             PG8_WAIT_V(6); PG8_BAR; PG8_MMA(1, 1, At, B1); PG8_BAR;
;             PG8_LDB(B0, 1, 0); PG8_SCHED; PG8_LDA(At, 1, 0); PG8_STAGE(PG8_SA(0, 1), a2 + hstep);
;             PG8_WAIT_L(8); PG8_BAR; PG8_WAIT_L(0); PG8_MMA(0, 0, At, B0); PG8_BAR; PG8_SCHED;
;             PG8_LDB(B1, 1, 1); PG8_STAGE(PG8_SB(1, 0), b3);
;             PG8_BAR; PG8_WAIT_L(0); PG8_MMA(0, 1, At, B1); PG8_BAR;
;             PG8_LDA(At, 1, 1); PG8_STAGE(PG8_SA(1, 0), a3);
;             PG8_BAR; PG8_WAIT_L(0); PG8_MMA(1, 0, At, B0); PG8_BAR; PG8_SCHED;
	v_mfma_f32_16x16x32_bf16 v[52:55], v[234:237], v[194:197], v[52:55]
	v_mfma_f32_16x16x32_bf16 v[48:51], v[242:245], v[194:197], v[48:51]
	v_mfma_f32_16x16x32_bf16 v[36:39], v[234:237], v[202:205], v[36:39]
	v_mfma_f32_16x16x32_bf16 v[32:35], v[242:245], v[202:205], v[32:35]
	v_mfma_f32_16x16x32_bf16 v[20:23], v[234:237], v[210:213], v[20:23]
	v_mfma_f32_16x16x32_bf16 v[16:19], v[242:245], v[210:213], v[16:19]
	v_mfma_f32_16x16x32_bf16 v[4:7], v[234:237], v[226:229], v[4:7]
	v_mfma_f32_16x16x32_bf16 v[0:3], v[242:245], v[226:229], v[0:3]
	v_mfma_f32_16x16x32_bf16 v[52:55], v[238:241], v[198:201], v[52:55]
	s_add_i32 s37, 0, 0x18000
	v_mfma_f32_16x16x32_bf16 v[48:51], v[246:249], v[198:201], v[48:51]
	v_mfma_f32_16x16x32_bf16 v[36:39], v[238:241], v[206:209], v[36:39]
	v_mfma_f32_16x16x32_bf16 v[32:35], v[246:249], v[206:209], v[32:35]
	v_mfma_f32_16x16x32_bf16 v[20:23], v[238:241], v[214:217], v[20:23]
	v_mfma_f32_16x16x32_bf16 v[16:19], v[246:249], v[214:217], v[16:19]
	v_mfma_f32_16x16x32_bf16 v[4:7], v[238:241], v[230:233], v[4:7]
	s_setprio 0
	v_mfma_f32_16x16x32_bf16 v[0:3], v[246:249], v[230:233], v[0:3]
	s_barrier
	s_add_u32 s20, s20, 0x80000
	s_addc_u32 s21, s21, 0
	s_mov_b32 m0, s28
	s_nop 0
	global_load_lds_dwordx4 v144, s[20:21]
	s_mov_b32 m0, s29
	s_nop 0
	global_load_lds_dwordx4 v142, s[20:21]
	ds_read_b128 v[128:131], v187 offset:32768
	ds_read_b128 v[132:135], v187 offset:33792
	ds_read_b128 v[136:139], v187 offset:34816
	ds_read_b128 v[190:193], v187 offset:35840
	ds_read_b128 v[194:197], v189 offset:32768
	ds_read_b128 v[198:201], v189 offset:33792
	ds_read_b128 v[202:205], v189 offset:34816
	ds_read_b128 v[206:209], v189 offset:35840
	ds_read_b128 v[210:213], v189 offset:36864
	ds_read_b128 v[214:217], v189 offset:37888
	ds_read_b128 v[226:229], v189 offset:38912
	ds_read_b128 v[230:233], v189 offset:39936
	s_waitcnt lgkmcnt(8)
	s_setprio 1
	s_barrier
	s_waitcnt lgkmcnt(0)
	v_mfma_f32_16x16x32_bf16 v[124:127], v[128:131], v[194:197], v[124:127]
	v_mfma_f32_16x16x32_bf16 v[120:123], v[136:139], v[194:197], v[120:123]
	v_mfma_f32_16x16x32_bf16 v[108:111], v[128:131], v[202:205], v[108:111]
	v_mfma_f32_16x16x32_bf16 v[104:107], v[136:139], v[202:205], v[104:107]
	v_mfma_f32_16x16x32_bf16 v[92:95], v[128:131], v[210:213], v[92:95]
	v_mfma_f32_16x16x32_bf16 v[88:91], v[136:139], v[210:213], v[88:91]
	v_mfma_f32_16x16x32_bf16 v[76:79], v[128:131], v[226:229], v[76:79]
	v_mfma_f32_16x16x32_bf16 v[72:75], v[136:139], v[226:229], v[72:75]
	v_mfma_f32_16x16x32_bf16 v[124:127], v[132:135], v[198:201], v[124:127]
	v_mfma_f32_16x16x32_bf16 v[120:123], v[190:193], v[198:201], v[120:123]
	v_mfma_f32_16x16x32_bf16 v[108:111], v[132:135], v[206:209], v[108:111]
	v_mfma_f32_16x16x32_bf16 v[104:107], v[190:193], v[206:209], v[104:107]
	v_mfma_f32_16x16x32_bf16 v[92:95], v[132:135], v[214:217], v[92:95]
	v_mfma_f32_16x16x32_bf16 v[88:91], v[190:193], v[214:217], v[88:91]
	v_mfma_f32_16x16x32_bf16 v[76:79], v[132:135], v[230:233], v[76:79]
	s_setprio 0
	v_mfma_f32_16x16x32_bf16 v[72:75], v[190:193], v[230:233], v[72:75]
	s_barrier
	s_add_i32 s20, 0, 0x1c000
	s_add_i32 s21, s37, s25
	s_add_i32 m0, s21, 0xffffff80
	s_nop 0
	global_load_lds_dwordx4 v144, s[18:19] offset:128
	s_add_i32 m0, s21, 0x1f80
	s_nop 0
	global_load_lds_dwordx4 v142, s[18:19] offset:128
	ds_read_b128 v[234:237], v187 offset:49152
	ds_read_b128 v[238:241], v187 offset:50176
	ds_read_b128 v[242:245], v187 offset:51200
	ds_read_b128 v[246:249], v187 offset:52224
	s_waitcnt lgkmcnt(0)
	s_setprio 1
	s_barrier
	v_mfma_f32_16x16x32_bf16 v[116:119], v[234:237], v[194:197], v[116:119]
	v_mfma_f32_16x16x32_bf16 v[112:115], v[242:245], v[194:197], v[112:115]
	v_mfma_f32_16x16x32_bf16 v[100:103], v[234:237], v[202:205], v[100:103]
	v_mfma_f32_16x16x32_bf16 v[96:99], v[242:245], v[202:205], v[96:99]
	v_mfma_f32_16x16x32_bf16 v[84:87], v[234:237], v[210:213], v[84:87]
	v_mfma_f32_16x16x32_bf16 v[80:83], v[242:245], v[210:213], v[80:83]
	v_mfma_f32_16x16x32_bf16 v[68:71], v[234:237], v[226:229], v[68:71]
	v_mfma_f32_16x16x32_bf16 v[64:67], v[242:245], v[226:229], v[64:67]
	v_mfma_f32_16x16x32_bf16 v[116:119], v[238:241], v[198:201], v[116:119]
	s_add_i32 m0, s30, 0xffffff80
	v_mfma_f32_16x16x32_bf16 v[112:115], v[246:249], v[198:201], v[112:115]
	v_mfma_f32_16x16x32_bf16 v[100:103], v[238:241], v[206:209], v[100:103]
	v_mfma_f32_16x16x32_bf16 v[96:99], v[246:249], v[206:209], v[96:99]
	v_mfma_f32_16x16x32_bf16 v[84:87], v[238:241], v[214:217], v[84:87]
	v_mfma_f32_16x16x32_bf16 v[80:83], v[246:249], v[214:217], v[80:83]
	v_mfma_f32_16x16x32_bf16 v[68:71], v[238:241], v[230:233], v[68:71]
	s_setprio 0
	v_mfma_f32_16x16x32_bf16 v[64:67], v[246:249], v[230:233], v[64:67]
	s_barrier
; #define PG8_STAGE(bufoff, gbase) do { _Pragma("unroll") for (int _i = 0; _i < 2; ++_i) \
;         __builtin_amdgcn_global_load_lds((const unsigned*)((const char*)(gbase) + voff[_i]), (LAS unsigned*)(lds + (bufoff) + ldsw + _i * 8192), 16, 0, 0); } while (0)
; #define PG8_MMA(ai, bj, At, Bt) do { __builtin_amdgcn_s_setprio(1); _Pragma("unroll") for (int m = 0; m < 4; ++m) _Pragma("unroll") for (int n = 0; n < 2; ++n) _Pragma("unroll") for (int k = 0; k < 2; ++k) \
;         acc[ai][bj][m][n] = __builtin_amdgcn_mfma_f32_16x16x32_bf16(Bt[n][k], At[m][k], acc[ai][bj][m][n], 0, 0, 0); __builtin_amdgcn_s_setprio(0); } while (0)
; #define PG8_WAIT_V(n) asm volatile("s_waitcnt vmcnt(" #n ")" ::: "memory")
; #define PG8_WAIT_L(n) asm volatile("s_waitcnt lgkmcnt(" #n ")" ::: "memory")
; #define PG8_BAR __builtin_amdgcn_s_barrier()
; #define PG8_SCHED __builtin_amdgcn_sched_barrier(0)
; template <class Epi>
; DI void gemm_phase(LAS unsigned char* lds, const Gemm g, const StaticOrder& S, const Epi& E) {
;     ...
;             PG8_BAR; PG8_WAIT_L(0); PG8_MMA(1, 0, At, B0); PG8_BAR; PG8_SCHED;
;             PG8_STAGE(PG8_SB(1, 1), b3 + hstep);
;             PG8_WAIT_V(6); PG8_BAR; PG8_MMA(1, 1, At, B1); PG8_BAR;
;     DI void operator()(const f32x4 (&acc)[2][2][4][2], const Unit& u, int wr, int wc, int fr, int fq) const {
;         const int row0 = u.pm * BM + wr * 64 + fr, col0 = u.pn * BM + wc * 16 + 4 * fq;
;         const bool rot = u.pn < 18;
; #pragma unroll
;         for (int ai = 0; ai < 2; ++ai)
; #pragma unroll
;             for (int m = 0; m < 4; ++m) { const int row = row0 + ai * HALF + m * 16; u16* rowp = O + (size_t)row * NQKV_DIL + col0;
;                 f32x4 c4 = (f32x4){1.f, 1.f, 1.f, 1.f}, s4 = (f32x4){0.f, 0.f, 0.f, 0.f};
;                 if (rot) { const int pos = row & (SEQ - 1); c4 = *(const f32x4*)(cs + pos * 64 + wc * 16 + 4 * fq); s4 = *(const f32x4*)(sn + pos * 64 + wc * 16 + 4 * fq); }
	global_load_lds_dwordx4 v144, s[100:101] offset:128
	s_add_i32 m0, s31, 0xffffff80
	s_nop 0
	global_load_lds_dwordx4 v142, s[100:101] offset:128
	ds_read_b128 v[194:197], v189 offset:49152
	ds_read_b128 v[198:201], v189 offset:50176
	ds_read_b128 v[202:205], v189 offset:51200
	ds_read_b128 v[206:209], v189 offset:52224
	ds_read_b128 v[210:213], v189 offset:53248
	ds_read_b128 v[214:217], v189 offset:54272
	ds_read_b128 v[226:229], v189 offset:55296
	ds_read_b128 v[230:233], v189 offset:56320
	s_waitcnt lgkmcnt(0)
	s_setprio 1
	s_barrier
	v_mfma_f32_16x16x32_bf16 v[60:63], v[128:131], v[194:197], v[60:63]
	v_mfma_f32_16x16x32_bf16 v[56:59], v[136:139], v[194:197], v[56:59]
	v_mfma_f32_16x16x32_bf16 v[44:47], v[128:131], v[202:205], v[44:47]
	v_mfma_f32_16x16x32_bf16 v[40:43], v[136:139], v[202:205], v[40:43]
	v_mfma_f32_16x16x32_bf16 v[28:31], v[128:131], v[210:213], v[28:31]
	v_mfma_f32_16x16x32_bf16 v[24:27], v[136:139], v[210:213], v[24:27]
	v_mfma_f32_16x16x32_bf16 v[12:15], v[128:131], v[226:229], v[12:15]
	v_mfma_f32_16x16x32_bf16 v[8:11], v[136:139], v[226:229], v[8:11]
	v_mfma_f32_16x16x32_bf16 v[60:63], v[132:135], v[198:201], v[60:63]
	v_mfma_f32_16x16x32_bf16 v[56:59], v[190:193], v[198:201], v[56:59]
	v_mfma_f32_16x16x32_bf16 v[44:47], v[132:135], v[206:209], v[44:47]
	v_mfma_f32_16x16x32_bf16 v[40:43], v[190:193], v[206:209], v[40:43]
	v_mfma_f32_16x16x32_bf16 v[28:31], v[132:135], v[214:217], v[28:31]
	v_mfma_f32_16x16x32_bf16 v[24:27], v[190:193], v[214:217], v[24:27]
	v_mfma_f32_16x16x32_bf16 v[12:15], v[132:135], v[230:233], v[12:15]
	s_setprio 0
	v_mfma_f32_16x16x32_bf16 v[8:11], v[190:193], v[230:233], v[8:11]
	s_barrier
	s_add_u32 s18, s18, 0x80080
	s_addc_u32 s19, s19, 0
	s_add_i32 s20, s20, s25
	s_mov_b32 m0, s20
	s_nop 0
	global_load_lds_dwordx4 v144, s[18:19]
	s_add_i32 m0, s20, 0x2000
	s_nop 0
	global_load_lds_dwordx4 v142, s[18:19]
	s_waitcnt vmcnt(6)
	s_setprio 1
	s_barrier
	v_mfma_f32_16x16x32_bf16 v[52:55], v[234:237], v[194:197], v[52:55]
	v_mfma_f32_16x16x32_bf16 v[48:51], v[242:245], v[194:197], v[48:51]
	v_mfma_f32_16x16x32_bf16 v[36:39], v[234:237], v[202:205], v[36:39]
	v_mfma_f32_16x16x32_bf16 v[32:35], v[242:245], v[202:205], v[32:35]
	v_mfma_f32_16x16x32_bf16 v[20:23], v[234:237], v[210:213], v[20:23]
	v_mfma_f32_16x16x32_bf16 v[16:19], v[242:245], v[210:213], v[16:19]
	v_mfma_f32_16x16x32_bf16 v[4:7], v[234:237], v[226:229], v[4:7]
	v_mfma_f32_16x16x32_bf16 v[0:3], v[242:245], v[226:229], v[0:3]
	v_mfma_f32_16x16x32_bf16 v[52:55], v[238:241], v[198:201], v[52:55]
	s_add_i32 s36, s36, 2
	v_mfma_f32_16x16x32_bf16 v[48:51], v[246:249], v[198:201], v[48:51]
	s_add_u32 s8, s8, 0x100
	v_mfma_f32_16x16x32_bf16 v[36:39], v[238:241], v[206:209], v[36:39]
	s_addc_u32 s9, s9, 0
	v_mfma_f32_16x16x32_bf16 v[32:35], v[246:249], v[206:209], v[32:35]
	s_add_u32 s33, s33, 0x100
	v_mfma_f32_16x16x32_bf16 v[20:23], v[238:241], v[214:217], v[20:23]
	s_addc_u32 s35, s35, 0
	v_mfma_f32_16x16x32_bf16 v[16:19], v[246:249], v[214:217], v[16:19]
	s_cmp_gt_u32 s36, 29
	v_mfma_f32_16x16x32_bf16 v[4:7], v[238:241], v[230:233], v[4:7]
	s_setprio 0
	v_mfma_f32_16x16x32_bf16 v[0:3], v[246:249], v[230:233], v[0:3]
	s_barrier
	s_cbranch_scc0 .LBB0_202
	s_cmp_lt_i32 s2, 18
	v_lshl_add_u32 v190, s3, 8, v186
	v_mov_b32_e32 v128, 1.0
	v_mov_b32_e32 v132, 0
	s_cselect_b64 s[18:19], -1, 0
	s_cmp_gt_i32 s2, 17
	v_mov_b32_e32 v134, 0
	v_mov_b32_e32 v135, 0
	v_mov_b32_e32 v136, 0
	v_mov_b32_e32 v137, 0
	v_mov_b32_e32 v138, 1.0
	v_mov_b32_e32 v139, 1.0
	v_mov_b32_e32 v140, 1.0
	v_mov_b32_e32 v141, 1.0
	s_cbranch_scc1 .LBB0_205
	v_lshlrev_b32_e32 v129, 8, v190
	v_and_b32_e32 v158, 0xfcf00, v129
	v_lshl_add_u64 v[130:131], v[146:147], 0, v[158:159]
	v_lshl_add_u64 v[134:135], v[148:149], 0, v[158:159]
	global_load_dwordx4 v[138:141], v[130:131], off
	s_nop 0
	global_load_dwordx4 v[134:137], v[134:135], off

; #define PG8_STAGE(bufoff, gbase) do { _Pragma("unroll") for (int _i = 0; _i < 2; ++_i) \
;         __builtin_amdgcn_global_load_lds((const unsigned*)((const char*)(gbase) + voff[_i]), (LAS unsigned*)(lds + (bufoff) + ldsw + _i * 8192), 16, 0, 0); } while (0)
; #define PG8_LDA(dst, b, h) do { _Pragma("unroll") for (int m = 0; m < 4; ++m) _Pragma("unroll") for (int k = 0; k < 2; ++k) dst[m][k] = *(const LAS bf16x8*)(lds + PG8_SA(b, h) + aoff + m * 2048 + k * 1024); } while (0)
; #define PG8_LDB(dst, b, h) do { _Pragma("unroll") for (int n = 0; n < 2; ++n) _Pragma("unroll") for (int k = 0; k < 2; ++k) dst[n][k] = *(const LAS bf16x8*)(lds + PG8_SB(b, h) + boff + n * 2048 + k * 1024); } while (0)
; #define PG8_MMA(ai, bj, At, Bt) do { __builtin_amdgcn_s_setprio(1); _Pragma("unroll") for (int m = 0; m < 4; ++m) _Pragma("unroll") for (int n = 0; n < 2; ++n) _Pragma("unroll") for (int k = 0; k < 2; ++k) \
;         acc[ai][bj][m][n] = __builtin_amdgcn_mfma_f32_16x16x32_bf16(Bt[n][k], At[m][k], acc[ai][bj][m][n], 0, 0, 0); __builtin_amdgcn_s_setprio(0); } while (0)
; #define PG8_WAIT_V(n) asm volatile("s_waitcnt vmcnt(" #n ")" ::: "memory")
; #define PG8_WAIT_L(n) asm volatile("s_waitcnt lgkmcnt(" #n ")" ::: "memory")
; #define PG8_BAR __builtin_amdgcn_s_barrier()
; #define PG8_SCHED __builtin_amdgcn_sched_barrier(0)
; template <class Epi>
; DI void gemm_phase(LAS unsigned char* lds, const Gemm g, const StaticOrder& S, const Epi& E) {
;     ...
;         for (int t = 0; t < nt; t += 2) {
;             const bool last = (t == nt - 2);
;             const char* a1 = cA + (size_t)(t + 1) * kstep;
;             const char* a2 = last ? nA : cA + (size_t)(t + 2) * kstep; const char* b2 = last ? nB : cB + (size_t)(t + 2) * kstep;
;             const char* a3 = a2 + kstep; const char* b3 = b2 + kstep;
;             PG8_LDB(B0, 0, 0); PG8_SCHED; PG8_LDA(At, 0, 0); PG8_STAGE(PG8_SA(1, 1), a1 + hstep);
;             PG8_WAIT_L(8); PG8_BAR; PG8_WAIT_L(0); PG8_MMA(0, 0, At, B0); PG8_BAR; PG8_SCHED;
;             PG8_LDB(B1, 0, 1); PG8_STAGE(PG8_SB(0, 0), b2);
;             PG8_BAR; PG8_WAIT_L(0); PG8_MMA(0, 1, At, B1); PG8_BAR;
;             PG8_LDA(At, 0, 1); PG8_STAGE(PG8_SA(0, 0), a2);
;             PG8_BAR; PG8_WAIT_L(0); PG8_MMA(1, 0, At, B0); PG8_BAR; PG8_SCHED;
;             PG8_STAGE(PG8_SB(0, 1), b2 + hstep);
;             PG8_WAIT_V(6); PG8_BAR; PG8_MMA(1, 1, At, B1); PG8_BAR;
.LBB0_231:
	s_add_u32 s18, s16, 0xfff80080
	s_addc_u32 s19, s17, -1
	s_add_i32 s37, 0, 0x10000
	s_cmp_eq_u32 s36, 28
	s_cselect_b32 s21, s4, s19
	s_cselect_b32 s20, s5, s18
	s_cselect_b32 s19, s9, s35
	s_cselect_b32 s18, s11, s34
	s_add_i32 m0, s24, 0xc000
	s_nop 0
	global_load_lds_dwordx4 v130, s[16:17]
	s_add_i32 m0, s24, 0xe000
	s_nop 0
	global_load_lds_dwordx4 v132, s[16:17]
	ds_read_b128 v[138:141], v135
	ds_read_b128 v[142:145], v135 offset:1024
	ds_read_b128 v[146:149], v135 offset:2048
	ds_read_b128 v[150:153], v135 offset:3072
	ds_read_b128 v[186:189], v137
	ds_read_b128 v[190:193], v137 offset:1024
	ds_read_b128 v[194:197], v137 offset:2048
	ds_read_b128 v[198:201], v137 offset:3072
	ds_read_b128 v[202:205], v137 offset:4096
	ds_read_b128 v[206:209], v137 offset:5120
	ds_read_b128 v[210:213], v137 offset:6144
	ds_read_b128 v[214:217], v137 offset:7168
	s_waitcnt lgkmcnt(8)
	s_setprio 1
	s_barrier
	s_waitcnt lgkmcnt(0)
	v_mfma_f32_16x16x32_bf16 v[124:127], v[138:141], v[186:189], v[124:127]
	v_mfma_f32_16x16x32_bf16 v[120:123], v[146:149], v[186:189], v[120:123]
	v_mfma_f32_16x16x32_bf16 v[116:119], v[138:141], v[194:197], v[116:119]
	v_mfma_f32_16x16x32_bf16 v[112:115], v[146:149], v[194:197], v[112:115]
	v_mfma_f32_16x16x32_bf16 v[100:103], v[138:141], v[202:205], v[100:103]
	v_mfma_f32_16x16x32_bf16 v[96:99], v[146:149], v[202:205], v[96:99]
	v_mfma_f32_16x16x32_bf16 v[84:87], v[138:141], v[210:213], v[84:87]
	v_mfma_f32_16x16x32_bf16 v[80:83], v[146:149], v[210:213], v[80:83]
	v_mfma_f32_16x16x32_bf16 v[124:127], v[142:145], v[190:193], v[124:127]
	v_mfma_f32_16x16x32_bf16 v[120:123], v[150:153], v[190:193], v[120:123]
	v_mfma_f32_16x16x32_bf16 v[116:119], v[142:145], v[198:201], v[116:119]
	v_mfma_f32_16x16x32_bf16 v[112:115], v[150:153], v[198:201], v[112:115]
	v_mfma_f32_16x16x32_bf16 v[100:103], v[142:145], v[206:209], v[100:103]
	v_mfma_f32_16x16x32_bf16 v[96:99], v[150:153], v[206:209], v[96:99]
	v_mfma_f32_16x16x32_bf16 v[84:87], v[142:145], v[214:217], v[84:87]
	s_setprio 0
	v_mfma_f32_16x16x32_bf16 v[80:83], v[150:153], v[214:217], v[80:83]
	s_barrier
	s_add_i32 s40, 0, 0x14000
	s_add_i32 s37, s37, s23
	s_mov_b32 m0, s37
	s_nop 0
	global_load_lds_dwordx4 v158, s[18:19]
	s_add_i32 m0, s37, 0x2000
	s_nop 0
	global_load_lds_dwordx4 v128, s[18:19]
	ds_read_b128 v[226:229], v135 offset:16384
	ds_read_b128 v[230:233], v135 offset:17408
	ds_read_b128 v[234:237], v135 offset:18432
	ds_read_b128 v[238:241], v135 offset:19456
	s_waitcnt lgkmcnt(0)
	s_setprio 1
	s_barrier
	v_mfma_f32_16x16x32_bf16 v[108:111], v[226:229], v[186:189], v[108:111]
	v_mfma_f32_16x16x32_bf16 v[104:107], v[234:237], v[186:189], v[104:107]
	v_mfma_f32_16x16x32_bf16 v[92:95], v[226:229], v[194:197], v[92:95]
	v_mfma_f32_16x16x32_bf16 v[88:91], v[234:237], v[194:197], v[88:91]
	v_mfma_f32_16x16x32_bf16 v[76:79], v[226:229], v[202:205], v[76:79]
	v_mfma_f32_16x16x32_bf16 v[72:75], v[234:237], v[202:205], v[72:75]
	v_mfma_f32_16x16x32_bf16 v[68:71], v[226:229], v[210:213], v[68:71]
	v_mfma_f32_16x16x32_bf16 v[64:67], v[234:237], v[210:213], v[64:67]
	v_mfma_f32_16x16x32_bf16 v[108:111], v[230:233], v[190:193], v[108:111]
	s_mov_b32 m0, s24
	v_mfma_f32_16x16x32_bf16 v[104:107], v[238:241], v[190:193], v[104:107]
	s_mov_b64 s[100:101], s[20:21]
	v_mfma_f32_16x16x32_bf16 v[92:95], v[230:233], v[198:201], v[92:95]
	v_mfma_f32_16x16x32_bf16 v[88:91], v[238:241], v[198:201], v[88:91]
	v_mfma_f32_16x16x32_bf16 v[76:79], v[230:233], v[206:209], v[76:79]
	v_mfma_f32_16x16x32_bf16 v[72:75], v[238:241], v[206:209], v[72:75]
	v_mfma_f32_16x16x32_bf16 v[68:71], v[230:233], v[214:217], v[68:71]
	s_setprio 0
	v_mfma_f32_16x16x32_bf16 v[64:67], v[238:241], v[214:217], v[64:67]
	s_barrier
	global_load_lds_dwordx4 v158, s[20:21]
	s_mov_b64 s[100:101], s[20:21]
	s_mov_b32 m0, s25
	s_nop 0
	global_load_lds_dwordx4 v128, s[20:21]
	ds_read_b128 v[186:189], v137 offset:16384
	ds_read_b128 v[190:193], v137 offset:17408
	ds_read_b128 v[194:197], v137 offset:18432
	ds_read_b128 v[198:201], v137 offset:19456
	ds_read_b128 v[202:205], v137 offset:20480
	ds_read_b128 v[206:209], v137 offset:21504
	ds_read_b128 v[210:213], v137 offset:22528
	ds_read_b128 v[214:217], v137 offset:23552
	s_waitcnt lgkmcnt(0)
	s_setprio 1
	s_barrier
	v_mfma_f32_16x16x32_bf16 v[60:63], v[138:141], v[186:189], v[60:63]
	v_mfma_f32_16x16x32_bf16 v[56:59], v[146:149], v[186:189], v[56:59]
	v_mfma_f32_16x16x32_bf16 v[52:55], v[138:141], v[194:197], v[52:55]
	v_mfma_f32_16x16x32_bf16 v[48:51], v[146:149], v[194:197], v[48:51]
	v_mfma_f32_16x16x32_bf16 v[36:39], v[138:141], v[202:205], v[36:39]
	v_mfma_f32_16x16x32_bf16 v[32:35], v[146:149], v[202:205], v[32:35]
	v_mfma_f32_16x16x32_bf16 v[20:23], v[138:141], v[210:213], v[20:23]
	v_mfma_f32_16x16x32_bf16 v[16:19], v[146:149], v[210:213], v[16:19]
	v_mfma_f32_16x16x32_bf16 v[60:63], v[142:145], v[190:193], v[60:63]
	v_mfma_f32_16x16x32_bf16 v[56:59], v[150:153], v[190:193], v[56:59]
	v_mfma_f32_16x16x32_bf16 v[52:55], v[142:145], v[198:201], v[52:55]
	v_mfma_f32_16x16x32_bf16 v[48:51], v[150:153], v[198:201], v[48:51]
	v_mfma_f32_16x16x32_bf16 v[36:39], v[142:145], v[206:209], v[36:39]
	v_mfma_f32_16x16x32_bf16 v[32:35], v[150:153], v[206:209], v[32:35]
	v_mfma_f32_16x16x32_bf16 v[20:23], v[142:145], v[214:217], v[20:23]
	s_setprio 0
	v_mfma_f32_16x16x32_bf16 v[16:19], v[150:153], v[214:217], v[16:19]
	s_barrier
	s_add_u32 s38, s18, 0x80000
	s_addc_u32 s39, s19, 0
	s_add_i32 s37, s40, s23
	s_mov_b32 m0, s37
	s_nop 0
	global_load_lds_dwordx4 v158, s[38:39]
	s_add_i32 m0, s37, 0x2000
	s_nop 0
	global_load_lds_dwordx4 v128, s[38:39]
	s_waitcnt vmcnt(6)
	s_setprio 1
	s_barrier
; #define PG8_STAGE(bufoff, gbase) do { _Pragma("unroll") for (int _i = 0; _i < 2; ++_i) \
;         __builtin_amdgcn_global_load_lds((const unsigned*)((const char*)(gbase) + voff[_i]), (LAS unsigned*)(lds + (bufoff) + ldsw + _i * 8192), 16, 0, 0); } while (0)
; #define PG8_LDA(dst, b, h) do { _Pragma("unroll") for (int m = 0; m < 4; ++m) _Pragma("unroll") for (int k = 0; k < 2; ++k) dst[m][k] = *(const LAS bf16x8*)(lds + PG8_SA(b, h) + aoff + m * 2048 + k * 1024); } while (0)
; #define PG8_LDB(dst, b, h) do { _Pragma("unroll") for (int n = 0; n < 2; ++n) _Pragma("unroll") for (int k = 0; k < 2; ++k) dst[n][k] = *(const LAS bf16x8*)(lds + PG8_SB(b, h) + boff + n * 2048 + k * 1024); } while (0)
; #define PG8_MMA(ai, bj, At, Bt) do { __builtin_amdgcn_s_setprio(1); _Pragma("unroll") for (int m = 0; m < 4; ++m) _Pragma("unroll") for (int n = 0; n < 2; ++n) _Pragma("unroll") for (int k = 0; k < 2; ++k) \
;         acc[ai][bj][m][n] = __builtin_amdgcn_mfma_f32_16x16x32_bf16(Bt[n][k], At[m][k], acc[ai][bj][m][n], 0, 0, 0); __builtin_amdgcn_s_setprio(0); } while (0)
; #define PG8_WAIT_V(n) asm volatile("s_waitcnt vmcnt(" #n ")" ::: "memory")
; #define PG8_WAIT_L(n) asm volatile("s_waitcnt lgkmcnt(" #n ")" ::: "memory")
; #define PG8_BAR __builtin_amdgcn_s_barrier()
; #define PG8_SCHED __builtin_amdgcn_sched_barrier(0)
; template <class Epi>
; DI void gemm_phase(LAS unsigned char* lds, const Gemm g, const StaticOrder& S, const Epi& E) {
;     ...
;             PG8_WAIT_V(6); PG8_BAR; PG8_MMA(1, 1, At, B1); PG8_BAR;
;             PG8_LDB(B0, 1, 0); PG8_SCHED; PG8_LDA(At, 1, 0); PG8_STAGE(PG8_SA(0, 1), a2 + hstep);
;             PG8_WAIT_L(8); PG8_BAR; PG8_WAIT_L(0); PG8_MMA(0, 0, At, B0); PG8_BAR; PG8_SCHED;
;             PG8_LDB(B1, 1, 1); PG8_STAGE(PG8_SB(1, 0), b3);
;             PG8_BAR; PG8_WAIT_L(0); PG8_MMA(0, 1, At, B1); PG8_BAR;
;             PG8_LDA(At, 1, 1); PG8_STAGE(PG8_SA(1, 0), a3);
;             PG8_BAR; PG8_WAIT_L(0); PG8_MMA(1, 0, At, B0); PG8_BAR; PG8_SCHED;
	v_mfma_f32_16x16x32_bf16 v[44:47], v[226:229], v[186:189], v[44:47]
	v_mfma_f32_16x16x32_bf16 v[40:43], v[234:237], v[186:189], v[40:43]
	v_mfma_f32_16x16x32_bf16 v[28:31], v[226:229], v[194:197], v[28:31]
	v_mfma_f32_16x16x32_bf16 v[24:27], v[234:237], v[194:197], v[24:27]
	v_mfma_f32_16x16x32_bf16 v[12:15], v[226:229], v[202:205], v[12:15]
	v_mfma_f32_16x16x32_bf16 v[8:11], v[234:237], v[202:205], v[8:11]
	v_mfma_f32_16x16x32_bf16 v[4:7], v[226:229], v[210:213], v[4:7]
	v_mfma_f32_16x16x32_bf16 v[0:3], v[234:237], v[210:213], v[0:3]
	v_mfma_f32_16x16x32_bf16 v[44:47], v[230:233], v[190:193], v[44:47]
	s_add_i32 s37, 0, 0x18000
	v_mfma_f32_16x16x32_bf16 v[40:43], v[238:241], v[190:193], v[40:43]
	v_mfma_f32_16x16x32_bf16 v[28:31], v[230:233], v[198:201], v[28:31]
	v_mfma_f32_16x16x32_bf16 v[24:27], v[238:241], v[198:201], v[24:27]
	v_mfma_f32_16x16x32_bf16 v[12:15], v[230:233], v[206:209], v[12:15]
	v_mfma_f32_16x16x32_bf16 v[8:11], v[238:241], v[206:209], v[8:11]
	v_mfma_f32_16x16x32_bf16 v[4:7], v[230:233], v[214:217], v[4:7]
	s_setprio 0
	v_mfma_f32_16x16x32_bf16 v[0:3], v[238:241], v[214:217], v[0:3]
	s_barrier
	s_add_u32 s20, s20, 0x80000
	s_addc_u32 s21, s21, 0
	s_mov_b32 m0, s26
	s_nop 0
	global_load_lds_dwordx4 v158, s[20:21]
	s_mov_b32 m0, s27
	s_nop 0
	global_load_lds_dwordx4 v128, s[20:21]
	ds_read_b128 v[138:141], v135 offset:32768
	ds_read_b128 v[142:145], v135 offset:33792
	ds_read_b128 v[146:149], v135 offset:34816
	ds_read_b128 v[150:153], v135 offset:35840
	ds_read_b128 v[186:189], v137 offset:32768
	ds_read_b128 v[190:193], v137 offset:33792
	ds_read_b128 v[194:197], v137 offset:34816
	ds_read_b128 v[198:201], v137 offset:35840
	ds_read_b128 v[202:205], v137 offset:36864
	ds_read_b128 v[206:209], v137 offset:37888
	ds_read_b128 v[210:213], v137 offset:38912
	ds_read_b128 v[214:217], v137 offset:39936
	s_waitcnt lgkmcnt(8)
	s_setprio 1
	s_barrier
	s_waitcnt lgkmcnt(0)
	v_mfma_f32_16x16x32_bf16 v[124:127], v[138:141], v[186:189], v[124:127]
	v_mfma_f32_16x16x32_bf16 v[120:123], v[146:149], v[186:189], v[120:123]
	v_mfma_f32_16x16x32_bf16 v[116:119], v[138:141], v[194:197], v[116:119]
	v_mfma_f32_16x16x32_bf16 v[112:115], v[146:149], v[194:197], v[112:115]
	v_mfma_f32_16x16x32_bf16 v[100:103], v[138:141], v[202:205], v[100:103]
	v_mfma_f32_16x16x32_bf16 v[96:99], v[146:149], v[202:205], v[96:99]
	v_mfma_f32_16x16x32_bf16 v[84:87], v[138:141], v[210:213], v[84:87]
	v_mfma_f32_16x16x32_bf16 v[80:83], v[146:149], v[210:213], v[80:83]
	v_mfma_f32_16x16x32_bf16 v[124:127], v[142:145], v[190:193], v[124:127]
	v_mfma_f32_16x16x32_bf16 v[120:123], v[150:153], v[190:193], v[120:123]
	v_mfma_f32_16x16x32_bf16 v[116:119], v[142:145], v[198:201], v[116:119]
	v_mfma_f32_16x16x32_bf16 v[112:115], v[150:153], v[198:201], v[112:115]
	v_mfma_f32_16x16x32_bf16 v[100:103], v[142:145], v[206:209], v[100:103]
	v_mfma_f32_16x16x32_bf16 v[96:99], v[150:153], v[206:209], v[96:99]
	v_mfma_f32_16x16x32_bf16 v[84:87], v[142:145], v[214:217], v[84:87]
	s_setprio 0
	v_mfma_f32_16x16x32_bf16 v[80:83], v[150:153], v[214:217], v[80:83]
	s_barrier
	s_add_i32 s20, 0, 0x1c000
	s_add_i32 s21, s37, s23
	s_add_i32 m0, s21, 0xffffff80
	s_nop 0
	global_load_lds_dwordx4 v158, s[18:19] offset:128
	s_add_i32 m0, s21, 0x1f80
	s_nop 0
	global_load_lds_dwordx4 v128, s[18:19] offset:128
	ds_read_b128 v[226:229], v135 offset:49152
	ds_read_b128 v[230:233], v135 offset:50176
	ds_read_b128 v[234:237], v135 offset:51200
	ds_read_b128 v[238:241], v135 offset:52224
	s_waitcnt lgkmcnt(0)
	s_setprio 1
	s_barrier
	v_mfma_f32_16x16x32_bf16 v[108:111], v[226:229], v[186:189], v[108:111]
	v_mfma_f32_16x16x32_bf16 v[104:107], v[234:237], v[186:189], v[104:107]
	v_mfma_f32_16x16x32_bf16 v[92:95], v[226:229], v[194:197], v[92:95]
	v_mfma_f32_16x16x32_bf16 v[88:91], v[234:237], v[194:197], v[88:91]
	v_mfma_f32_16x16x32_bf16 v[76:79], v[226:229], v[202:205], v[76:79]
	v_mfma_f32_16x16x32_bf16 v[72:75], v[234:237], v[202:205], v[72:75]
	v_mfma_f32_16x16x32_bf16 v[68:71], v[226:229], v[210:213], v[68:71]
	v_mfma_f32_16x16x32_bf16 v[64:67], v[234:237], v[210:213], v[64:67]
	v_mfma_f32_16x16x32_bf16 v[108:111], v[230:233], v[190:193], v[108:111]
	s_add_i32 m0, s28, 0xffffff80
	v_mfma_f32_16x16x32_bf16 v[104:107], v[238:241], v[190:193], v[104:107]
	v_mfma_f32_16x16x32_bf16 v[92:95], v[230:233], v[198:201], v[92:95]
	v_mfma_f32_16x16x32_bf16 v[88:91], v[238:241], v[198:201], v[88:91]
	v_mfma_f32_16x16x32_bf16 v[76:79], v[230:233], v[206:209], v[76:79]
	v_mfma_f32_16x16x32_bf16 v[72:75], v[238:241], v[206:209], v[72:75]
	v_mfma_f32_16x16x32_bf16 v[68:71], v[230:233], v[214:217], v[68:71]
	s_setprio 0
	v_mfma_f32_16x16x32_bf16 v[64:67], v[238:241], v[214:217], v[64:67]
	s_barrier
	global_load_lds_dwordx4 v158, s[100:101] offset:128
	s_add_i32 m0, s29, 0xffffff80
	s_nop 0
	global_load_lds_dwordx4 v128, s[100:101] offset:128
	ds_read_b128 v[186:189], v137 offset:49152
	ds_read_b128 v[190:193], v137 offset:50176
	ds_read_b128 v[194:197], v137 offset:51200
	ds_read_b128 v[198:201], v137 offset:52224
	ds_read_b128 v[202:205], v137 offset:53248
	ds_read_b128 v[206:209], v137 offset:54272
	ds_read_b128 v[210:213], v137 offset:55296
	ds_read_b128 v[214:217], v137 offset:56320
	s_waitcnt lgkmcnt(0)
	s_setprio 1
	s_barrier
; #define PG8_STAGE(bufoff, gbase) do { _Pragma("unroll") for (int _i = 0; _i < 2; ++_i) \
;         __builtin_amdgcn_global_load_lds((const unsigned*)((const char*)(gbase) + voff[_i]), (LAS unsigned*)(lds + (bufoff) + ldsw + _i * 8192), 16, 0, 0); } while (0)
; #define PG8_MMA(ai, bj, At, Bt) do { __builtin_amdgcn_s_setprio(1); _Pragma("unroll") for (int m = 0; m < 4; ++m) _Pragma("unroll") for (int n = 0; n < 2; ++n) _Pragma("unroll") for (int k = 0; k < 2; ++k) \
;         acc[ai][bj][m][n] = __builtin_amdgcn_mfma_f32_16x16x32_bf16(Bt[n][k], At[m][k], acc[ai][bj][m][n], 0, 0, 0); __builtin_amdgcn_s_setprio(0); } while (0)
; #define PG8_WAIT_V(n) asm volatile("s_waitcnt vmcnt(" #n ")" ::: "memory")
; #define PG8_WAIT_L(n) asm volatile("s_waitcnt lgkmcnt(" #n ")" ::: "memory")
; #define PG8_BAR __builtin_amdgcn_s_barrier()
; #define PG8_SCHED __builtin_amdgcn_sched_barrier(0)
; template <class Epi>
; DI void gemm_phase(LAS unsigned char* lds, const Gemm g, const StaticOrder& S, const Epi& E) {
;     ...
;             PG8_BAR; PG8_WAIT_L(0); PG8_MMA(1, 0, At, B0); PG8_BAR; PG8_SCHED;
;             PG8_STAGE(PG8_SB(1, 1), b3 + hstep);
;             PG8_WAIT_V(6); PG8_BAR; PG8_MMA(1, 1, At, B1); PG8_BAR;
;         }
	v_mfma_f32_16x16x32_bf16 v[60:63], v[138:141], v[186:189], v[60:63]
	v_mfma_f32_16x16x32_bf16 v[56:59], v[146:149], v[186:189], v[56:59]
	v_mfma_f32_16x16x32_bf16 v[52:55], v[138:141], v[194:197], v[52:55]
	v_mfma_f32_16x16x32_bf16 v[48:51], v[146:149], v[194:197], v[48:51]
	v_mfma_f32_16x16x32_bf16 v[36:39], v[138:141], v[202:205], v[36:39]
	v_mfma_f32_16x16x32_bf16 v[32:35], v[146:149], v[202:205], v[32:35]
	v_mfma_f32_16x16x32_bf16 v[20:23], v[138:141], v[210:213], v[20:23]
	v_mfma_f32_16x16x32_bf16 v[16:19], v[146:149], v[210:213], v[16:19]
	v_mfma_f32_16x16x32_bf16 v[60:63], v[142:145], v[190:193], v[60:63]
	v_mfma_f32_16x16x32_bf16 v[56:59], v[150:153], v[190:193], v[56:59]
	v_mfma_f32_16x16x32_bf16 v[52:55], v[142:145], v[198:201], v[52:55]
	v_mfma_f32_16x16x32_bf16 v[48:51], v[150:153], v[198:201], v[48:51]
	v_mfma_f32_16x16x32_bf16 v[36:39], v[142:145], v[206:209], v[36:39]
	v_mfma_f32_16x16x32_bf16 v[32:35], v[150:153], v[206:209], v[32:35]
	v_mfma_f32_16x16x32_bf16 v[20:23], v[142:145], v[214:217], v[20:23]
	s_setprio 0
	v_mfma_f32_16x16x32_bf16 v[16:19], v[150:153], v[214:217], v[16:19]
	s_barrier
	s_add_u32 s18, s18, 0x80080
	s_addc_u32 s19, s19, 0
	s_add_i32 s20, s20, s23
	s_mov_b32 m0, s20
	s_nop 0
	global_load_lds_dwordx4 v158, s[18:19]
	s_add_i32 m0, s20, 0x2000
	s_nop 0
	global_load_lds_dwordx4 v128, s[18:19]
	s_waitcnt vmcnt(6)
	s_setprio 1
	s_barrier
	v_mfma_f32_16x16x32_bf16 v[44:47], v[226:229], v[186:189], v[44:47]
	v_mfma_f32_16x16x32_bf16 v[40:43], v[234:237], v[186:189], v[40:43]
	v_mfma_f32_16x16x32_bf16 v[28:31], v[226:229], v[194:197], v[28:31]
	v_mfma_f32_16x16x32_bf16 v[24:27], v[234:237], v[194:197], v[24:27]
	v_mfma_f32_16x16x32_bf16 v[12:15], v[226:229], v[202:205], v[12:15]
	v_mfma_f32_16x16x32_bf16 v[8:11], v[234:237], v[202:205], v[8:11]
	v_mfma_f32_16x16x32_bf16 v[4:7], v[226:229], v[210:213], v[4:7]
	v_mfma_f32_16x16x32_bf16 v[0:3], v[234:237], v[210:213], v[0:3]
	v_mfma_f32_16x16x32_bf16 v[44:47], v[230:233], v[190:193], v[44:47]
	s_add_i32 s36, s36, 2
	v_mfma_f32_16x16x32_bf16 v[40:43], v[238:241], v[190:193], v[40:43]
	s_add_u32 s16, s16, 0x100
	v_mfma_f32_16x16x32_bf16 v[28:31], v[230:233], v[198:201], v[28:31]
	s_addc_u32 s17, s17, 0
	v_mfma_f32_16x16x32_bf16 v[24:27], v[238:241], v[198:201], v[24:27]
	s_add_u32 s34, s34, 0x100
	v_mfma_f32_16x16x32_bf16 v[12:15], v[230:233], v[206:209], v[12:15]
	s_addc_u32 s35, s35, 0
	v_mfma_f32_16x16x32_bf16 v[8:11], v[238:241], v[206:209], v[8:11]
	s_cmp_gt_u32 s36, 29
	v_mfma_f32_16x16x32_bf16 v[4:7], v[230:233], v[214:217], v[4:7]
	s_setprio 0
	v_mfma_f32_16x16x32_bf16 v[0:3], v[238:241], v[214:217], v[0:3]
	s_barrier
	s_cbranch_scc0 .LBB0_231
; #define PG8_WAIT_V(n) asm volatile("s_waitcnt vmcnt(" #n ")" ::: "memory")
; #define PG8_BAR __builtin_amdgcn_s_barrier()
; template <class Epi>
; DI void gemm_phase(LAS unsigned char* lds, const Gemm g, const StaticOrder& S, const Epi& E) {
;     ...
;         E(acc, cur, wr, wc, fr, fq);
;         if (!has_next) break;
; #pragma unroll
;         for (int a = 0; a < 2; ++a)
; #pragma unroll
;             for (int b = 0; b < 2; ++b)
; #pragma unroll
;                 for (int m = 0; m < 4; ++m)
; #pragma unroll
;                     for (int n = 0; n < 2; ++n) acc[a][b][m][n] = (f32x4){0.f, 0.f, 0.f, 0.f};
;         cur = nxt; cA = nA; cB = nB; ++ui;
;     }
;     PG8_WAIT_V(0);
;     if (wr == 0) PG8_BAR;
;     PG8_BAR;
;     DI void operator()(const f32x4 (&acc)[2][2][4][2], const Unit& u, int wr, int wc, int fr, int fq) const {
;         const int row0 = u.pm * BM + wr * 64 + fr, col0 = u.pn * BM + wc * 32 + 8 * fq;
; #pragma unroll
;         for (int ai = 0; ai < 2; ++ai)
; #pragma unroll
;             for (int m = 0; m < 4; ++m) { u16* rowp = O + (size_t)(row0 + ai * HALF + m * 16) * ldc + col0;
; #pragma unroll
;                 for (int bj = 0; bj < 2; ++bj) { const f32x4 v0 = acc[ai][bj][m][0], v1 = acc[ai][bj][m][1];
;                     *(u32x4*)(rowp + bj * HALF) = (u32x4){pk(v0[0], v0[1]), pk(v0[2], v0[3]), pk(v1[0], v1[1]), pk(v1[2], v1[3])}; } }
	v_lshl_add_u32 v144, s33, 8, v134
	v_lshl_or_b32 v138, s31, 8, v136
	v_ashrrev_i32_e32 v139, 31, v138
	v_mov_b64_e32 v[140:141], s[50:51]
	s_movk_i32 s9, 0x3000
	v_cvt_pk_bf16_f32 v68, v68, v69
	v_cvt_pk_bf16_f32 v69, v70, v71
	v_cvt_pk_bf16_f32 v70, v64, v65
	v_add_u32_e32 v64, 0x80, v144
	v_mad_i64_i32 v[142:143], s[4:5], v144, s9, v[140:141]
	v_lshlrev_b64 v[138:139], 1, v[138:139]
	v_cvt_pk_bf16_f32 v108, v108, v109
	v_cvt_pk_bf16_f32 v109, v110, v111
	v_cvt_pk_bf16_f32 v110, v104, v105
	v_or_b32_e32 v104, 16, v144
	v_mad_i64_i32 v[64:65], s[4:5], v64, s9, v[140:141]
	v_cvt_pk_bf16_f32 v44, v44, v45
	v_cvt_pk_bf16_f32 v45, v46, v47
	v_cvt_pk_bf16_f32 v46, v40, v41
	v_add_u32_e32 v40, 0x90, v144
	v_lshl_add_u64 v[142:143], v[142:143], 0, v[138:139]
	v_cvt_pk_bf16_f32 v111, v106, v107
	v_mad_i64_i32 v[104:105], s[4:5], v104, s9, v[140:141]
	v_cvt_pk_bf16_f32 v92, v92, v93
	v_cvt_pk_bf16_f32 v93, v94, v95
	v_cvt_pk_bf16_f32 v94, v88, v89
	v_or_b32_e32 v88, 32, v144
	v_lshl_add_u64 v[64:65], v[64:65], 0, v[138:139]
	v_cvt_pk_bf16_f32 v47, v42, v43
	v_mad_i64_i32 v[40:41], s[4:5], v40, s9, v[140:141]
	v_cvt_pk_bf16_f32 v28, v28, v29
	v_cvt_pk_bf16_f32 v29, v30, v31
	v_cvt_pk_bf16_f32 v30, v24, v25
	v_add_u32_e32 v24, 0xa0, v144
	global_store_dwordx4 v[142:143], v[108:111], off offset:256
	v_cvt_pk_bf16_f32 v95, v90, v91
	v_mad_i64_i32 v[88:89], s[4:5], v88, s9, v[140:141]
	v_lshl_add_u64 v[108:109], v[104:105], 0, v[138:139]
	v_cvt_pk_bf16_f32 v76, v76, v77
	v_cvt_pk_bf16_f32 v77, v78, v79
	v_cvt_pk_bf16_f32 v78, v72, v73
	v_or_b32_e32 v72, 48, v144
	global_store_dwordx4 v[64:65], v[44:47], off offset:256
	v_cvt_pk_bf16_f32 v31, v26, v27
	v_mad_i64_i32 v[24:25], s[4:5], v24, s9, v[140:141]
	v_lshl_add_u64 v[44:45], v[40:41], 0, v[138:139]
	v_cvt_pk_bf16_f32 v12, v12, v13
	v_cvt_pk_bf16_f32 v13, v14, v15
	v_cvt_pk_bf16_f32 v14, v8, v9
	v_add_u32_e32 v8, 0xb0, v144
	global_store_dwordx4 v[108:109], v[92:95], off offset:256
	v_cvt_pk_bf16_f32 v79, v74, v75
	v_mad_i64_i32 v[72:73], s[4:5], v72, s9, v[140:141]
	v_lshl_add_u64 v[92:93], v[88:89], 0, v[138:139]
	global_store_dwordx4 v[44:45], v[28:31], off offset:256
	v_cvt_pk_bf16_f32 v15, v10, v11
	v_mad_i64_i32 v[8:9], s[4:5], v8, s9, v[140:141]
	v_lshl_add_u64 v[28:29], v[24:25], 0, v[138:139]
	v_cvt_pk_bf16_f32 v124, v124, v125
	v_cvt_pk_bf16_f32 v125, v126, v127
	v_cvt_pk_bf16_f32 v126, v120, v121
	v_cvt_pk_bf16_f32 v127, v122, v123
	v_cvt_pk_bf16_f32 v104, v116, v117
	v_cvt_pk_bf16_f32 v105, v118, v119
	v_cvt_pk_bf16_f32 v106, v112, v113
	v_cvt_pk_bf16_f32 v107, v114, v115
	v_cvt_pk_bf16_f32 v88, v100, v101
	v_cvt_pk_bf16_f32 v89, v102, v103
	v_cvt_pk_bf16_f32 v90, v96, v97
	v_cvt_pk_bf16_f32 v91, v98, v99
	global_store_dwordx4 v[92:93], v[76:79], off offset:256
	v_cvt_pk_bf16_f32 v74, v80, v81
	v_cvt_pk_bf16_f32 v75, v82, v83
	v_lshl_add_u64 v[76:77], v[72:73], 0, v[138:139]
	v_cvt_pk_bf16_f32 v72, v84, v85
	v_cvt_pk_bf16_f32 v73, v86, v87
	v_cvt_pk_bf16_f32 v71, v66, v67
	v_cvt_pk_bf16_f32 v60, v60, v61
	v_cvt_pk_bf16_f32 v61, v62, v63
	v_cvt_pk_bf16_f32 v62, v56, v57
	v_cvt_pk_bf16_f32 v63, v58, v59
	v_cvt_pk_bf16_f32 v40, v52, v53
	v_cvt_pk_bf16_f32 v41, v54, v55
	v_cvt_pk_bf16_f32 v42, v48, v49
	v_cvt_pk_bf16_f32 v43, v50, v51
	v_cvt_pk_bf16_f32 v24, v36, v37
	v_cvt_pk_bf16_f32 v25, v38, v39
	v_cvt_pk_bf16_f32 v26, v32, v33
	v_cvt_pk_bf16_f32 v27, v34, v35
	global_store_dwordx4 v[28:29], v[12:15], off offset:256
	v_cvt_pk_bf16_f32 v10, v16, v17
	v_cvt_pk_bf16_f32 v11, v18, v19
	v_lshl_add_u64 v[12:13], v[8:9], 0, v[138:139]
	v_cvt_pk_bf16_f32 v8, v20, v21
	v_cvt_pk_bf16_f32 v9, v22, v23
	v_cvt_pk_bf16_f32 v4, v4, v5
	v_cvt_pk_bf16_f32 v5, v6, v7
	v_cvt_pk_bf16_f32 v6, v0, v1
	v_cvt_pk_bf16_f32 v7, v2, v3
	s_and_b64 vcc, exec, s[6:7]
	s_mov_b32 s31, s8
	s_mov_b32 s33, s10
	s_mov_b64 s[18:19], s[14:15]
	s_mov_b64 s[16:17], s[12:13]
	global_store_dwordx4 v[142:143], v[124:127], off
	global_store_dwordx4 v[108:109], v[104:107], off
	global_store_dwordx4 v[92:93], v[88:91], off
	global_store_dwordx4 v[76:77], v[72:75], off
	global_store_dwordx4 v[76:77], v[68:71], off offset:256
	global_store_dwordx4 v[64:65], v[60:63], off
	global_store_dwordx4 v[44:45], v[40:43], off
	global_store_dwordx4 v[28:29], v[24:27], off
	global_store_dwordx4 v[12:13], v[8:11], off
	global_store_dwordx4 v[12:13], v[4:7], off offset:256
	s_cbranch_vccz .LBB0_228
	s_waitcnt vmcnt(0)
	s_cmpk_gt_u32 s2, 0xff
	s_cbranch_scc1 .LBB0_235
	s_barrier

; #define PG8_STAGE(bufoff, gbase) do { _Pragma("unroll") for (int _i = 0; _i < 2; ++_i) \
;         __builtin_amdgcn_global_load_lds((const unsigned*)((const char*)(gbase) + voff[_i]), (LAS unsigned*)(lds + (bufoff) + ldsw + _i * 8192), 16, 0, 0); } while (0)
; #define PG8_LDA(dst, b, h) do { _Pragma("unroll") for (int m = 0; m < 4; ++m) _Pragma("unroll") for (int k = 0; k < 2; ++k) dst[m][k] = *(const LAS bf16x8*)(lds + PG8_SA(b, h) + aoff + m * 2048 + k * 1024); } while (0)
; #define PG8_LDB(dst, b, h) do { _Pragma("unroll") for (int n = 0; n < 2; ++n) _Pragma("unroll") for (int k = 0; k < 2; ++k) dst[n][k] = *(const LAS bf16x8*)(lds + PG8_SB(b, h) + boff + n * 2048 + k * 1024); } while (0)
; #define PG8_MMA(ai, bj, At, Bt) do { __builtin_amdgcn_s_setprio(1); _Pragma("unroll") for (int m = 0; m < 4; ++m) _Pragma("unroll") for (int n = 0; n < 2; ++n) _Pragma("unroll") for (int k = 0; k < 2; ++k) \
;         acc[ai][bj][m][n] = __builtin_amdgcn_mfma_f32_16x16x32_bf16(Bt[n][k], At[m][k], acc[ai][bj][m][n], 0, 0, 0); __builtin_amdgcn_s_setprio(0); } while (0)
; #define PG8_WAIT_V(n) asm volatile("s_waitcnt vmcnt(" #n ")" ::: "memory")
; #define PG8_WAIT_L(n) asm volatile("s_waitcnt lgkmcnt(" #n ")" ::: "memory")
; #define PG8_BAR __builtin_amdgcn_s_barrier()
; #define PG8_SCHED __builtin_amdgcn_sched_barrier(0)
; template <class Epi>
; DI void gemm_phase(LAS unsigned char* lds, const Gemm g, const StaticOrder& S, const Epi& E) {
;     ...
;         for (int t = 0; t < nt; t += 2) {
;             const bool last = (t == nt - 2);
;             const char* a1 = cA + (size_t)(t + 1) * kstep;
;             const char* a2 = last ? nA : cA + (size_t)(t + 2) * kstep; const char* b2 = last ? nB : cB + (size_t)(t + 2) * kstep;
;             const char* a3 = a2 + kstep; const char* b3 = b2 + kstep;
;             PG8_LDB(B0, 0, 0); PG8_SCHED; PG8_LDA(At, 0, 0); PG8_STAGE(PG8_SA(1, 1), a1 + hstep);
;             PG8_WAIT_L(8); PG8_BAR; PG8_WAIT_L(0); PG8_MMA(0, 0, At, B0); PG8_BAR; PG8_SCHED;
;             PG8_LDB(B1, 0, 1); PG8_STAGE(PG8_SB(0, 0), b2);
;             PG8_BAR; PG8_WAIT_L(0); PG8_MMA(0, 1, At, B1); PG8_BAR;
;             PG8_LDA(At, 0, 1); PG8_STAGE(PG8_SA(0, 0), a2);
;             PG8_BAR; PG8_WAIT_L(0); PG8_MMA(1, 0, At, B0); PG8_BAR; PG8_SCHED;
;             PG8_STAGE(PG8_SB(0, 1), b2 + hstep);
;             PG8_WAIT_V(6); PG8_BAR; PG8_MMA(1, 1, At, B1); PG8_BAR;
.LBB0_320:
	s_add_u32 s26, s24, 0x100
	s_addc_u32 s27, s25, 0
	s_add_i32 s47, 0, 0x10000
	s_cmp_eq_u32 s46, 28
	s_cselect_b32 s31, s4, s27
	s_cselect_b32 s30, s5, s26
	s_cselect_b32 s29, s9, s45
	s_cselect_b32 s28, s11, s33
	v_lshl_add_u64 v[214:215], s[24:25], 0, v[190:191]
	s_add_i32 m0, s38, 0xc000
	s_nop 0
	global_load_lds_dwordx4 v[214:215], off
	v_lshl_add_u64 v[214:215], s[24:25], 0, v[192:193]
	s_add_i32 m0, s38, 0xe000
	s_nop 0
	global_load_lds_dwordx4 v[214:215], off
	ds_read_b128 v[128:131], v226
	ds_read_b128 v[132:135], v226 offset:1024
	ds_read_b128 v[136:139], v226 offset:2048
	ds_read_b128 v[140:143], v226 offset:3072
	ds_read_b128 v[144:147], v228
	ds_read_b128 v[148:151], v228 offset:1024
	ds_read_b128 v[152:155], v228 offset:2048
	ds_read_b128 v[194:197], v228 offset:3072
	ds_read_b128 v[198:201], v228 offset:4096
	ds_read_b128 v[202:205], v228 offset:5120
	ds_read_b128 v[206:209], v228 offset:6144
	ds_read_b128 v[210:213], v228 offset:7168
	s_waitcnt lgkmcnt(8)
	s_setprio 1
	s_barrier
	s_waitcnt lgkmcnt(0)
	v_mfma_f32_16x16x32_bf16 v[124:127], v[128:131], v[144:147], v[124:127]
	v_mfma_f32_16x16x32_bf16 v[120:123], v[136:139], v[144:147], v[120:123]
	v_mfma_f32_16x16x32_bf16 v[116:119], v[128:131], v[152:155], v[116:119]
	v_mfma_f32_16x16x32_bf16 v[112:115], v[136:139], v[152:155], v[112:115]
	v_mfma_f32_16x16x32_bf16 v[108:111], v[128:131], v[198:201], v[108:111]
	v_mfma_f32_16x16x32_bf16 v[104:107], v[136:139], v[198:201], v[104:107]
	v_mfma_f32_16x16x32_bf16 v[100:103], v[128:131], v[206:209], v[100:103]
	v_mfma_f32_16x16x32_bf16 v[96:99], v[136:139], v[206:209], v[96:99]
	v_mfma_f32_16x16x32_bf16 v[124:127], v[132:135], v[148:151], v[124:127]
	v_mfma_f32_16x16x32_bf16 v[120:123], v[140:143], v[148:151], v[120:123]
	v_mfma_f32_16x16x32_bf16 v[116:119], v[132:135], v[194:197], v[116:119]
	v_mfma_f32_16x16x32_bf16 v[112:115], v[140:143], v[194:197], v[112:115]
	v_mfma_f32_16x16x32_bf16 v[108:111], v[132:135], v[202:205], v[108:111]
	v_mfma_f32_16x16x32_bf16 v[104:107], v[140:143], v[202:205], v[104:107]
	v_mfma_f32_16x16x32_bf16 v[100:103], v[132:135], v[210:213], v[100:103]
	s_setprio 0
	v_mfma_f32_16x16x32_bf16 v[96:99], v[140:143], v[210:213], v[96:99]
	s_barrier
	s_add_i32 s48, 0, 0x14000
	s_add_i32 s24, s47, s37
	s_mov_b32 m0, s24
	s_nop 0
	global_load_lds_dwordx4 v188, s[28:29]
	s_add_i32 m0, s24, 0x2000
	s_nop 0
	global_load_lds_dwordx4 v186, s[28:29]
	ds_read_b128 v[214:217], v226 offset:16384
	ds_read_b128 v[230:233], v226 offset:17408
	ds_read_b128 v[234:237], v226 offset:18432
	ds_read_b128 v[238:241], v226 offset:19456
	s_waitcnt lgkmcnt(0)
	s_setprio 1
	s_barrier
	v_mfma_f32_16x16x32_bf16 v[60:63], v[214:217], v[144:147], v[60:63]
	v_mfma_f32_16x16x32_bf16 v[56:59], v[234:237], v[144:147], v[56:59]
	v_mfma_f32_16x16x32_bf16 v[52:55], v[214:217], v[152:155], v[52:55]
	v_mfma_f32_16x16x32_bf16 v[48:51], v[234:237], v[152:155], v[48:51]
	v_mfma_f32_16x16x32_bf16 v[44:47], v[214:217], v[198:201], v[44:47]
	v_mfma_f32_16x16x32_bf16 v[40:43], v[234:237], v[198:201], v[40:43]
	v_mfma_f32_16x16x32_bf16 v[36:39], v[214:217], v[206:209], v[36:39]
	v_mfma_f32_16x16x32_bf16 v[32:35], v[234:237], v[206:209], v[32:35]
	v_mfma_f32_16x16x32_bf16 v[60:63], v[230:233], v[148:151], v[60:63]
	s_mov_b32 m0, s38
	v_mfma_f32_16x16x32_bf16 v[56:59], v[238:241], v[148:151], v[56:59]
	s_mov_b64 s[100:101], s[30:31]
	v_mfma_f32_16x16x32_bf16 v[52:55], v[230:233], v[194:197], v[52:55]
	v_mfma_f32_16x16x32_bf16 v[48:51], v[238:241], v[194:197], v[48:51]
	v_mfma_f32_16x16x32_bf16 v[44:47], v[230:233], v[202:205], v[44:47]
	v_mfma_f32_16x16x32_bf16 v[40:43], v[238:241], v[202:205], v[40:43]
	v_mfma_f32_16x16x32_bf16 v[36:39], v[230:233], v[210:213], v[36:39]
	s_setprio 0
	v_mfma_f32_16x16x32_bf16 v[32:35], v[238:241], v[210:213], v[32:35]
	s_barrier
	global_load_lds_dwordx4 v188, s[30:31]
	s_mov_b64 s[100:101], s[30:31]
	s_mov_b32 m0, s39
	s_nop 0
	global_load_lds_dwordx4 v186, s[30:31]
	ds_read_b128 v[144:147], v228 offset:16384
	ds_read_b128 v[148:151], v228 offset:17408
	ds_read_b128 v[152:155], v228 offset:18432
	ds_read_b128 v[194:197], v228 offset:19456
	ds_read_b128 v[198:201], v228 offset:20480
	ds_read_b128 v[202:205], v228 offset:21504
	ds_read_b128 v[206:209], v228 offset:22528
	ds_read_b128 v[210:213], v228 offset:23552
	s_waitcnt lgkmcnt(0)
	s_setprio 1
	s_barrier
	v_mfma_f32_16x16x32_bf16 v[92:95], v[128:131], v[144:147], v[92:95]
	v_mfma_f32_16x16x32_bf16 v[88:91], v[136:139], v[144:147], v[88:91]
	v_mfma_f32_16x16x32_bf16 v[84:87], v[128:131], v[152:155], v[84:87]
	v_mfma_f32_16x16x32_bf16 v[80:83], v[136:139], v[152:155], v[80:83]
	v_mfma_f32_16x16x32_bf16 v[76:79], v[128:131], v[198:201], v[76:79]
	v_mfma_f32_16x16x32_bf16 v[72:75], v[136:139], v[198:201], v[72:75]
	v_mfma_f32_16x16x32_bf16 v[68:71], v[128:131], v[206:209], v[68:71]
	v_mfma_f32_16x16x32_bf16 v[64:67], v[136:139], v[206:209], v[64:67]
	v_mfma_f32_16x16x32_bf16 v[92:95], v[132:135], v[148:151], v[92:95]
	v_mfma_f32_16x16x32_bf16 v[88:91], v[140:143], v[148:151], v[88:91]
	v_mfma_f32_16x16x32_bf16 v[84:87], v[132:135], v[194:197], v[84:87]
	v_mfma_f32_16x16x32_bf16 v[80:83], v[140:143], v[194:197], v[80:83]
	v_mfma_f32_16x16x32_bf16 v[76:79], v[132:135], v[202:205], v[76:79]
	v_mfma_f32_16x16x32_bf16 v[72:75], v[140:143], v[202:205], v[72:75]
	v_mfma_f32_16x16x32_bf16 v[68:71], v[132:135], v[210:213], v[68:71]
	s_setprio 0
	v_mfma_f32_16x16x32_bf16 v[64:67], v[140:143], v[210:213], v[64:67]
	s_barrier
	s_add_u32 s24, s28, 0x80000
	s_addc_u32 s25, s29, 0
	s_add_i32 s47, s48, s37
	s_mov_b32 m0, s47
	s_nop 0
	global_load_lds_dwordx4 v188, s[24:25]
	s_add_i32 m0, s47, 0x2000
	s_nop 0
	global_load_lds_dwordx4 v186, s[24:25]
	s_waitcnt vmcnt(6)
	s_setprio 1
	s_barrier
; #define PG8_STAGE(bufoff, gbase) do { _Pragma("unroll") for (int _i = 0; _i < 2; ++_i) \
;         __builtin_amdgcn_global_load_lds((const unsigned*)((const char*)(gbase) + voff[_i]), (LAS unsigned*)(lds + (bufoff) + ldsw + _i * 8192), 16, 0, 0); } while (0)
; #define PG8_LDA(dst, b, h) do { _Pragma("unroll") for (int m = 0; m < 4; ++m) _Pragma("unroll") for (int k = 0; k < 2; ++k) dst[m][k] = *(const LAS bf16x8*)(lds + PG8_SA(b, h) + aoff + m * 2048 + k * 1024); } while (0)
; #define PG8_LDB(dst, b, h) do { _Pragma("unroll") for (int n = 0; n < 2; ++n) _Pragma("unroll") for (int k = 0; k < 2; ++k) dst[n][k] = *(const LAS bf16x8*)(lds + PG8_SB(b, h) + boff + n * 2048 + k * 1024); } while (0)
; #define PG8_MMA(ai, bj, At, Bt) do { __builtin_amdgcn_s_setprio(1); _Pragma("unroll") for (int m = 0; m < 4; ++m) _Pragma("unroll") for (int n = 0; n < 2; ++n) _Pragma("unroll") for (int k = 0; k < 2; ++k) \
;         acc[ai][bj][m][n] = __builtin_amdgcn_mfma_f32_16x16x32_bf16(Bt[n][k], At[m][k], acc[ai][bj][m][n], 0, 0, 0); __builtin_amdgcn_s_setprio(0); } while (0)
; #define PG8_WAIT_V(n) asm volatile("s_waitcnt vmcnt(" #n ")" ::: "memory")
; #define PG8_WAIT_L(n) asm volatile("s_waitcnt lgkmcnt(" #n ")" ::: "memory")
; #define PG8_BAR __builtin_amdgcn_s_barrier()
; #define PG8_SCHED __builtin_amdgcn_sched_barrier(0)
; template <class Epi>
; DI void gemm_phase(LAS unsigned char* lds, const Gemm g, const StaticOrder& S, const Epi& E) {
;     ...
;             PG8_WAIT_V(6); PG8_BAR; PG8_MMA(1, 1, At, B1); PG8_BAR;
;             PG8_LDB(B0, 1, 0); PG8_SCHED; PG8_LDA(At, 1, 0); PG8_STAGE(PG8_SA(0, 1), a2 + hstep);
;             PG8_WAIT_L(8); PG8_BAR; PG8_WAIT_L(0); PG8_MMA(0, 0, At, B0); PG8_BAR; PG8_SCHED;
;             PG8_LDB(B1, 1, 1); PG8_STAGE(PG8_SB(1, 0), b3);
;             PG8_BAR; PG8_WAIT_L(0); PG8_MMA(0, 1, At, B1); PG8_BAR;
;             PG8_LDA(At, 1, 1); PG8_STAGE(PG8_SA(1, 0), a3);
;             PG8_BAR; PG8_WAIT_L(0); PG8_MMA(1, 0, At, B0); PG8_BAR; PG8_SCHED;
	v_mfma_f32_16x16x32_bf16 v[28:31], v[214:217], v[144:147], v[28:31]
	v_mfma_f32_16x16x32_bf16 v[24:27], v[234:237], v[144:147], v[24:27]
	v_mfma_f32_16x16x32_bf16 v[20:23], v[214:217], v[152:155], v[20:23]
	v_mfma_f32_16x16x32_bf16 v[16:19], v[234:237], v[152:155], v[16:19]
	v_mfma_f32_16x16x32_bf16 v[12:15], v[214:217], v[198:201], v[12:15]
	v_mfma_f32_16x16x32_bf16 v[8:11], v[234:237], v[198:201], v[8:11]
	v_mfma_f32_16x16x32_bf16 v[4:7], v[214:217], v[206:209], v[4:7]
	v_mfma_f32_16x16x32_bf16 v[0:3], v[234:237], v[206:209], v[0:3]
	v_mfma_f32_16x16x32_bf16 v[28:31], v[230:233], v[148:151], v[28:31]
	s_add_i32 s47, 0, 0x18000
	v_mfma_f32_16x16x32_bf16 v[24:27], v[238:241], v[148:151], v[24:27]
	v_mfma_f32_16x16x32_bf16 v[20:23], v[230:233], v[194:197], v[20:23]
	v_mfma_f32_16x16x32_bf16 v[16:19], v[238:241], v[194:197], v[16:19]
	v_mfma_f32_16x16x32_bf16 v[12:15], v[230:233], v[202:205], v[12:15]
	v_mfma_f32_16x16x32_bf16 v[8:11], v[238:241], v[202:205], v[8:11]
	v_mfma_f32_16x16x32_bf16 v[4:7], v[230:233], v[210:213], v[4:7]
	s_setprio 0
	v_mfma_f32_16x16x32_bf16 v[0:3], v[238:241], v[210:213], v[0:3]
	s_barrier
	s_add_u32 s24, s30, 0x80000
	s_addc_u32 s25, s31, 0
	s_mov_b32 m0, s40
	s_nop 0
	global_load_lds_dwordx4 v188, s[24:25]
	s_mov_b32 m0, s41
	s_nop 0
	global_load_lds_dwordx4 v186, s[24:25]
	ds_read_b128 v[128:131], v226 offset:32768
	ds_read_b128 v[132:135], v226 offset:33792
	ds_read_b128 v[136:139], v226 offset:34816
	ds_read_b128 v[140:143], v226 offset:35840
	ds_read_b128 v[144:147], v228 offset:32768
	ds_read_b128 v[148:151], v228 offset:33792
	ds_read_b128 v[152:155], v228 offset:34816
	ds_read_b128 v[194:197], v228 offset:35840
	ds_read_b128 v[198:201], v228 offset:36864
	ds_read_b128 v[202:205], v228 offset:37888
	ds_read_b128 v[206:209], v228 offset:38912
	ds_read_b128 v[210:213], v228 offset:39936
	s_waitcnt lgkmcnt(8)
	s_setprio 1
	s_barrier
	s_waitcnt lgkmcnt(0)
	v_mfma_f32_16x16x32_bf16 v[124:127], v[128:131], v[144:147], v[124:127]
	v_mfma_f32_16x16x32_bf16 v[120:123], v[136:139], v[144:147], v[120:123]
	v_mfma_f32_16x16x32_bf16 v[116:119], v[128:131], v[152:155], v[116:119]
	v_mfma_f32_16x16x32_bf16 v[112:115], v[136:139], v[152:155], v[112:115]
	v_mfma_f32_16x16x32_bf16 v[108:111], v[128:131], v[198:201], v[108:111]
	v_mfma_f32_16x16x32_bf16 v[104:107], v[136:139], v[198:201], v[104:107]
	v_mfma_f32_16x16x32_bf16 v[100:103], v[128:131], v[206:209], v[100:103]
	v_mfma_f32_16x16x32_bf16 v[96:99], v[136:139], v[206:209], v[96:99]
	v_mfma_f32_16x16x32_bf16 v[124:127], v[132:135], v[148:151], v[124:127]
	v_mfma_f32_16x16x32_bf16 v[120:123], v[140:143], v[148:151], v[120:123]
	v_mfma_f32_16x16x32_bf16 v[116:119], v[132:135], v[194:197], v[116:119]
	v_mfma_f32_16x16x32_bf16 v[112:115], v[140:143], v[194:197], v[112:115]
	v_mfma_f32_16x16x32_bf16 v[108:111], v[132:135], v[202:205], v[108:111]
	v_mfma_f32_16x16x32_bf16 v[104:107], v[140:143], v[202:205], v[104:107]
	v_mfma_f32_16x16x32_bf16 v[100:103], v[132:135], v[210:213], v[100:103]
	s_setprio 0
	v_mfma_f32_16x16x32_bf16 v[96:99], v[140:143], v[210:213], v[96:99]
	s_barrier
	s_add_i32 s30, 0, 0x1c000
	s_add_i32 s24, s47, s37
	s_add_i32 m0, s24, 0xffffff80
	s_nop 0
	global_load_lds_dwordx4 v188, s[28:29] offset:128
	s_add_i32 m0, s24, 0x1f80
	s_nop 0
	global_load_lds_dwordx4 v186, s[28:29] offset:128
	ds_read_b128 v[214:217], v226 offset:49152
	ds_read_b128 v[230:233], v226 offset:50176
	ds_read_b128 v[234:237], v226 offset:51200
	ds_read_b128 v[238:241], v226 offset:52224
	s_waitcnt lgkmcnt(0)
	s_setprio 1
	s_barrier
	v_mfma_f32_16x16x32_bf16 v[60:63], v[214:217], v[144:147], v[60:63]
	v_mfma_f32_16x16x32_bf16 v[56:59], v[234:237], v[144:147], v[56:59]
	v_mfma_f32_16x16x32_bf16 v[52:55], v[214:217], v[152:155], v[52:55]
	v_mfma_f32_16x16x32_bf16 v[48:51], v[234:237], v[152:155], v[48:51]
	v_mfma_f32_16x16x32_bf16 v[44:47], v[214:217], v[198:201], v[44:47]
	v_mfma_f32_16x16x32_bf16 v[40:43], v[234:237], v[198:201], v[40:43]
	v_mfma_f32_16x16x32_bf16 v[36:39], v[214:217], v[206:209], v[36:39]
	v_mfma_f32_16x16x32_bf16 v[32:35], v[234:237], v[206:209], v[32:35]
	v_mfma_f32_16x16x32_bf16 v[60:63], v[230:233], v[148:151], v[60:63]
	s_add_i32 m0, s42, 0xffffff80
	v_mfma_f32_16x16x32_bf16 v[56:59], v[238:241], v[148:151], v[56:59]
	v_mfma_f32_16x16x32_bf16 v[52:55], v[230:233], v[194:197], v[52:55]
	v_mfma_f32_16x16x32_bf16 v[48:51], v[238:241], v[194:197], v[48:51]
	v_mfma_f32_16x16x32_bf16 v[44:47], v[230:233], v[202:205], v[44:47]
	v_mfma_f32_16x16x32_bf16 v[40:43], v[238:241], v[202:205], v[40:43]
	v_mfma_f32_16x16x32_bf16 v[36:39], v[230:233], v[210:213], v[36:39]
	s_setprio 0
	v_mfma_f32_16x16x32_bf16 v[32:35], v[238:241], v[210:213], v[32:35]
	s_barrier
	global_load_lds_dwordx4 v188, s[100:101] offset:128
	s_add_i32 m0, s43, 0xffffff80
	s_nop 0
	global_load_lds_dwordx4 v186, s[100:101] offset:128
	ds_read_b128 v[144:147], v228 offset:49152
	ds_read_b128 v[148:151], v228 offset:50176
	ds_read_b128 v[152:155], v228 offset:51200
	ds_read_b128 v[194:197], v228 offset:52224
	ds_read_b128 v[198:201], v228 offset:53248
	ds_read_b128 v[202:205], v228 offset:54272
	ds_read_b128 v[206:209], v228 offset:55296
	ds_read_b128 v[210:213], v228 offset:56320
	s_waitcnt lgkmcnt(0)
	s_setprio 1
	s_barrier
; template <class Epi>
; DI void gemm_phase(LAS unsigned char* lds, const Gemm g, const StaticOrder& S, const Epi& E) {
;     ...
;             PG8_BAR; PG8_WAIT_L(0); PG8_MMA(1, 0, At, B0); PG8_BAR; PG8_SCHED;
;             PG8_STAGE(PG8_SB(1, 1), b3 + hstep);
;             PG8_WAIT_V(6); PG8_BAR; PG8_MMA(1, 1, At, B1); PG8_BAR;
;         }
;     template <bool LN, int BJ, int LO, int HI> DI void batch(const f32x4 (&acc)[2][2][4][2], unsigned row0, unsigned col0, const f32x4 (&gv)[2], const f32x4 (&bv)[2]) const {
;         f32x4 r[HI - LO]; float mean[(HI - LO) / 2], rstd[(HI - LO) / 2];
; #pragma unroll
;         for (int i = LO; i < HI; ++i) { const int ai = i >> 3, m = (i >> 1) & 3, n = i & 1; const unsigned row = row0 + ai * HALF + m * 16;
;             if (n == 0) { mean[(i - LO) >> 1] = 0.f; rstd[(i - LO) >> 1] = 1.f;
;                 if (LN) { const float2 st = *(const float2*)(stats + row * 2u); mean[(i - LO) >> 1] = st.x; rstd[(i - LO) >> 1] = st.y; } }
;             r[i - LO] = *(const f32x4*)(src + (row * (unsigned)DM + col0 + BJ * HALF + n * 16)); }
; #pragma unroll
;         for (int i = LO; i < HI; ++i) { const int ai = i >> 3, m = (i >> 1) & 3, n = i & 1; const unsigned row = row0 + ai * HALF + m * 16;
;             *(f32x4*)(Y + (row * (unsigned)DM + col0 + BJ * HALF + n * 16)) = acc[ai][BJ][m][n] + ((r[i - LO] - mean[(i - LO) >> 1]) * rstd[(i - LO) >> 1]) * gv[n] + bv[n]; }
;         __builtin_amdgcn_sched_barrier(0);
;     }
;     template <bool LN, int BJ> DI void load_gb(unsigned col0, f32x4 (&gv)[2], f32x4 (&bv)[2]) const {
; #pragma unroll
;         for (int n = 0; n < 2; ++n) {
;             if (LN) { gv[n] = *(const f32x4*)(gam + col0 + BJ * HALF + n * 16) * ALPHA; bv[n] = *(const f32x4*)(bet + col0 + BJ * HALF + n * 16) * ALPHA; }
;             else { gv[n] = (f32x4){ALPHA, ALPHA, ALPHA, ALPHA}; bv[n] = (f32x4){0.f, 0.f, 0.f, 0.f}; }
;         }
;     }
;     template <bool LN> DI void run(const f32x4 (&acc)[2][2][4][2], const Unit& u, int wr, int wc, int fr, int fq) const {
;         const unsigned row0 = u.pm * BM + wr * 64 + fr, col0 = u.pn * BM + wc * 32 + 4 * fq;
;         f32x4 gv[2], bv[2];
;         load_gb<LN, 0>(col0, gv, bv);
;         batch<LN, 0, 0, 4>(acc, row0, col0, gv, bv);
;         batch<LN, 0, 4, 8>(acc, row0, col0, gv, bv);
;         batch<LN, 0, 8, 12>(acc, row0, col0, gv, bv);
	v_mfma_f32_16x16x32_bf16 v[92:95], v[128:131], v[144:147], v[92:95]
	v_mfma_f32_16x16x32_bf16 v[88:91], v[136:139], v[144:147], v[88:91]
	v_mfma_f32_16x16x32_bf16 v[84:87], v[128:131], v[152:155], v[84:87]
	v_mfma_f32_16x16x32_bf16 v[80:83], v[136:139], v[152:155], v[80:83]
	v_mfma_f32_16x16x32_bf16 v[76:79], v[128:131], v[198:201], v[76:79]
	v_mfma_f32_16x16x32_bf16 v[72:75], v[136:139], v[198:201], v[72:75]
	v_mfma_f32_16x16x32_bf16 v[68:71], v[128:131], v[206:209], v[68:71]
	v_mfma_f32_16x16x32_bf16 v[64:67], v[136:139], v[206:209], v[64:67]
	v_mfma_f32_16x16x32_bf16 v[92:95], v[132:135], v[148:151], v[92:95]
	v_mfma_f32_16x16x32_bf16 v[88:91], v[140:143], v[148:151], v[88:91]
	v_mfma_f32_16x16x32_bf16 v[84:87], v[132:135], v[194:197], v[84:87]
	v_mfma_f32_16x16x32_bf16 v[80:83], v[140:143], v[194:197], v[80:83]
	v_mfma_f32_16x16x32_bf16 v[76:79], v[132:135], v[202:205], v[76:79]
	v_mfma_f32_16x16x32_bf16 v[72:75], v[140:143], v[202:205], v[72:75]
	v_mfma_f32_16x16x32_bf16 v[68:71], v[132:135], v[210:213], v[68:71]
	s_setprio 0
	v_mfma_f32_16x16x32_bf16 v[64:67], v[140:143], v[210:213], v[64:67]
	s_barrier
	s_add_u32 s24, s28, 0x80080
	s_addc_u32 s25, s29, 0
	s_add_i32 s28, s30, s37
	s_mov_b32 m0, s28
	s_nop 0
	global_load_lds_dwordx4 v188, s[24:25]
	s_add_i32 m0, s28, 0x2000
	s_nop 0
	global_load_lds_dwordx4 v186, s[24:25]
	s_waitcnt vmcnt(6)
	s_setprio 1
	s_barrier
	v_mfma_f32_16x16x32_bf16 v[28:31], v[214:217], v[144:147], v[28:31]
	v_mfma_f32_16x16x32_bf16 v[24:27], v[234:237], v[144:147], v[24:27]
	v_mfma_f32_16x16x32_bf16 v[20:23], v[214:217], v[152:155], v[20:23]
	v_mfma_f32_16x16x32_bf16 v[16:19], v[234:237], v[152:155], v[16:19]
	v_mfma_f32_16x16x32_bf16 v[12:15], v[214:217], v[198:201], v[12:15]
	v_mfma_f32_16x16x32_bf16 v[8:11], v[234:237], v[198:201], v[8:11]
	v_mfma_f32_16x16x32_bf16 v[4:7], v[214:217], v[206:209], v[4:7]
	v_mfma_f32_16x16x32_bf16 v[0:3], v[234:237], v[206:209], v[0:3]
	v_mfma_f32_16x16x32_bf16 v[28:31], v[230:233], v[148:151], v[28:31]
	s_add_i32 s46, s46, 2
	v_mfma_f32_16x16x32_bf16 v[24:27], v[238:241], v[148:151], v[24:27]
	s_add_u32 s33, s33, 0x100
	v_mfma_f32_16x16x32_bf16 v[20:23], v[230:233], v[194:197], v[20:23]
	s_addc_u32 s45, s45, 0
	v_mfma_f32_16x16x32_bf16 v[16:19], v[238:241], v[194:197], v[16:19]
	s_cmp_gt_u32 s46, 29
	v_mfma_f32_16x16x32_bf16 v[12:15], v[230:233], v[202:205], v[12:15]
	s_mov_b64 s[24:25], s[26:27]
	v_mfma_f32_16x16x32_bf16 v[8:11], v[238:241], v[202:205], v[8:11]
	v_mfma_f32_16x16x32_bf16 v[4:7], v[230:233], v[210:213], v[4:7]
	s_setprio 0
	v_mfma_f32_16x16x32_bf16 v[0:3], v[238:241], v[210:213], v[0:3]
	s_barrier
	s_cbranch_scc0 .LBB0_320
	v_lshl_add_u32 v206, s3, 8, v225
	v_lshl_or_b32 v158, s2, 8, v227
	v_lshlrev_b32_e32 v232, 11, v206
	s_andn2_b64 vcc, exec, s[14:15]
	v_or_b32_e32 v231, 16, v158
	v_add_u32_e32 v194, v232, v158
	v_or_b32_e32 v230, 0x80, v158
	v_or_b32_e32 v229, 0x90, v158
	s_cbranch_vccnz .LBB0_323
	v_lshlrev_b64 v[132:133], 2, v[158:159]
	v_lshl_add_u64 v[140:141], s[16:17], 0, v[132:133]
	global_load_dwordx4 v[128:131], v[140:141], off
	v_lshl_add_u64 v[142:143], s[18:19], 0, v[132:133]
	v_readlane_b32 s2, v253, 8
	v_mov_b32_e32 v195, v159
	v_lshlrev_b32_e32 v136, 1, v206
	v_mov_b32_e32 v137, v159
	v_readlane_b32 s3, v253, 9
	v_lshlrev_b64 v[212:213], 2, v[194:195]
	v_add_u32_e32 v146, v232, v231
	v_lshl_add_u64 v[144:145], v[136:137], 2, s[2:3]
	v_lshl_add_u64 v[136:137], s[88:89], 0, v[212:213]
	v_mov_b32_e32 v147, v159
	v_lshl_add_u64 v[146:147], v[146:147], 2, s[88:89]
	v_or_b32_e32 v195, 16, v206
	v_mov_b32_e32 v201, v159
	v_mov_b32_e32 v209, v159
	v_lshl_add_u64 v[212:213], s[90:91], 0, v[212:213]
	s_waitcnt vmcnt(0)
	v_pk_mul_f32 v[152:153], v[130:131], s[78:79] op_sel_hi:[1,0]
	v_pk_mul_f32 v[154:155], v[128:129], s[78:79] op_sel_hi:[1,0]
	global_load_dwordx4 v[132:135], v[142:143], off
	global_load_dwordx4 v[128:131], v[140:141], off offset:64
	global_load_dwordx2 v[204:205], v[144:145], off
	global_load_dwordx4 v[196:199], v[146:147], off
	v_lshlrev_b32_e32 v146, 1, v195
	global_load_dwordx4 v[136:139], v[136:137], off
	v_lshlrev_b32_e32 v195, 11, v195
	v_mov_b32_e32 v147, v159
	v_add_u32_e32 v200, v195, v158
	v_lshl_add_u64 v[146:147], v[146:147], 2, s[2:3]
	v_lshl_add_u64 v[200:201], v[200:201], 2, s[88:89]
	global_load_dwordx2 v[214:215], v[146:147], off
	v_add_u32_e32 v208, v195, v231
	global_load_dwordx4 v[200:203], v[200:201], off
	v_lshl_add_u64 v[208:209], v[208:209], 2, s[88:89]
	global_load_dwordx4 v[208:211], v[208:209], off
	s_waitcnt vmcnt(0)
	v_pk_mul_f32 v[148:149], v[130:131], s[78:79] op_sel_hi:[1,0]
	v_pk_mul_f32 v[150:151], v[128:129], s[78:79] op_sel_hi:[1,0]
	global_load_dwordx4 v[128:131], v[142:143], off offset:64
	v_sub_f32_e32 v137, v137, v204
	v_sub_f32_e32 v136, v136, v204
	v_sub_f32_e32 v139, v139, v204
	v_sub_f32_e32 v138, v138, v204
	v_pk_mul_f32 v[138:139], v[204:205], v[138:139] op_sel:[1,0]
	v_pk_mul_f32 v[136:137], v[204:205], v[136:137] op_sel:[1,0]
	v_pk_fma_f32 v[138:139], v[152:153], v[138:139], v[126:127]
	v_pk_fma_f32 v[136:137], v[154:155], v[136:137], v[124:125]
	v_pk_fma_f32 v[138:139], v[134:135], s[78:79], v[138:139] op_sel_hi:[1,0,1]
	v_pk_fma_f32 v[136:137], v[132:133], s[78:79], v[136:137] op_sel_hi:[1,0,1]
	global_store_dwordx4 v[212:213], v[136:139], off
	s_nop 1
	v_sub_f32_e32 v137, v197, v204
	v_sub_f32_e32 v136, v196, v204
	v_sub_f32_e32 v139, v199, v204
	v_sub_f32_e32 v138, v198, v204
	v_pk_mul_f32 v[138:139], v[204:205], v[138:139] op_sel:[1,0]
	v_pk_mul_f32 v[136:137], v[204:205], v[136:137] op_sel:[1,0]
	v_pk_fma_f32 v[138:139], v[148:149], v[138:139], v[122:123]
	v_pk_fma_f32 v[136:137], v[150:151], v[136:137], v[120:121]
	v_or_b32_e32 v196, 16, v194
	v_mov_b32_e32 v197, v159
	v_lshl_add_u64 v[196:197], v[196:197], 2, s[90:91]
	s_waitcnt vmcnt(0)
;     template <bool LN, int BJ, int LO, int HI> DI void batch(const f32x4 (&acc)[2][2][4][2], unsigned row0, unsigned col0, const f32x4 (&gv)[2], const f32x4 (&bv)[2]) const {
;         f32x4 r[HI - LO]; float mean[(HI - LO) / 2], rstd[(HI - LO) / 2];
; #pragma unroll
;         for (int i = LO; i < HI; ++i) { const int ai = i >> 3, m = (i >> 1) & 3, n = i & 1; const unsigned row = row0 + ai * HALF + m * 16;
;             if (n == 0) { mean[(i - LO) >> 1] = 0.f; rstd[(i - LO) >> 1] = 1.f;
;                 if (LN) { const float2 st = *(const float2*)(stats + row * 2u); mean[(i - LO) >> 1] = st.x; rstd[(i - LO) >> 1] = st.y; } }
;             r[i - LO] = *(const f32x4*)(src + (row * (unsigned)DM + col0 + BJ * HALF + n * 16)); }
; #pragma unroll
;         for (int i = LO; i < HI; ++i) { const int ai = i >> 3, m = (i >> 1) & 3, n = i & 1; const unsigned row = row0 + ai * HALF + m * 16;
;             *(f32x4*)(Y + (row * (unsigned)DM + col0 + BJ * HALF + n * 16)) = acc[ai][BJ][m][n] + ((r[i - LO] - mean[(i - LO) >> 1]) * rstd[(i - LO) >> 1]) * gv[n] + bv[n]; }
	v_pk_fma_f32 v[138:139], v[130:131], s[78:79], v[138:139] op_sel_hi:[1,0,1]
	v_pk_fma_f32 v[136:137], v[128:129], s[78:79], v[136:137] op_sel_hi:[1,0,1]
	global_store_dwordx4 v[196:197], v[136:139], off
	v_add_u32_e32 v196, 0x8000, v194
	v_mov_b32_e32 v197, v159
	v_sub_f32_e32 v137, v201, v214
	v_sub_f32_e32 v136, v200, v214
	v_sub_f32_e32 v139, v203, v214
	v_sub_f32_e32 v138, v202, v214
	v_pk_mul_f32 v[138:139], v[214:215], v[138:139] op_sel:[1,0]
	v_pk_mul_f32 v[136:137], v[214:215], v[136:137] op_sel:[1,0]
	v_pk_fma_f32 v[138:139], v[152:153], v[138:139], v[118:119]
	v_pk_fma_f32 v[136:137], v[154:155], v[136:137], v[116:117]
	v_pk_fma_f32 v[138:139], v[134:135], s[78:79], v[138:139] op_sel_hi:[1,0,1]
	v_pk_fma_f32 v[136:137], v[132:133], s[78:79], v[136:137] op_sel_hi:[1,0,1]
	v_lshl_add_u64 v[196:197], v[196:197], 2, s[90:91]
	global_store_dwordx4 v[196:197], v[136:139], off
	v_add_u32_e32 v196, 0x8010, v194
	v_mov_b32_e32 v197, v159
	v_sub_f32_e32 v137, v209, v214
	v_sub_f32_e32 v136, v208, v214
	v_sub_f32_e32 v139, v211, v214
	v_sub_f32_e32 v138, v210, v214
	v_pk_mul_f32 v[138:139], v[214:215], v[138:139] op_sel:[1,0]
	v_pk_mul_f32 v[136:137], v[214:215], v[136:137] op_sel:[1,0]
	v_pk_fma_f32 v[138:139], v[148:149], v[138:139], v[114:115]
	v_pk_fma_f32 v[136:137], v[150:151], v[136:137], v[112:113]
	v_pk_fma_f32 v[138:139], v[130:131], s[78:79], v[138:139] op_sel_hi:[1,0,1]
	v_pk_fma_f32 v[136:137], v[128:129], s[78:79], v[136:137] op_sel_hi:[1,0,1]
	v_lshl_add_u64 v[196:197], v[196:197], 2, s[90:91]
	global_store_dwordx4 v[196:197], v[136:139], off
	s_nop 1
	v_or_b32_e32 v138, 32, v206
	v_lshlrev_b32_e32 v136, 1, v138
	v_mov_b32_e32 v137, v159
	v_lshlrev_b32_e32 v236, 11, v138
	v_lshl_add_u64 v[200:201], v[136:137], 2, s[2:3]
	v_add_u32_e32 v136, v236, v158
	v_lshl_add_u64 v[136:137], v[136:137], 2, s[88:89]
	global_load_dwordx2 v[204:205], v[200:201], off
	v_add_u32_e32 v196, v236, v231
	global_load_dwordx4 v[136:139], v[136:137], off
	v_mov_b32_e32 v197, v159
	v_lshl_add_u64 v[196:197], v[196:197], 2, s[88:89]
	global_load_dwordx4 v[196:199], v[196:197], off
	v_or_b32_e32 v207, 48, v206
	v_lshlrev_b32_e32 v235, 11, v207
	v_lshlrev_b32_e32 v202, 1, v207
	v_mov_b32_e32 v203, v159
	v_add_u32_e32 v208, v235, v158
	v_mov_b32_e32 v209, v159
	v_lshl_add_u64 v[202:203], v[202:203], 2, s[2:3]
	v_lshl_add_u64 v[208:209], v[208:209], 2, s[88:89]
	global_load_dwordx2 v[216:217], v[202:203], off
	v_add_u32_e32 v212, v235, v231
	global_load_dwordx4 v[208:211], v[208:209], off
	v_mov_b32_e32 v213, v159
	v_lshl_add_u64 v[212:213], v[212:213], 2, s[88:89]
	global_load_dwordx4 v[212:215], v[212:213], off
	v_add_u32_e32 v218, 0x10000, v194
	v_mov_b32_e32 v219, v159
	v_lshl_add_u64 v[218:219], v[218:219], 2, s[90:91]
	s_waitcnt vmcnt(0)
	v_sub_f32_e32 v137, v137, v204
	v_sub_f32_e32 v136, v136, v204
	v_sub_f32_e32 v139, v139, v204
	v_sub_f32_e32 v138, v138, v204
	v_pk_mul_f32 v[138:139], v[204:205], v[138:139] op_sel:[1,0]
	v_pk_mul_f32 v[136:137], v[204:205], v[136:137] op_sel:[1,0]
	v_pk_fma_f32 v[138:139], v[152:153], v[138:139], v[110:111]
	v_pk_fma_f32 v[136:137], v[154:155], v[136:137], v[108:109]
	v_pk_fma_f32 v[138:139], v[134:135], s[78:79], v[138:139] op_sel_hi:[1,0,1]
	v_pk_fma_f32 v[136:137], v[132:133], s[78:79], v[136:137] op_sel_hi:[1,0,1]
	global_store_dwordx4 v[218:219], v[136:139], off
	s_nop 1
	v_sub_f32_e32 v137, v197, v204
	v_sub_f32_e32 v136, v196, v204
	v_sub_f32_e32 v139, v199, v204
	v_sub_f32_e32 v138, v198, v204
	v_pk_mul_f32 v[138:139], v[204:205], v[138:139] op_sel:[1,0]
	v_pk_mul_f32 v[136:137], v[204:205], v[136:137] op_sel:[1,0]
	v_pk_fma_f32 v[138:139], v[148:149], v[138:139], v[106:107]
	v_pk_fma_f32 v[136:137], v[150:151], v[136:137], v[104:105]
	v_add_u32_e32 v196, 0x10010, v194
	v_mov_b32_e32 v197, v159
	v_pk_fma_f32 v[138:139], v[130:131], s[78:79], v[138:139] op_sel_hi:[1,0,1]
	v_pk_fma_f32 v[136:137], v[128:129], s[78:79], v[136:137] op_sel_hi:[1,0,1]
	v_lshl_add_u64 v[196:197], v[196:197], 2, s[90:91]
	global_store_dwordx4 v[196:197], v[136:139], off
	v_add_u32_e32 v196, 0x18000, v194
	v_mov_b32_e32 v197, v159
	v_sub_f32_e32 v137, v209, v216
	v_sub_f32_e32 v136, v208, v216
	v_sub_f32_e32 v139, v211, v216
	v_sub_f32_e32 v138, v210, v216
	v_pk_mul_f32 v[138:139], v[216:217], v[138:139] op_sel:[1,0]
	v_pk_mul_f32 v[136:137], v[216:217], v[136:137] op_sel:[1,0]
	v_pk_fma_f32 v[138:139], v[152:153], v[138:139], v[102:103]
	v_pk_fma_f32 v[136:137], v[154:155], v[136:137], v[100:101]
	v_pk_fma_f32 v[138:139], v[134:135], s[78:79], v[138:139] op_sel_hi:[1,0,1]
	v_pk_fma_f32 v[136:137], v[132:133], s[78:79], v[136:137] op_sel_hi:[1,0,1]
	v_lshl_add_u64 v[196:197], v[196:197], 2, s[90:91]
	global_store_dwordx4 v[196:197], v[136:139], off
	v_add_u32_e32 v196, 0x18010, v194
	v_mov_b32_e32 v197, v159
	v_sub_f32_e32 v137, v213, v216
	v_sub_f32_e32 v136, v212, v216
	v_sub_f32_e32 v139, v215, v216
	v_sub_f32_e32 v138, v214, v216
	v_pk_mul_f32 v[138:139], v[216:217], v[138:139] op_sel:[1,0]
	v_pk_mul_f32 v[136:137], v[216:217], v[136:137] op_sel:[1,0]
	v_pk_fma_f32 v[138:139], v[148:149], v[138:139], v[98:99]
	v_pk_fma_f32 v[136:137], v[150:151], v[136:137], v[96:97]
	v_pk_fma_f32 v[138:139], v[130:131], s[78:79], v[138:139] op_sel_hi:[1,0,1]
	v_pk_fma_f32 v[136:137], v[128:129], s[78:79], v[136:137] op_sel_hi:[1,0,1]
	v_lshl_add_u64 v[196:197], v[196:197], 2, s[90:91]
	global_store_dwordx4 v[196:197], v[136:139], off
	s_nop 1
	v_add_u32_e32 v138, 0x80, v206
	v_lshlrev_b32_e32 v136, 1, v138
	v_mov_b32_e32 v137, v159
	v_lshlrev_b32_e32 v233, 11, v138
	v_lshl_add_u64 v[196:197], v[136:137], 2, s[2:3]
	v_add_u32_e32 v136, v233, v158
	v_lshl_add_u64 v[136:137], v[136:137], 2, s[88:89]
	global_load_dwordx2 v[204:205], v[196:197], off
	v_add_u32_e32 v198, v233, v231
	global_load_dwordx4 v[136:139], v[136:137], off
	v_mov_b32_e32 v199, v159
	v_add_u32_e32 v207, 0x90, v206
	v_lshl_add_u64 v[198:199], v[198:199], 2, s[88:89]
	v_lshlrev_b32_e32 v234, 11, v207
	global_load_dwordx4 v[208:211], v[198:199], off
	v_add_u32_e32 v212, v234, v158
	v_mov_b32_e32 v213, v159
	v_lshl_add_u64 v[212:213], v[212:213], 2, s[88:89]
	global_load_dwordx4 v[212:215], v[212:213], off
	v_lshlrev_b32_e32 v198, 1, v207
	v_mov_b32_e32 v199, v159
	v_lshl_add_u64 v[198:199], v[198:199], 2, s[2:3]
	global_load_dwordx2 v[238:239], v[198:199], off
	v_add_u32_e32 v216, v234, v231
	v_mov_b32_e32 v217, v159
	v_lshl_add_u64 v[216:217], v[216:217], 2, s[88:89]
	global_load_dwordx4 v[216:219], v[216:217], off
	v_add_u32_e32 v240, 0x40000, v194
	v_mov_b32_e32 v241, v159
	v_lshl_add_u64 v[240:241], v[240:241], 2, s[90:91]
	s_waitcnt vmcnt(0)
;     template <bool LN, int BJ, int LO, int HI> DI void batch(const f32x4 (&acc)[2][2][4][2], unsigned row0, unsigned col0, const f32x4 (&gv)[2], const f32x4 (&bv)[2]) const {
;         f32x4 r[HI - LO]; float mean[(HI - LO) / 2], rstd[(HI - LO) / 2];
; #pragma unroll
;         for (int i = LO; i < HI; ++i) { const int ai = i >> 3, m = (i >> 1) & 3, n = i & 1; const unsigned row = row0 + ai * HALF + m * 16;
;             if (n == 0) { mean[(i - LO) >> 1] = 0.f; rstd[(i - LO) >> 1] = 1.f;
;                 if (LN) { const float2 st = *(const float2*)(stats + row * 2u); mean[(i - LO) >> 1] = st.x; rstd[(i - LO) >> 1] = st.y; } }
;             r[i - LO] = *(const f32x4*)(src + (row * (unsigned)DM + col0 + BJ * HALF + n * 16)); }
; #pragma unroll
;         for (int i = LO; i < HI; ++i) { const int ai = i >> 3, m = (i >> 1) & 3, n = i & 1; const unsigned row = row0 + ai * HALF + m * 16;
;             *(f32x4*)(Y + (row * (unsigned)DM + col0 + BJ * HALF + n * 16)) = acc[ai][BJ][m][n] + ((r[i - LO] - mean[(i - LO) >> 1]) * rstd[(i - LO) >> 1]) * gv[n] + bv[n]; }
	v_sub_f32_e32 v137, v137, v204
	v_sub_f32_e32 v136, v136, v204
	v_sub_f32_e32 v139, v139, v204
	v_sub_f32_e32 v138, v138, v204
	v_pk_mul_f32 v[138:139], v[204:205], v[138:139] op_sel:[1,0]
	v_pk_mul_f32 v[136:137], v[204:205], v[136:137] op_sel:[1,0]
	v_pk_fma_f32 v[138:139], v[152:153], v[138:139], v[94:95]
	v_pk_fma_f32 v[136:137], v[154:155], v[136:137], v[92:93]
	v_pk_fma_f32 v[138:139], v[134:135], s[78:79], v[138:139] op_sel_hi:[1,0,1]
	v_pk_fma_f32 v[136:137], v[132:133], s[78:79], v[136:137] op_sel_hi:[1,0,1]
	global_store_dwordx4 v[240:241], v[136:139], off
	s_nop 1
	v_sub_f32_e32 v137, v209, v204
	v_sub_f32_e32 v136, v208, v204
	v_sub_f32_e32 v139, v211, v204
	v_sub_f32_e32 v138, v210, v204
	v_pk_mul_f32 v[138:139], v[204:205], v[138:139] op_sel:[1,0]
	v_pk_mul_f32 v[136:137], v[204:205], v[136:137] op_sel:[1,0]
	v_pk_fma_f32 v[138:139], v[148:149], v[138:139], v[90:91]
	v_pk_fma_f32 v[136:137], v[150:151], v[136:137], v[88:89]
	v_add_u32_e32 v204, 0x40010, v194
	v_mov_b32_e32 v205, v159
	v_pk_fma_f32 v[138:139], v[130:131], s[78:79], v[138:139] op_sel_hi:[1,0,1]
	v_pk_fma_f32 v[136:137], v[128:129], s[78:79], v[136:137] op_sel_hi:[1,0,1]
	v_lshl_add_u64 v[204:205], v[204:205], 2, s[90:91]
	global_store_dwordx4 v[204:205], v[136:139], off
	v_add_u32_e32 v204, 0x48000, v194
	v_mov_b32_e32 v205, v159
	v_sub_f32_e32 v137, v213, v238
	v_sub_f32_e32 v136, v212, v238
	v_sub_f32_e32 v139, v215, v238
	v_sub_f32_e32 v138, v214, v238
	v_pk_mul_f32 v[138:139], v[238:239], v[138:139] op_sel:[1,0]
	v_pk_mul_f32 v[136:137], v[238:239], v[136:137] op_sel:[1,0]
	v_pk_fma_f32 v[138:139], v[152:153], v[138:139], v[86:87]
	v_pk_fma_f32 v[136:137], v[154:155], v[136:137], v[84:85]
	v_pk_fma_f32 v[138:139], v[134:135], s[78:79], v[138:139] op_sel_hi:[1,0,1]
	v_pk_fma_f32 v[136:137], v[132:133], s[78:79], v[136:137] op_sel_hi:[1,0,1]
	v_lshl_add_u64 v[204:205], v[204:205], 2, s[90:91]
	global_store_dwordx4 v[204:205], v[136:139], off
	v_add_u32_e32 v204, 0x48010, v194
	v_mov_b32_e32 v205, v159
	v_sub_f32_e32 v137, v217, v238
	v_sub_f32_e32 v136, v216, v238
	v_sub_f32_e32 v139, v219, v238
	v_sub_f32_e32 v138, v218, v238
	v_pk_mul_f32 v[138:139], v[238:239], v[138:139] op_sel:[1,0]
	v_pk_mul_f32 v[136:137], v[238:239], v[136:137] op_sel:[1,0]
	v_pk_fma_f32 v[138:139], v[148:149], v[138:139], v[82:83]
	v_pk_fma_f32 v[136:137], v[150:151], v[136:137], v[80:81]
	v_pk_fma_f32 v[138:139], v[130:131], s[78:79], v[138:139] op_sel_hi:[1,0,1]
	v_pk_fma_f32 v[136:137], v[128:129], s[78:79], v[136:137] op_sel_hi:[1,0,1]
	v_lshl_add_u64 v[204:205], v[204:205], 2, s[90:91]
	global_store_dwordx4 v[204:205], v[136:139], off
	s_nop 1
	v_add_u32_e32 v138, 0xa0, v206
	v_lshlrev_b32_e32 v136, 1, v138
	v_mov_b32_e32 v137, v159
	v_lshlrev_b32_e32 v237, 11, v138
	v_lshl_add_u64 v[204:205], v[136:137], 2, s[2:3]
	v_add_u32_e32 v136, v237, v158
	v_lshl_add_u64 v[136:137], v[136:137], 2, s[88:89]
	global_load_dwordx2 v[240:241], v[204:205], off
	v_add_u32_e32 v208, v237, v231
	global_load_dwordx4 v[136:139], v[136:137], off
	v_mov_b32_e32 v209, v159
	v_lshl_add_u64 v[208:209], v[208:209], 2, s[88:89]
	global_load_dwordx4 v[212:215], v[208:209], off
	v_add_u32_e32 v208, 0xb0, v206
	v_lshlrev_b32_e32 v206, 1, v208
	v_mov_b32_e32 v207, v159
	v_lshlrev_b32_e32 v238, 11, v208
	v_lshl_add_u64 v[210:211], v[206:207], 2, s[2:3]
	v_add_u32_e32 v206, v238, v158
	v_lshl_add_u64 v[206:207], v[206:207], 2, s[88:89]
	global_load_dwordx2 v[242:243], v[210:211], off
	v_add_u32_e32 v216, v238, v231
	global_load_dwordx4 v[206:209], v[206:207], off
	v_mov_b32_e32 v217, v159
	v_lshl_add_u64 v[216:217], v[216:217], 2, s[88:89]
	global_load_dwordx4 v[216:219], v[216:217], off
	v_add_u32_e32 v244, 0x50000, v194
	v_mov_b32_e32 v245, v159
	v_lshl_add_u64 v[244:245], v[244:245], 2, s[90:91]
	s_waitcnt vmcnt(0)
	v_sub_f32_e32 v137, v137, v240
	v_sub_f32_e32 v136, v136, v240
	v_sub_f32_e32 v139, v139, v240
	v_sub_f32_e32 v138, v138, v240
	v_pk_mul_f32 v[138:139], v[240:241], v[138:139] op_sel:[1,0]
	v_pk_mul_f32 v[136:137], v[240:241], v[136:137] op_sel:[1,0]
	v_pk_fma_f32 v[138:139], v[152:153], v[138:139], v[78:79]
	v_pk_fma_f32 v[136:137], v[154:155], v[136:137], v[76:77]
	v_pk_fma_f32 v[138:139], v[134:135], s[78:79], v[138:139] op_sel_hi:[1,0,1]
	v_pk_fma_f32 v[136:137], v[132:133], s[78:79], v[136:137] op_sel_hi:[1,0,1]
	global_store_dwordx4 v[244:245], v[136:139], off
	s_nop 1
	v_sub_f32_e32 v137, v213, v240
	v_sub_f32_e32 v136, v212, v240
	v_sub_f32_e32 v139, v215, v240
	v_sub_f32_e32 v138, v214, v240
	v_pk_mul_f32 v[138:139], v[240:241], v[138:139] op_sel:[1,0]
	v_pk_mul_f32 v[136:137], v[240:241], v[136:137] op_sel:[1,0]
	v_pk_fma_f32 v[138:139], v[148:149], v[138:139], v[74:75]
	v_pk_fma_f32 v[136:137], v[150:151], v[136:137], v[72:73]
	v_add_u32_e32 v212, 0x50010, v194
	v_mov_b32_e32 v213, v159
	v_pk_fma_f32 v[138:139], v[130:131], s[78:79], v[138:139] op_sel_hi:[1,0,1]
	v_pk_fma_f32 v[136:137], v[128:129], s[78:79], v[136:137] op_sel_hi:[1,0,1]
	v_lshl_add_u64 v[212:213], v[212:213], 2, s[90:91]
	global_store_dwordx4 v[212:213], v[136:139], off
	s_nop 1
	v_sub_f32_e32 v137, v207, v242
	v_sub_f32_e32 v136, v206, v242
	v_sub_f32_e32 v139, v209, v242
	v_sub_f32_e32 v138, v208, v242
	v_pk_mul_f32 v[136:137], v[242:243], v[136:137] op_sel:[1,0]
	v_pk_mul_f32 v[138:139], v[242:243], v[138:139] op_sel:[1,0]
	v_pk_fma_f32 v[136:137], v[154:155], v[136:137], v[68:69]
	v_pk_fma_f32 v[138:139], v[152:153], v[138:139], v[70:71]
	v_pk_fma_f32 v[132:133], v[132:133], s[78:79], v[136:137] op_sel_hi:[1,0,1]
	v_add_u32_e32 v136, 0x58000, v194
	v_mov_b32_e32 v137, v159
	v_pk_fma_f32 v[134:135], v[134:135], s[78:79], v[138:139] op_sel_hi:[1,0,1]
	v_lshl_add_u64 v[136:137], v[136:137], 2, s[90:91]
	global_store_dwordx4 v[136:137], v[132:135], off
	s_nop 1
	v_sub_f32_e32 v133, v217, v242
	v_sub_f32_e32 v132, v216, v242
	v_sub_f32_e32 v135, v219, v242
	v_sub_f32_e32 v134, v218, v242
	v_pk_mul_f32 v[132:133], v[242:243], v[132:133] op_sel:[1,0]
	v_pk_mul_f32 v[134:135], v[242:243], v[134:135] op_sel:[1,0]
	v_pk_fma_f32 v[132:133], v[150:151], v[132:133], v[64:65]
	v_pk_fma_f32 v[134:135], v[148:149], v[134:135], v[66:67]
	v_pk_fma_f32 v[128:129], v[128:129], s[78:79], v[132:133] op_sel_hi:[1,0,1]
	v_add_u32_e32 v132, 0x58010, v194
	v_mov_b32_e32 v133, v159
	v_pk_fma_f32 v[130:131], v[130:131], s[78:79], v[134:135] op_sel_hi:[1,0,1]
	v_lshl_add_u64 v[132:133], v[132:133], 2, s[90:91]
	global_store_dwordx4 v[132:133], v[128:131], off
	global_load_dwordx4 v[128:131], v[140:141], off offset:512
	v_add_u32_e32 v136, v232, v230
	v_mov_b32_e32 v137, v159
	v_lshl_add_u64 v[136:137], v[136:137], 2, s[88:89]
	s_waitcnt vmcnt(0)
;     template <bool LN, int BJ, int LO, int HI> DI void batch(const f32x4 (&acc)[2][2][4][2], unsigned row0, unsigned col0, const f32x4 (&gv)[2], const f32x4 (&bv)[2]) const {
;         f32x4 r[HI - LO]; float mean[(HI - LO) / 2], rstd[(HI - LO) / 2];
; #pragma unroll
;         for (int i = LO; i < HI; ++i) { const int ai = i >> 3, m = (i >> 1) & 3, n = i & 1; const unsigned row = row0 + ai * HALF + m * 16;
;             if (n == 0) { mean[(i - LO) >> 1] = 0.f; rstd[(i - LO) >> 1] = 1.f;
;                 if (LN) { const float2 st = *(const float2*)(stats + row * 2u); mean[(i - LO) >> 1] = st.x; rstd[(i - LO) >> 1] = st.y; } }
;             r[i - LO] = *(const f32x4*)(src + (row * (unsigned)DM + col0 + BJ * HALF + n * 16)); }
; #pragma unroll
;         for (int i = LO; i < HI; ++i) { const int ai = i >> 3, m = (i >> 1) & 3, n = i & 1; const unsigned row = row0 + ai * HALF + m * 16;
;             *(f32x4*)(Y + (row * (unsigned)DM + col0 + BJ * HALF + n * 16)) = acc[ai][BJ][m][n] + ((r[i - LO] - mean[(i - LO) >> 1]) * rstd[(i - LO) >> 1]) * gv[n] + bv[n]; }
;         __builtin_amdgcn_sched_barrier(0);
;     }
;     template <bool LN, int BJ> DI void load_gb(unsigned col0, f32x4 (&gv)[2], f32x4 (&bv)[2]) const {
; #pragma unroll
;         for (int n = 0; n < 2; ++n) {
;             if (LN) { gv[n] = *(const f32x4*)(gam + col0 + BJ * HALF + n * 16) * ALPHA; bv[n] = *(const f32x4*)(bet + col0 + BJ * HALF + n * 16) * ALPHA; }
;             else { gv[n] = (f32x4){ALPHA, ALPHA, ALPHA, ALPHA}; bv[n] = (f32x4){0.f, 0.f, 0.f, 0.f}; }
;         }
;     }
	v_pk_mul_f32 v[212:213], v[130:131], s[78:79] op_sel_hi:[1,0]
	v_pk_mul_f32 v[214:215], v[128:129], s[78:79] op_sel_hi:[1,0]
	global_load_dwordx4 v[132:135], v[142:143], off offset:512
	global_load_dwordx4 v[128:131], v[140:141], off offset:576
	s_waitcnt vmcnt(0)
	v_pk_mul_f32 v[206:207], v[130:131], s[78:79] op_sel_hi:[1,0]
	v_pk_mul_f32 v[208:209], v[128:129], s[78:79] op_sel_hi:[1,0]
	global_load_dwordx4 v[128:131], v[142:143], off offset:576
	global_load_dwordx2 v[220:221], v[144:145], off
	global_load_dwordx4 v[240:243], v[136:137], off
	v_add_u32_e32 v136, v232, v229
	v_mov_b32_e32 v137, v159
	v_lshl_add_u64 v[136:137], v[136:137], 2, s[88:89]
	global_load_dwordx4 v[244:247], v[136:137], off
	global_load_dwordx2 v[218:219], v[146:147], off
	v_add_u32_e32 v136, v195, v230
	v_mov_b32_e32 v137, v159
	v_lshl_add_u64 v[136:137], v[136:137], 2, s[88:89]
	global_load_dwordx4 v[248:251], v[136:137], off
	v_add_u32_e32 v136, v195, v229
	v_mov_b32_e32 v137, v159
	v_lshl_add_u64 v[136:137], v[136:137], 2, s[88:89]
	global_load_dwordx4 v[152:155], v[136:137], off
	global_load_dwordx2 v[216:217], v[200:201], off
	v_add_u32_e32 v136, v236, v230
	v_mov_b32_e32 v137, v159
	v_lshl_add_u64 v[136:137], v[136:137], 2, s[88:89]
	global_load_dwordx4 v[148:151], v[136:137], off
	v_add_u32_e32 v136, v236, v229
	v_mov_b32_e32 v137, v159
	v_lshl_add_u64 v[136:137], v[136:137], 2, s[88:89]
	global_load_dwordx4 v[144:147], v[136:137], off
	global_load_dwordx2 v[200:201], v[202:203], off
	v_add_u32_e32 v136, v235, v230
	v_mov_b32_e32 v137, v159
	v_lshl_add_u64 v[136:137], v[136:137], 2, s[88:89]
	global_load_dwordx4 v[140:143], v[136:137], off
	v_add_u32_e32 v136, v235, v229
	v_mov_b32_e32 v137, v159
	v_lshl_add_u64 v[136:137], v[136:137], 2, s[88:89]
	global_load_dwordx4 v[136:139], v[136:137], off
	v_add_u32_e32 v202, 0x80, v194
	v_mov_b32_e32 v203, v159
	v_lshl_add_u64 v[202:203], v[202:203], 2, s[90:91]
	s_waitcnt vmcnt(0)
	v_sub_f32_e32 v241, v241, v220
	v_sub_f32_e32 v240, v240, v220
	v_sub_f32_e32 v243, v243, v220
	v_sub_f32_e32 v242, v242, v220
	v_pk_mul_f32 v[242:243], v[220:221], v[242:243] op_sel:[1,0]
	v_pk_mul_f32 v[240:241], v[220:221], v[240:241] op_sel:[1,0]
	v_pk_fma_f32 v[242:243], v[212:213], v[242:243], v[62:63]
	v_pk_fma_f32 v[240:241], v[214:215], v[240:241], v[60:61]
	v_pk_fma_f32 v[242:243], v[134:135], s[78:79], v[242:243] op_sel_hi:[1,0,1]
	v_pk_fma_f32 v[240:241], v[132:133], s[78:79], v[240:241] op_sel_hi:[1,0,1]
	global_store_dwordx4 v[202:203], v[240:243], off
	v_sub_f32_e32 v203, v245, v220
	v_sub_f32_e32 v202, v244, v220
	v_sub_f32_e32 v241, v247, v220
	v_sub_f32_e32 v240, v246, v220
	v_pk_mul_f32 v[202:203], v[220:221], v[202:203] op_sel:[1,0]
	v_pk_mul_f32 v[240:241], v[220:221], v[240:241] op_sel:[1,0]
	v_pk_fma_f32 v[202:203], v[208:209], v[202:203], v[56:57]
	v_pk_fma_f32 v[220:221], v[206:207], v[240:241], v[58:59]
	v_pk_fma_f32 v[240:241], v[128:129], s[78:79], v[202:203] op_sel_hi:[1,0,1]
	v_add_u32_e32 v202, 0x90, v194
	v_mov_b32_e32 v203, v159
	v_pk_fma_f32 v[242:243], v[130:131], s[78:79], v[220:221] op_sel_hi:[1,0,1]
	v_lshl_add_u64 v[202:203], v[202:203], 2, s[90:91]
	global_store_dwordx4 v[202:203], v[240:243], off
	v_sub_f32_e32 v203, v249, v218
	v_sub_f32_e32 v202, v248, v218
	v_sub_f32_e32 v221, v251, v218
	v_sub_f32_e32 v220, v250, v218
	v_pk_mul_f32 v[202:203], v[218:219], v[202:203] op_sel:[1,0]
	v_pk_mul_f32 v[220:221], v[218:219], v[220:221] op_sel:[1,0]
	v_pk_fma_f32 v[202:203], v[214:215], v[202:203], v[52:53]
	v_pk_fma_f32 v[220:221], v[212:213], v[220:221], v[54:55]
	v_pk_fma_f32 v[240:241], v[132:133], s[78:79], v[202:203] op_sel_hi:[1,0,1]
	v_add_u32_e32 v202, 0x8080, v194
	v_mov_b32_e32 v203, v159
	v_sub_f32_e32 v153, v153, v218
	v_sub_f32_e32 v152, v152, v218
	v_sub_f32_e32 v155, v155, v218
	v_sub_f32_e32 v154, v154, v218
	v_pk_fma_f32 v[242:243], v[134:135], s[78:79], v[220:221] op_sel_hi:[1,0,1]
	v_lshl_add_u64 v[202:203], v[202:203], 2, s[90:91]
	v_pk_mul_f32 v[154:155], v[218:219], v[154:155] op_sel:[1,0]
	v_pk_mul_f32 v[152:153], v[218:219], v[152:153] op_sel:[1,0]
	global_store_dwordx4 v[202:203], v[240:243], off
	v_pk_fma_f32 v[152:153], v[208:209], v[152:153], v[48:49]
	v_pk_fma_f32 v[154:155], v[206:207], v[154:155], v[50:51]
	v_add_u32_e32 v202, 0x8090, v194
	v_mov_b32_e32 v203, v159
	v_sub_f32_e32 v149, v149, v216
	v_sub_f32_e32 v148, v148, v216
	v_sub_f32_e32 v151, v151, v216
	v_sub_f32_e32 v150, v150, v216
	v_pk_fma_f32 v[154:155], v[130:131], s[78:79], v[154:155] op_sel_hi:[1,0,1]
	v_pk_fma_f32 v[152:153], v[128:129], s[78:79], v[152:153] op_sel_hi:[1,0,1]
	v_lshl_add_u64 v[202:203], v[202:203], 2, s[90:91]
	v_pk_mul_f32 v[150:151], v[216:217], v[150:151] op_sel:[1,0]
	v_pk_mul_f32 v[148:149], v[216:217], v[148:149] op_sel:[1,0]
	global_store_dwordx4 v[202:203], v[152:155], off
	v_pk_fma_f32 v[148:149], v[214:215], v[148:149], v[44:45]
	v_pk_fma_f32 v[150:151], v[212:213], v[150:151], v[46:47]
	v_add_u32_e32 v152, 0x10080, v194
	v_mov_b32_e32 v153, v159
	v_sub_f32_e32 v145, v145, v216
	v_sub_f32_e32 v144, v144, v216
	v_sub_f32_e32 v147, v147, v216
	v_sub_f32_e32 v146, v146, v216
	v_pk_fma_f32 v[150:151], v[134:135], s[78:79], v[150:151] op_sel_hi:[1,0,1]
	v_pk_fma_f32 v[148:149], v[132:133], s[78:79], v[148:149] op_sel_hi:[1,0,1]
	v_lshl_add_u64 v[152:153], v[152:153], 2, s[90:91]
	v_pk_mul_f32 v[146:147], v[216:217], v[146:147] op_sel:[1,0]
	v_pk_mul_f32 v[144:145], v[216:217], v[144:145] op_sel:[1,0]
	global_store_dwordx4 v[152:153], v[148:151], off
	v_pk_fma_f32 v[144:145], v[208:209], v[144:145], v[40:41]
	v_pk_fma_f32 v[146:147], v[206:207], v[146:147], v[42:43]
;     template <bool LN, int BJ, int LO, int HI> DI void batch(const f32x4 (&acc)[2][2][4][2], unsigned row0, unsigned col0, const f32x4 (&gv)[2], const f32x4 (&bv)[2]) const {
;         f32x4 r[HI - LO]; float mean[(HI - LO) / 2], rstd[(HI - LO) / 2];
; #pragma unroll
;         for (int i = LO; i < HI; ++i) { const int ai = i >> 3, m = (i >> 1) & 3, n = i & 1; const unsigned row = row0 + ai * HALF + m * 16;
;             if (n == 0) { mean[(i - LO) >> 1] = 0.f; rstd[(i - LO) >> 1] = 1.f;
;                 if (LN) { const float2 st = *(const float2*)(stats + row * 2u); mean[(i - LO) >> 1] = st.x; rstd[(i - LO) >> 1] = st.y; } }
;             r[i - LO] = *(const f32x4*)(src + (row * (unsigned)DM + col0 + BJ * HALF + n * 16)); }
; #pragma unroll
;         for (int i = LO; i < HI; ++i) { const int ai = i >> 3, m = (i >> 1) & 3, n = i & 1; const unsigned row = row0 + ai * HALF + m * 16;
;             *(f32x4*)(Y + (row * (unsigned)DM + col0 + BJ * HALF + n * 16)) = acc[ai][BJ][m][n] + ((r[i - LO] - mean[(i - LO) >> 1]) * rstd[(i - LO) >> 1]) * gv[n] + bv[n]; }
	v_add_u32_e32 v148, 0x10090, v194
	v_mov_b32_e32 v149, v159
	v_sub_f32_e32 v141, v141, v200
	v_sub_f32_e32 v140, v140, v200
	v_sub_f32_e32 v143, v143, v200
	v_sub_f32_e32 v142, v142, v200
	v_pk_fma_f32 v[146:147], v[130:131], s[78:79], v[146:147] op_sel_hi:[1,0,1]
	v_pk_fma_f32 v[144:145], v[128:129], s[78:79], v[144:145] op_sel_hi:[1,0,1]
	v_lshl_add_u64 v[148:149], v[148:149], 2, s[90:91]
	v_pk_mul_f32 v[142:143], v[200:201], v[142:143] op_sel:[1,0]
	v_pk_mul_f32 v[140:141], v[200:201], v[140:141] op_sel:[1,0]
	global_store_dwordx4 v[148:149], v[144:147], off
	v_pk_fma_f32 v[140:141], v[214:215], v[140:141], v[36:37]
	v_pk_fma_f32 v[142:143], v[212:213], v[142:143], v[38:39]
	v_add_u32_e32 v144, 0x18080, v194
	v_mov_b32_e32 v145, v159
	v_sub_f32_e32 v137, v137, v200
	v_sub_f32_e32 v136, v136, v200
	v_sub_f32_e32 v139, v139, v200
	v_sub_f32_e32 v138, v138, v200
	v_pk_fma_f32 v[142:143], v[134:135], s[78:79], v[142:143] op_sel_hi:[1,0,1]
	v_pk_fma_f32 v[140:141], v[132:133], s[78:79], v[140:141] op_sel_hi:[1,0,1]
	v_lshl_add_u64 v[144:145], v[144:145], 2, s[90:91]
	v_pk_mul_f32 v[138:139], v[200:201], v[138:139] op_sel:[1,0]
	v_pk_mul_f32 v[136:137], v[200:201], v[136:137] op_sel:[1,0]
	global_store_dwordx4 v[144:145], v[140:143], off
	v_pk_fma_f32 v[136:137], v[208:209], v[136:137], v[32:33]
	v_pk_fma_f32 v[138:139], v[206:207], v[138:139], v[34:35]
	v_add_u32_e32 v140, 0x18090, v194
	v_mov_b32_e32 v141, v159
	v_pk_fma_f32 v[138:139], v[130:131], s[78:79], v[138:139] op_sel_hi:[1,0,1]
	v_pk_fma_f32 v[136:137], v[128:129], s[78:79], v[136:137] op_sel_hi:[1,0,1]
	v_lshl_add_u64 v[140:141], v[140:141], 2, s[90:91]
	global_store_dwordx4 v[140:141], v[136:139], off
	s_nop 1
	v_add_u32_e32 v136, v233, v230
	v_mov_b32_e32 v137, v159
	v_lshl_add_u64 v[136:137], v[136:137], 2, s[88:89]
	global_load_dwordx2 v[220:221], v[196:197], off
	global_load_dwordx4 v[216:219], v[136:137], off
	v_add_u32_e32 v136, v233, v229
	v_mov_b32_e32 v137, v159
	v_lshl_add_u64 v[136:137], v[136:137], 2, s[88:89]
	global_load_dwordx4 v[240:243], v[136:137], off
	global_load_dwordx2 v[200:201], v[198:199], off
	v_add_u32_e32 v136, v234, v230
	v_mov_b32_e32 v137, v159
	v_lshl_add_u64 v[136:137], v[136:137], 2, s[88:89]
	global_load_dwordx4 v[244:247], v[136:137], off
	v_add_u32_e32 v136, v234, v229
	v_mov_b32_e32 v137, v159
	v_lshl_add_u64 v[136:137], v[136:137], 2, s[88:89]
	global_load_dwordx4 v[152:155], v[136:137], off
	global_load_dwordx2 v[198:199], v[204:205], off
	v_add_u32_e32 v136, v237, v230
	v_mov_b32_e32 v137, v159
	v_lshl_add_u64 v[136:137], v[136:137], 2, s[88:89]
	global_load_dwordx4 v[148:151], v[136:137], off
	v_add_u32_e32 v136, v237, v229
	v_mov_b32_e32 v137, v159
	v_lshl_add_u64 v[136:137], v[136:137], 2, s[88:89]
	global_load_dwordx4 v[144:147], v[136:137], off
	global_load_dwordx2 v[196:197], v[210:211], off
	v_add_u32_e32 v136, v238, v230
	v_mov_b32_e32 v137, v159
	v_lshl_add_u64 v[136:137], v[136:137], 2, s[88:89]
	global_load_dwordx4 v[140:143], v[136:137], off
	v_add_u32_e32 v136, v238, v229
	v_mov_b32_e32 v137, v159
	v_lshl_add_u64 v[136:137], v[136:137], 2, s[88:89]
	global_load_dwordx4 v[136:139], v[136:137], off
	v_add_u32_e32 v210, 0x40080, v194
	v_mov_b32_e32 v211, v159
	v_lshl_add_u64 v[210:211], v[210:211], 2, s[90:91]
	s_waitcnt vmcnt(0)
;     template <bool LN, int BJ, int LO, int HI> DI void batch(const f32x4 (&acc)[2][2][4][2], unsigned row0, unsigned col0, const f32x4 (&gv)[2], const f32x4 (&bv)[2]) const {
;         f32x4 r[HI - LO]; float mean[(HI - LO) / 2], rstd[(HI - LO) / 2];
; #pragma unroll
;         for (int i = LO; i < HI; ++i) { const int ai = i >> 3, m = (i >> 1) & 3, n = i & 1; const unsigned row = row0 + ai * HALF + m * 16;
;             if (n == 0) { mean[(i - LO) >> 1] = 0.f; rstd[(i - LO) >> 1] = 1.f;
;                 if (LN) { const float2 st = *(const float2*)(stats + row * 2u); mean[(i - LO) >> 1] = st.x; rstd[(i - LO) >> 1] = st.y; } }
;             r[i - LO] = *(const f32x4*)(src + (row * (unsigned)DM + col0 + BJ * HALF + n * 16)); }
; #pragma unroll
;         for (int i = LO; i < HI; ++i) { const int ai = i >> 3, m = (i >> 1) & 3, n = i & 1; const unsigned row = row0 + ai * HALF + m * 16;
;             *(f32x4*)(Y + (row * (unsigned)DM + col0 + BJ * HALF + n * 16)) = acc[ai][BJ][m][n] + ((r[i - LO] - mean[(i - LO) >> 1]) * rstd[(i - LO) >> 1]) * gv[n] + bv[n]; }
	v_sub_f32_e32 v203, v217, v220
	v_sub_f32_e32 v202, v216, v220
	v_sub_f32_e32 v205, v219, v220
	v_sub_f32_e32 v204, v218, v220
	v_pk_mul_f32 v[204:205], v[220:221], v[204:205] op_sel:[1,0]
	v_pk_mul_f32 v[202:203], v[220:221], v[202:203] op_sel:[1,0]
	v_pk_fma_f32 v[204:205], v[212:213], v[204:205], v[30:31]
	v_pk_fma_f32 v[202:203], v[214:215], v[202:203], v[28:29]
	v_pk_fma_f32 v[204:205], v[134:135], s[78:79], v[204:205] op_sel_hi:[1,0,1]
	v_pk_fma_f32 v[202:203], v[132:133], s[78:79], v[202:203] op_sel_hi:[1,0,1]
	global_store_dwordx4 v[210:211], v[202:205], off
	v_add_u32_e32 v210, 0x40090, v194
	v_mov_b32_e32 v211, v159
	v_sub_f32_e32 v203, v241, v220
	v_sub_f32_e32 v202, v240, v220
	v_sub_f32_e32 v205, v243, v220
	v_sub_f32_e32 v204, v242, v220
	v_pk_mul_f32 v[204:205], v[220:221], v[204:205] op_sel:[1,0]
	v_pk_mul_f32 v[202:203], v[220:221], v[202:203] op_sel:[1,0]
	v_pk_fma_f32 v[204:205], v[206:207], v[204:205], v[26:27]
	v_pk_fma_f32 v[202:203], v[208:209], v[202:203], v[24:25]
	v_pk_fma_f32 v[204:205], v[130:131], s[78:79], v[204:205] op_sel_hi:[1,0,1]
	v_pk_fma_f32 v[202:203], v[128:129], s[78:79], v[202:203] op_sel_hi:[1,0,1]
	v_lshl_add_u64 v[210:211], v[210:211], 2, s[90:91]
	global_store_dwordx4 v[210:211], v[202:205], off
	v_sub_f32_e32 v149, v149, v198
	v_sub_f32_e32 v148, v148, v198
	v_sub_f32_e32 v203, v245, v200
	v_sub_f32_e32 v202, v244, v200
	v_sub_f32_e32 v141, v141, v196
	v_sub_f32_e32 v140, v140, v196
	v_sub_f32_e32 v205, v247, v200
	v_sub_f32_e32 v204, v246, v200
	v_pk_mul_f32 v[202:203], v[200:201], v[202:203] op_sel:[1,0]
	v_sub_f32_e32 v151, v151, v198
	v_sub_f32_e32 v150, v150, v198
	v_pk_mul_f32 v[148:149], v[198:199], v[148:149] op_sel:[1,0]
	v_sub_f32_e32 v143, v143, v196
	v_sub_f32_e32 v142, v142, v196
	v_pk_mul_f32 v[140:141], v[196:197], v[140:141] op_sel:[1,0]
	v_pk_mul_f32 v[204:205], v[200:201], v[204:205] op_sel:[1,0]
	v_pk_fma_f32 v[202:203], v[214:215], v[202:203], v[20:21]
	v_sub_f32_e32 v153, v153, v200
	v_sub_f32_e32 v152, v152, v200
	v_sub_f32_e32 v155, v155, v200
	v_sub_f32_e32 v154, v154, v200
	v_pk_mul_f32 v[150:151], v[198:199], v[150:151] op_sel:[1,0]
	v_pk_fma_f32 v[148:149], v[214:215], v[148:149], v[12:13]
	v_pk_mul_f32 v[142:143], v[196:197], v[142:143] op_sel:[1,0]
	v_pk_fma_f32 v[140:141], v[214:215], v[140:141], v[4:5]
	v_pk_fma_f32 v[204:205], v[212:213], v[204:205], v[22:23]
	v_pk_fma_f32 v[202:203], v[132:133], s[78:79], v[202:203] op_sel_hi:[1,0,1]
	v_pk_mul_f32 v[154:155], v[200:201], v[154:155] op_sel:[1,0]
	v_pk_mul_f32 v[152:153], v[200:201], v[152:153] op_sel:[1,0]
	v_pk_fma_f32 v[150:151], v[212:213], v[150:151], v[14:15]
	v_pk_fma_f32 v[148:149], v[132:133], s[78:79], v[148:149] op_sel_hi:[1,0,1]
	v_pk_fma_f32 v[142:143], v[212:213], v[142:143], v[6:7]
	v_pk_fma_f32 v[132:133], v[132:133], s[78:79], v[140:141] op_sel_hi:[1,0,1]
	v_add_u32_e32 v140, 0x58080, v194
	v_mov_b32_e32 v141, v159
	v_pk_fma_f32 v[204:205], v[134:135], s[78:79], v[204:205] op_sel_hi:[1,0,1]
	v_pk_fma_f32 v[152:153], v[208:209], v[152:153], v[16:17]
	v_pk_fma_f32 v[154:155], v[206:207], v[154:155], v[18:19]
	v_add_u32_e32 v200, 0x48090, v194
	v_mov_b32_e32 v201, v159
	v_pk_fma_f32 v[150:151], v[134:135], s[78:79], v[150:151] op_sel_hi:[1,0,1]
	v_pk_fma_f32 v[134:135], v[134:135], s[78:79], v[142:143] op_sel_hi:[1,0,1]
	v_lshl_add_u64 v[140:141], v[140:141], 2, s[90:91]
	v_pk_fma_f32 v[154:155], v[130:131], s[78:79], v[154:155] op_sel_hi:[1,0,1]
	v_pk_fma_f32 v[152:153], v[128:129], s[78:79], v[152:153] op_sel_hi:[1,0,1]
	v_lshl_add_u64 v[200:201], v[200:201], 2, s[90:91]
	v_sub_f32_e32 v145, v145, v198
	v_sub_f32_e32 v144, v144, v198
	global_store_dwordx4 v[140:141], v[132:135], off
	global_store_dwordx4 v[200:201], v[152:155], off
	v_sub_f32_e32 v147, v147, v198
	v_sub_f32_e32 v133, v137, v196
	v_sub_f32_e32 v132, v136, v196
	v_add_u32_e32 v152, 0x50080, v194
	v_mov_b32_e32 v153, v159
	v_sub_f32_e32 v146, v146, v198
	v_pk_mul_f32 v[144:145], v[198:199], v[144:145] op_sel:[1,0]
	v_sub_f32_e32 v135, v139, v196
	v_sub_f32_e32 v134, v138, v196
	v_pk_mul_f32 v[132:133], v[196:197], v[132:133] op_sel:[1,0]
	v_lshl_add_u64 v[152:153], v[152:153], 2, s[90:91]
	v_pk_mul_f32 v[146:147], v[198:199], v[146:147] op_sel:[1,0]
	v_pk_fma_f32 v[144:145], v[208:209], v[144:145], v[8:9]
	v_pk_mul_f32 v[134:135], v[196:197], v[134:135] op_sel:[1,0]
	v_pk_fma_f32 v[132:133], v[208:209], v[132:133], v[0:1]
	v_add_u32_e32 v210, 0x48080, v194
	v_mov_b32_e32 v211, v159
	global_store_dwordx4 v[152:153], v[148:151], off
	v_pk_fma_f32 v[146:147], v[206:207], v[146:147], v[10:11]
	v_pk_fma_f32 v[144:145], v[128:129], s[78:79], v[144:145] op_sel_hi:[1,0,1]
	v_add_u32_e32 v148, 0x50090, v194
	v_mov_b32_e32 v149, v159
	v_pk_fma_f32 v[134:135], v[206:207], v[134:135], v[2:3]
	v_pk_fma_f32 v[128:129], v[128:129], s[78:79], v[132:133] op_sel_hi:[1,0,1]
	v_add_u32_e32 v132, 0x58090, v194
	v_mov_b32_e32 v133, v159
	v_lshl_add_u64 v[210:211], v[210:211], 2, s[90:91]
	v_pk_fma_f32 v[146:147], v[130:131], s[78:79], v[146:147] op_sel_hi:[1,0,1]
	v_lshl_add_u64 v[148:149], v[148:149], 2, s[90:91]
	v_pk_fma_f32 v[130:131], v[130:131], s[78:79], v[134:135] op_sel_hi:[1,0,1]
	v_lshl_add_u64 v[132:133], v[132:133], 2, s[90:91]
	global_store_dwordx4 v[210:211], v[202:205], off
	global_store_dwordx4 v[148:149], v[144:147], off
	global_store_dwordx4 v[132:133], v[128:131], off
	s_mov_b64 s[24:25], 0
	s_branch .LBB0_324
